# hgwait + attention: removed the full lgkmcnt(0) drains that precede the compiler's counted waits before QK MFMAs
# baseline (speedup 1.0000x reference)
; #define GAS __attribute__((address_space(1)))
; template <bool GRPB> __device__ __forceinline__ void attn_pass(const float mbK, const float bmax2, const int pass, float* __restrict__ scr, bf16* __restrict__ mixrow, const float lam, const float* __restrict__ gsub, const float one_m_li, ...
;     ...
;   const float cL = __uint_as_float(__builtin_amdgcn_readfirstlane(__float_as_uint(tb2[0]))), cR = __uint_as_float(__builtin_amdgcn_readfirstlane(__float_as_uint(tb2[384])));
;   const int qw = __builtin_amdgcn_readfirstlane(q0seq + wid * 32), qpos = qw + r32;
;   float m_reg, l_reg = 0; bf16x8 qr[4]; f32x16 o[4];
; #pragma unroll
;   for (int d = 0; d < 4; ++d) o[d] = f32x16{};
;   const bf16* Qw = Qb + (long)(wid * 32 + r32) * LDK + hi * 8;
; #pragma unroll
;   for (int d0 = 0; d0 < 4; ++d0) qr[d0] = *(const GAS bf16x8*)(Qw + d0 * 16);
;   { float qs = 0.f;
; #pragma unroll
;     for (int d0 = 0; d0 < 4; ++d0)
; #pragma unroll
;       for (int j = 0; j < 8; ++j) { const float v = bf2f((unsigned short)qr[d0][j]); qs = fmaf(v, v, qs); }
;     { auto rr = __builtin_amdgcn_permlane32_swap(__float_as_uint(qs), __float_as_uint(qs), false, false); qs = __uint_as_float(rr[0]) + __uint_as_float(rr[1]); }
;     m_reg = __builtin_sqrtf(qs) * mbK + bmax2 + 0.25f; }
; __device__ __forceinline__ void attn_phase(const Params& p, int e, char* lds) {
;     ...
;     const int qb = u & 15, h = (u >> 4) & 3, b = u >> 6;
;     if (h != cur_h) { int tf_ = threadIdx.x; asm volatile("" : "+v"(tf_));
;       __syncthreads(); for (int d = tf_; d < 385; d += 512) tb2[d] = p.rel_bias[rel_bucket(d - 192) * 4 + h] * LOG2E; cur_h = h; __syncthreads(); }
;     const long row0 = (long)b * SEQ + qb * 256;
;     float bmax2 = -1e30f;
; #pragma unroll 4
;     for (int bk = 0; bk < 32; ++bk) bmax2 = fmaxf(bmax2, p.rel_bias[bk * 4 + h] * LOG2E);
;     const unsigned* kmx = (const unsigned*)(p.ws + WS_KMX) + e * 128 + b * 8 + h * 2;
;     const float mbK0 = __uint_as_float(__builtin_amdgcn_readfirstlane(__float_as_uint(C1 * 1.01f * __builtin_sqrtf(2.0f * __uint_as_float(kmx[0])))));
;     const float mbK1 = __uint_as_float(__builtin_amdgcn_readfirstlane(__float_as_uint(C1 * 1.01f * __builtin_sqrtf(2.0f * __uint_as_float(kmx[1])))));
;     bmax2 = __uint_as_float(__builtin_amdgcn_readfirstlane(__float_as_uint(bmax2)));
.LBB0_295:
	s_lshl_b32 s0, s59, 8
	s_ashr_i32 s48, s59, 6
	s_and_b32 s39, s0, 0xf00
	s_ashr_i32 s49, s48, 31
	s_lshl_b32 s0, s48, 3
	s_lshl_b64 s[46:47], s[48:49], 12
	s_ashr_i32 s1, s0, 31
	s_or_b32 s46, s46, s39
	s_lshl_b64 s[0:1], s[0:1], 2
	s_add_u32 s0, s35, s0
	s_addc_u32 s1, s56, s1
	s_lshl_b32 s2, s44, 3
	s_add_u32 s0, s0, s2
	s_addc_u32 s1, s1, 0
	v_mov_b64_e32 v[2:3], s[0:1]
	flat_load_dwordx2 v[2:3], v[2:3]
	s_mov_b32 s2, 0xf800000
	v_mov_b32_e32 v6, 0x3fba82f9
	v_readfirstlane_b32 s45, v0
	v_lshrrev_b32_e32 v0, 6, v232
	s_mov_b32 s10, 0xf800000
	v_mov_b32_e32 v198, 0x260
	s_waitcnt vmcnt(0) lgkmcnt(0)
	v_add_f32_e32 v1, v2, v2
	v_cmp_gt_f32_e32 vcc, s2, v1
	v_mul_f32_e32 v2, 0x4f800000, v1
	s_nop 0
	v_cndmask_b32_e32 v1, v1, v2, vcc
	v_sqrt_f32_e32 v2, v1
	s_nop 0
	v_add_u32_e32 v4, -1, v2
	v_fma_f32 v5, -v4, v2, v1
	v_cmp_ge_f32_e64 s[0:1], 0, v5
	v_add_u32_e32 v5, 1, v2
	s_nop 0
	v_cndmask_b32_e64 v4, v2, v4, s[0:1]
	v_fma_f32 v2, -v5, v2, v1
	v_cmp_lt_f32_e64 s[0:1], 0, v2
	s_nop 1
	v_cndmask_b32_e64 v2, v4, v5, s[0:1]
	v_mul_f32_e32 v4, 0x37800000, v2
	v_mov_b32_e32 v5, 0x260
	v_cndmask_b32_e32 v2, v2, v4, vcc
	v_cmp_class_f32_e32 vcc, v1, v5
	s_nop 1
	v_cndmask_b32_e32 v1, v2, v1, vcc
	s_nop 0
	v_readfirstlane_b32 s0, v1
	v_add_f32_e32 v1, v3, v3
	v_cmp_gt_f32_e32 vcc, s2, v1
	v_mul_f32_e32 v2, 0x4f800000, v1
	v_mul_f32_e32 v216, s0, v6
	v_cndmask_b32_e32 v1, v1, v2, vcc
	v_sqrt_f32_e32 v2, v1
	s_nop 0
	v_add_u32_e32 v3, -1, v2
	v_fma_f32 v4, -v3, v2, v1
	v_cmp_ge_f32_e64 s[0:1], 0, v4
	v_add_u32_e32 v4, 1, v2
	s_nop 0
	v_cndmask_b32_e64 v3, v2, v3, s[0:1]
	v_fma_f32 v2, -v4, v2, v1
	v_cmp_lt_f32_e64 s[0:1], 0, v2
	s_nop 1
	v_cndmask_b32_e64 v2, v3, v4, s[0:1]
	v_mul_f32_e32 v3, 0x37800000, v2
	v_cndmask_b32_e32 v2, v2, v3, vcc
	v_cmp_class_f32_e32 vcc, v1, v5
	s_nop 1
	v_cndmask_b32_e32 v1, v2, v1, vcc
	s_nop 0
	v_readfirstlane_b32 s0, v1
	s_nop 1
	v_mul_f32_e32 v214, s0, v6
	v_readfirstlane_b32 s0, v0
	s_bitcmp1_b32 s0, 0
	s_cselect_b64 s[20:21], -1, 0
	s_lshl_b64 s[0:1], s[46:47], 13
	s_add_u32 s0, s30, s0
	s_addc_u32 s1, s31, s1
	s_lshl_b32 s2, s44, 8
	s_add_u32 s52, s0, s2
	s_addc_u32 s53, s1, 0
	s_lshl_b64 s[48:49], s[48:49], 25
	s_add_u32 s0, s30, s48
	s_addc_u32 s1, s31, s49
	s_add_u32 s50, s0, s2
	s_addc_u32 s51, s1, 0
	s_mov_b64 s[0:1], -1
	s_and_b64 vcc, exec, s[20:21]
	s_cbranch_vccz .LBB0_347
	v_readlane_b32 s0, v254, 39
	v_mov_b32_e32 v146, v232
	v_mov_b32_e32 v201, v144
	v_mov_b32_e32 v0, s0
	ds_read_b32 v0, v0
	v_readlane_b32 s0, v254, 40
	v_lshrrev_b32_e32 v2, 1, v146
	v_and_b32_e32 v200, 16, v2
	v_lshlrev_b32_e32 v8, 4, v146
	s_waitcnt lgkmcnt(0)
	v_readfirstlane_b32 s61, v0
	v_mov_b32_e32 v0, s0
	ds_read_b32 v0, v0
	s_movk_i32 s0, 0xffe0
	v_and_b32_e32 v9, 48, v8
	v_ashrrev_i32_e32 v12, 3, v146
	v_ashrrev_i32_e32 v13, 31, v12
	s_waitcnt lgkmcnt(0)
	v_readfirstlane_b32 s62, v0
	v_ashrrev_i32_e32 v0, 1, v146
	v_and_b32_e32 v1, 0xffffffe0, v0
	v_add_u32_e32 v1, s39, v1
	v_bfi_b32 v0, s0, v0, v146
	v_readfirstlane_b32 s63, v1
	v_ashrrev_i32_e32 v1, 31, v0
	v_lshlrev_b64 v[0:1], 13, v[0:1]
	v_lshl_add_u64 v[0:1], s[52:53], 0, v[0:1]
	v_lshl_add_u64 v[0:1], v[0:1], 0, v[200:201]
	global_load_dwordx4 v[164:167], v[0:1], off
	global_load_dwordx4 v[160:163], v[0:1], off offset:32
	global_load_dwordx4 v[156:159], v[0:1], off offset:64
	global_load_dwordx4 v[152:155], v[0:1], off offset:96
	s_barrier
	v_lshlrev_b64 v[52:53], 13, v[12:13]
	v_mov_b32_e32 v11, v144
	v_and_b32_e32 v147, 31, v146
	v_add_u32_e32 v215, s63, v147
	s_waitcnt vmcnt(3)
	v_lshlrev_b32_e32 v0, 16, v164
	v_fma_f32 v0, v0, v0, 0
	v_and_b32_e32 v1, 0xffff0000, v164
	v_fmac_f32_e32 v0, v1, v1
	v_lshlrev_b32_e32 v1, 16, v165
	v_fmac_f32_e32 v0, v1, v1
	v_and_b32_e32 v1, 0xffff0000, v165
	v_fmac_f32_e32 v0, v1, v1
	v_lshlrev_b32_e32 v1, 16, v166
	v_fmac_f32_e32 v0, v1, v1
	v_and_b32_e32 v1, 0xffff0000, v166
	v_fmac_f32_e32 v0, v1, v1
	v_lshlrev_b32_e32 v1, 16, v167
	v_fmac_f32_e32 v0, v1, v1
	v_and_b32_e32 v1, 0xffff0000, v167
	v_fmac_f32_e32 v0, v1, v1
	s_waitcnt vmcnt(2)
	v_lshlrev_b32_e32 v1, 16, v160
	v_fmac_f32_e32 v0, v1, v1
	v_and_b32_e32 v1, 0xffff0000, v160
	v_fmac_f32_e32 v0, v1, v1
	v_lshlrev_b32_e32 v1, 16, v161
	v_fmac_f32_e32 v0, v1, v1
	v_and_b32_e32 v1, 0xffff0000, v161
	v_fmac_f32_e32 v0, v1, v1
	v_lshlrev_b32_e32 v1, 16, v162
	v_fmac_f32_e32 v0, v1, v1
	v_and_b32_e32 v1, 0xffff0000, v162
	v_fmac_f32_e32 v0, v1, v1
	v_lshlrev_b32_e32 v1, 16, v163
	v_fmac_f32_e32 v0, v1, v1
	v_and_b32_e32 v1, 0xffff0000, v163
	v_fmac_f32_e32 v0, v1, v1
	s_waitcnt vmcnt(1)
	v_lshlrev_b32_e32 v1, 16, v156
	v_fmac_f32_e32 v0, v1, v1
	v_and_b32_e32 v1, 0xffff0000, v156
	v_fmac_f32_e32 v0, v1, v1
	v_lshlrev_b32_e32 v1, 16, v157
	v_fmac_f32_e32 v0, v1, v1
	v_and_b32_e32 v1, 0xffff0000, v157
	v_fmac_f32_e32 v0, v1, v1
	v_lshlrev_b32_e32 v1, 16, v158
	v_fmac_f32_e32 v0, v1, v1
	v_and_b32_e32 v1, 0xffff0000, v158
	v_fmac_f32_e32 v0, v1, v1
	v_lshlrev_b32_e32 v1, 16, v159
	v_fmac_f32_e32 v0, v1, v1
	v_and_b32_e32 v1, 0xffff0000, v159
	v_fmac_f32_e32 v0, v1, v1
	s_waitcnt vmcnt(0)
; __device__ __forceinline__ float bf2f(unsigned short b) { return __uint_as_float(((unsigned)b) << 16); }
; __device__ __forceinline__ int v_st(int k, int c) { const int kk = (k & ~0xC) | ((k & 4) << 1) | ((k & 8) >> 1); return ((kk >> 3) * 4 + (c >> 5)) * 512 + ((kk & 7) * 32 + (c & 31)) * 2; }
; __device__ __forceinline__ int v_rd_base(int lane) { return ((lane & 3) << 3) | (((lane >> 2) & 3) << 6) | (((lane >> 4) & 1) << 5) | (((lane >> 5) & 1) << 8); }
; #define SLOAD(i, k0) do { sr_[i].vs0 = *(const GAS bf16x8*)(&Vh[(long)((k0) + sr) * LDK + sc]); sr_[i].vs1 = *(const GAS bf16x8*)(&Vh[(long)((k0) + 32 + sr) * LDK + sc]); \
;     sr_[i].ks0 = *(const GAS bf16x8*)(&Kh[(long)((k0) + kr) * LDK + kc]); } while (0)
; #define SWRITE(b, i) do { *(bf16x8*)(V_lds + (b) * SHM_V + vst0) = sr_[i].vs0; *(bf16x8*)(V_lds + (b) * SHM_V + vst1) = sr_[i].vs1; \
;     *(bf16x8*)(K_lds + (b) * SHM_K + kst) = sr_[i].ks0; } while (0)
; template <bool GRPB> __device__ __forceinline__ void attn_pass(const float mbK, const float bmax2, const int pass, float* __restrict__ scr, bf16* __restrict__ mixrow, const float lam, const float* __restrict__ gsub, const float one_m_li, ...
;     ...
;       for (int j = 0; j < 8; ++j) { const float v = bf2f((unsigned short)qr[d0][j]); qs = fmaf(v, v, qs); }
;     { auto rr = __builtin_amdgcn_permlane32_swap(__float_as_uint(qs), __float_as_uint(qs), false, false); qs = __uint_as_float(rr[0]) + __uint_as_float(rr[1]); }
;     m_reg = __builtin_sqrtf(qs) * mbK + bmax2 + 0.25f; }
;   const int sr = tid >> 4, sc = (tid & 15) * 8, vst0 = v_st(sr, sc), vst1 = v_st(32 + sr, sc);
;   const int kr = tid >> 3, kc = (tid & 7) * 8, kst = KSWZ64(kr, kc * 2);
;   const int vb0 = (int)(uintptr_t)V_lds + v_rd_base(lane);
;   struct { bf16x8 vs0, vs1, ks0; } sr_[2];
;     ...
;   f32x16 pA0, pA1, pB0, pB1; float mnA, mnB, alA, alB; bf16x8 pa0, pa1, pa2, pa3; constexpr int NT = SEQ / KVBLK;
;   __syncthreads();
;   SLOAD(0, 0); SLOAD(1, KVBLK); asm volatile("s_waitcnt vmcnt(0)" ::: "memory"); SWRITE(0, 0); SWRITE(1, 1);
;   SLOAD(0, 2 * KVBLK); asm volatile("s_waitcnt vmcnt(0)" ::: "memory"); SWRITE(2, 0); __syncthreads();
	v_lshlrev_b32_e32 v1, 16, v152
	v_fmac_f32_e32 v0, v1, v1
	v_and_b32_e32 v1, 0xffff0000, v152
	v_fmac_f32_e32 v0, v1, v1
	v_lshlrev_b32_e32 v1, 16, v153
	v_fmac_f32_e32 v0, v1, v1
	v_and_b32_e32 v1, 0xffff0000, v153
	v_fmac_f32_e32 v0, v1, v1
	v_lshlrev_b32_e32 v1, 16, v154
	v_fmac_f32_e32 v0, v1, v1
	v_and_b32_e32 v1, 0xffff0000, v154
	v_fmac_f32_e32 v0, v1, v1
	v_lshlrev_b32_e32 v1, 16, v155
	v_fmac_f32_e32 v0, v1, v1
	v_and_b32_e32 v1, 0xffff0000, v155
	v_fmac_f32_e32 v0, v1, v1
	v_mov_b32_e32 v1, v0
	s_nop 1
	v_permlane32_swap_b32_e32 v0, v1
	v_add_f32_e32 v0, v0, v1
	v_cmp_gt_f32_e32 vcc, s10, v0
	v_mul_f32_e32 v1, 0x4f800000, v0
	s_nop 0
	v_cndmask_b32_e32 v0, v0, v1, vcc
	v_sqrt_f32_e32 v1, v0
	s_nop 0
	v_add_u32_e32 v2, -1, v1
	v_fma_f32 v3, -v2, v1, v0
	v_cmp_ge_f32_e64 s[0:1], 0, v3
	v_add_u32_e32 v3, 1, v1
	s_nop 0
	v_cndmask_b32_e64 v2, v1, v2, s[0:1]
	v_fma_f32 v1, -v3, v1, v0
	v_cmp_lt_f32_e64 s[0:1], 0, v1
	s_nop 1
	v_cndmask_b32_e64 v1, v2, v3, s[0:1]
	v_mul_f32_e32 v2, 0x37800000, v1
	v_cndmask_b32_e32 v1, v1, v2, vcc
	v_ashrrev_i32_e32 v2, 4, v146
	v_cmp_class_f32_e32 vcc, v0, v198
	v_and_b32_e32 v3, 0xfffff0, v2
	v_lshlrev_b32_e32 v5, 1, v2
	v_cndmask_b32_e32 v0, v1, v0, vcc
	v_lshlrev_b32_e32 v1, 3, v146
	v_and_or_b32 v3, v5, 8, v3
	v_lshrrev_b32_e32 v5, 1, v2
	v_lshrrev_b32_e32 v3, 1, v3
	v_bfe_u32 v7, v1, 5, 2
	v_and_b32_e32 v6, 3, v2
	v_or_b32_e32 v3, v3, v7
	v_and_or_b32 v5, v5, 4, v6
	v_lshlrev_b32_e32 v3, 9, v3
	v_lshlrev_b32_e32 v5, 6, v5
	v_add_u32_e32 v6, 32, v2
	v_or3_b32 v201, v3, v5, v9
	v_and_b32_e32 v3, 0xfffff0, v6
	v_lshlrev_b32_e32 v10, 1, v6
	v_and_or_b32 v3, v10, 8, v3
	v_lshrrev_b32_e32 v3, 1, v3
	v_or_b32_e32 v3, v3, v7
	v_lshlrev_b32_e32 v3, 9, v3
	v_or3_b32 v217, v3, v5, v9
	v_lshlrev_b32_e32 v3, 7, v12
	v_and_b32_e32 v10, 0x70, v8
	v_and_b32_e32 v5, 0x70, v146
	v_bitop3_b32 v218, v10, v3, v5 bitop3:0xde
	v_ashrrev_i32_e32 v3, 31, v2
	v_and_b32_e32 v4, 0x78, v1
	v_lshlrev_b64 v[50:51], 13, v[2:3]
	v_lshl_add_u64 v[2:3], s[50:51], 0, v[50:51]
	v_lshlrev_b32_e32 v8, 1, v4
	v_mov_b32_e32 v9, v144
	v_ashrrev_i32_e32 v7, 31, v6
	v_lshl_add_u64 v[18:19], v[2:3], 0, v[8:9]
	v_lshlrev_b64 v[6:7], 13, v[6:7]
	global_load_dwordx4 v[2:5], v[18:19], off offset:2048
	v_lshl_add_u64 v[6:7], s[50:51], 0, v[6:7]
	s_mov_b32 s0, 0x80000
	v_lshl_add_u64 v[6:7], v[6:7], 0, v[8:9]
	v_add_co_u32_e32 v14, vcc, s0, v18
	global_load_dwordx4 v[6:9], v[6:7], off offset:2048
	v_lshl_add_u64 v[12:13], s[50:51], 0, v[52:53]
	v_addc_co_u32_e32 v15, vcc, 0, v19, vcc
	s_mov_b32 s1, 0xc0000
	v_lshl_add_u64 v[20:21], v[12:13], 0, v[10:11]
	v_add_co_u32_e32 v22, vcc, s1, v18
	global_load_dwordx4 v[10:13], v[20:21], off offset:1024
	s_nop 0
	v_addc_co_u32_e32 v23, vcc, 0, v19, vcc
	global_load_dwordx4 v[14:17], v[14:15], off offset:2048
	v_add_co_u32_e32 v26, vcc, s0, v20
	global_load_dwordx4 v[22:25], v[22:23], off offset:2048
	s_nop 0
	v_addc_co_u32_e32 v27, vcc, 0, v21, vcc
	global_load_dwordx4 v[26:29], v[26:27], off offset:1024
	v_add_u32_e32 v30, 0, v201
	s_mov_b32 s0, 0x100000
	s_waitcnt vmcnt(3)
	v_add_u32_e32 v31, 0, v217
	s_mov_b32 s1, 0x140000
	v_add_u32_e32 v222, 0, v218
	v_and_b32_e32 v1, 0x70, v1
	v_fma_f32 v0, v216, v0, s45
	v_add_f32_e32 v0, 0x3e800000, v0
	s_waitcnt vmcnt(5)
	ds_write_b128 v30, v[2:5]
	v_add_co_u32_e32 v2, vcc, s0, v18
	s_waitcnt vmcnt(4)
	ds_write_b128 v31, v[6:9]
	v_addc_co_u32_e32 v3, vcc, 0, v19, vcc
	v_add_co_u32_e32 v6, vcc, s1, v18
	s_waitcnt vmcnt(3)
	ds_write_b128 v222, v[10:13] offset:49152
	v_addc_co_u32_e32 v7, vcc, 0, v19, vcc
	v_add_co_u32_e32 v10, vcc, s0, v20
	global_load_dwordx4 v[2:5], v[2:3], off offset:2048
	s_nop 0
	v_addc_co_u32_e32 v11, vcc, 0, v21, vcc
	global_load_dwordx4 v[6:9], v[6:7], off offset:2048
	s_nop 0
	global_load_dwordx4 v[10:13], v[10:11], off offset:1024
	s_waitcnt vmcnt(5)
	ds_write_b128 v30, v[14:17] offset:16384
	s_waitcnt vmcnt(4)
	ds_write_b128 v31, v[22:25] offset:16384
	s_waitcnt vmcnt(3)
	ds_write_b128 v222, v[26:29] offset:57344
	s_waitcnt vmcnt(0)
	s_waitcnt vmcnt(2)
	ds_write_b128 v30, v[2:5] offset:32768
	s_waitcnt vmcnt(1)
	ds_write_b128 v31, v[6:9] offset:32768
	v_add_u32_e32 v2, 0x10000, v222
	s_waitcnt vmcnt(0)
	ds_write_b128 v2, v[10:13]
	v_lshlrev_b32_e32 v10, 7, v147
	v_or_b32_e32 v11, 32, v200
	v_bitop3_b32 v227, v11, v10, v1 bitop3:0xde
	v_or_b32_e32 v11, 64, v200
	v_bitop3_b32 v229, v11, v10, v1 bitop3:0xde
	v_or_b32_e32 v11, 0x60, v200
	v_bitop3_b32 v224, v200, v10, v1 bitop3:0xde
	v_bitop3_b32 v230, v11, v10, v1 bitop3:0xde
	v_add_u32_e32 v223, 0, v224
	v_add_u32_e32 v225, 0, v227
	v_add_u32_e32 v226, 0, v229
	v_add_u32_e32 v228, 0, v230
	s_waitcnt lgkmcnt(0)
	s_barrier
; #define SBAR() __builtin_amdgcn_sched_barrier(0)
; __device__ __forceinline__ void partialSM(f32x16& p0, f32x16& p1, float& m_reg, float& mn, float& alpha, int kt0, int qpos, int qw, int hi, const float* tb2, float cL, float cR) {
;   mn = m_reg; alpha = 1.f;
;   const int rel_hi = kt0 + 63 - qw, rel_lo = kt0 - (qw + 31);
;   if (rel_hi <= -91 || rel_lo >= 91) {
;     const float cm = ((rel_hi <= -91) ? cL : cR) - m_reg;
; #pragma unroll
;     for (int r = 0; r < 16; ++r) { p0[r] = fmaf(p0[r], C1, cm); p1[r] = fmaf(p1[r], C1, cm); }
;   } else {
;     const float* tp = tb2 + (kt0 - qpos + 192 + 4 * hi);
; #pragma unroll
;     for (int r4 = 0; r4 < 4; ++r4) {
;       float ta[4], tb[4];
; #pragma unroll
;       for (int i = 0; i < 4; ++i) { ta[i] = tp[8 * r4 + i] - m_reg; tb[i] = tp[32 + 8 * r4 + i] - m_reg; }
; #pragma unroll
;       for (int i = 0; i < 4; ++i) { p0[4 * r4 + i] = fmaf(p0[4 * r4 + i], C1, ta[i]); p1[4 * r4 + i] = fmaf(p1[4 * r4 + i], C1, tb[i]); }
; __device__ __forceinline__ void qkt(f32x16& p0, f32x16& p1, const char* Ks, const bf16x8* qr, int r32, int hi) {
;   bf16x8 ka[4], kb[4];
; #pragma unroll
;   for (int d0 = 0; d0 < 4; ++d0) { const int cb = (d0 * 16 + hi * 8) * 2;
;     ka[d0] = *reinterpret_cast<const bf16x8*>(Ks + KSWZ64(r32, cb)); kb[d0] = *reinterpret_cast<const bf16x8*>(Ks + KSWZ64(32 + r32, cb)); }
;   asm volatile("s_waitcnt lgkmcnt(0)" ::: "memory"); SBAR();
;   p0 = f32x16{}; p1 = f32x16{};
; #pragma unroll
;   for (int d0 = 0; d0 < 4; ++d0) {
;     p0 = __builtin_amdgcn_mfma_f32_32x32x16_bf16(ka[d0], qr[d0], p0, 0, 0, 0);
;     p1 = __builtin_amdgcn_mfma_f32_32x32x16_bf16(kb[d0], qr[d0], p1, 0, 0, 0); }
	ds_read_b128 v[2:5], v223 offset:49152
	ds_read_b128 v[6:9], v223 offset:53248
	ds_read_b128 v[34:37], v225 offset:49152
	ds_read_b128 v[38:41], v225 offset:53248
	ds_read_b128 v[42:45], v226 offset:49152
	ds_read_b128 v[46:49], v226 offset:53248
	ds_read_b128 v[54:57], v228 offset:49152
	ds_read_b128 v[58:61], v228 offset:53248
	s_waitcnt lgkmcnt(7)
	v_mfma_f32_32x32x16_bf16 v[18:33], v[2:5], v[164:167], 0
	s_add_i32 s2, s63, 0xffffff66
	s_mov_b64 s[0:1], -1
	s_cmp_gt_u32 s2, 0xfffffeec
	s_waitcnt lgkmcnt(6)
	v_mfma_f32_32x32x16_bf16 v[2:17], v[6:9], v[164:167], 0
	s_waitcnt lgkmcnt(5)
	v_mfma_f32_32x32x16_bf16 v[18:33], v[34:37], v[160:163], v[18:33]
	s_waitcnt lgkmcnt(4)
	v_mfma_f32_32x32x16_bf16 v[2:17], v[38:41], v[160:163], v[2:17]
	s_waitcnt lgkmcnt(3)
	v_mfma_f32_32x32x16_bf16 v[18:33], v[42:45], v[156:159], v[18:33]
	s_waitcnt lgkmcnt(2)
	v_mfma_f32_32x32x16_bf16 v[2:17], v[46:49], v[156:159], v[2:17]
	s_waitcnt lgkmcnt(1)
	v_mfma_f32_32x32x16_bf16 v[18:33], v[54:57], v[152:155], v[18:33]
	v_lshlrev_b32_e32 v54, 2, v215
	s_waitcnt lgkmcnt(0)
	v_mfma_f32_32x32x16_bf16 v[2:17], v[58:61], v[152:155], v[2:17]
	s_cbranch_scc0 .LBB0_298
	v_sub_u32_e32 v1, 0, v54
	s_mov_b32 s0, 0x12b00
	v_add3_u32 v1, v1, v200, s0
	ds_read2_b32 v[34:35], v1 offset1:1
	ds_read2_b32 v[56:57], v1 offset0:32 offset1:33
	ds_read2_b32 v[58:59], v1 offset0:34 offset1:35
	ds_read2_b32 v[36:37], v1 offset0:2 offset1:3
	ds_read2_b32 v[38:39], v1 offset0:8 offset1:9
	ds_read2_b32 v[60:61], v1 offset0:40 offset1:41
	ds_read2_b32 v[62:63], v1 offset0:42 offset1:43
	ds_read2_b32 v[40:41], v1 offset0:10 offset1:11
	ds_read2_b32 v[42:43], v1 offset0:16 offset1:17
	ds_read2_b32 v[64:65], v1 offset0:48 offset1:49
	ds_read2_b32 v[66:67], v1 offset0:50 offset1:51
	ds_read2_b32 v[44:45], v1 offset0:18 offset1:19
	ds_read2_b32 v[46:47], v1 offset0:24 offset1:25
	ds_read2_b32 v[48:49], v1 offset0:26 offset1:27
	ds_read2_b32 v[68:69], v1 offset0:58 offset1:59
	ds_read2_b32 v[70:71], v1 offset0:56 offset1:57
	s_waitcnt lgkmcnt(3)
	v_sub_f32_e32 v47, v47, v0
	v_sub_f32_e32 v46, v46, v0
	s_waitcnt lgkmcnt(2)
	v_sub_f32_e32 v49, v49, v0
	v_sub_f32_e32 v48, v48, v0
	v_sub_f32_e32 v43, v43, v0
	v_sub_f32_e32 v42, v42, v0
	v_sub_f32_e32 v45, v45, v0
	v_sub_f32_e32 v44, v44, v0
	v_sub_f32_e32 v39, v39, v0
	v_sub_f32_e32 v38, v38, v0
	v_sub_f32_e32 v41, v41, v0
	v_sub_f32_e32 v40, v40, v0
	v_sub_f32_e32 v35, v35, v0
	v_sub_f32_e32 v34, v34, v0
	v_sub_f32_e32 v37, v37, v0
	v_sub_f32_e32 v36, v36, v0
	s_waitcnt lgkmcnt(0)
	v_sub_f32_e32 v71, v71, v0
	v_sub_f32_e32 v70, v70, v0
	v_sub_f32_e32 v69, v69, v0
	v_sub_f32_e32 v68, v68, v0
	v_sub_f32_e32 v65, v65, v0
	v_sub_f32_e32 v64, v64, v0
	v_sub_f32_e32 v67, v67, v0
	v_sub_f32_e32 v66, v66, v0
	v_sub_f32_e32 v61, v61, v0
	v_sub_f32_e32 v60, v60, v0
	v_sub_f32_e32 v63, v63, v0
	v_sub_f32_e32 v62, v62, v0
	v_sub_f32_e32 v57, v57, v0
	v_sub_f32_e32 v56, v56, v0
	v_sub_f32_e32 v59, v59, v0
	v_sub_f32_e32 v58, v58, v0
	v_pk_fma_f32 v[36:37], v[20:21], s[6:7], v[36:37] op_sel_hi:[1,0,1]
	v_pk_fma_f32 v[34:35], v[18:19], s[6:7], v[34:35] op_sel_hi:[1,0,1]
	v_pk_fma_f32 v[40:41], v[24:25], s[6:7], v[40:41] op_sel_hi:[1,0,1]
	v_pk_fma_f32 v[38:39], v[22:23], s[6:7], v[38:39] op_sel_hi:[1,0,1]
	v_pk_fma_f32 v[44:45], v[28:29], s[6:7], v[44:45] op_sel_hi:[1,0,1]
	v_pk_fma_f32 v[42:43], v[26:27], s[6:7], v[42:43] op_sel_hi:[1,0,1]
	v_pk_fma_f32 v[48:49], v[32:33], s[6:7], v[48:49] op_sel_hi:[1,0,1]
	v_pk_fma_f32 v[46:47], v[30:31], s[6:7], v[46:47] op_sel_hi:[1,0,1]
	v_pk_fma_f32 v[82:83], v[4:5], s[6:7], v[58:59] op_sel_hi:[1,0,1]
	v_pk_fma_f32 v[80:81], v[2:3], s[6:7], v[56:57] op_sel_hi:[1,0,1]
	v_pk_fma_f32 v[86:87], v[8:9], s[6:7], v[62:63] op_sel_hi:[1,0,1]
	v_pk_fma_f32 v[84:85], v[6:7], s[6:7], v[60:61] op_sel_hi:[1,0,1]
	v_pk_fma_f32 v[90:91], v[12:13], s[6:7], v[66:67] op_sel_hi:[1,0,1]
	v_pk_fma_f32 v[88:89], v[10:11], s[6:7], v[64:65] op_sel_hi:[1,0,1]
	v_pk_fma_f32 v[94:95], v[16:17], s[6:7], v[68:69] op_sel_hi:[1,0,1]
	v_pk_fma_f32 v[92:93], v[14:15], s[6:7], v[70:71] op_sel_hi:[1,0,1]
	s_mov_b64 s[0:1], 0

; #define SBAR() __builtin_amdgcn_sched_barrier(0)
; __device__ __forceinline__ void finishSM(f32x16& p0, f32x16& p1, float alpha, float& l_reg, bf16x8& pa0, bf16x8& pa1, bf16x8& pa2, bf16x8& pa3) {
; #pragma unroll
;   for (int r = 0; r < 16; ++r) p1[r] = __builtin_amdgcn_exp2f(p1[r]);
;   float ps = 0;
; #pragma unroll
;   for (int r = 0; r < 16; ++r) ps += p0[r];
; #pragma unroll
;   for (int r = 0; r < 16; ++r) ps += p1[r];
;   { auto rr = __builtin_amdgcn_permlane32_swap(__float_as_uint(ps), __float_as_uint(ps), false, false);
;     ps = __uint_as_float(rr[0]) + __uint_as_float(rr[1]); }
;   l_reg = l_reg * alpha + ps;
;     ...
;   PK4(p0, 0, pa0); PK4(p0, 8, pa1); PK4(p1, 0, pa2); PK4(p1, 8, pa3);
;     ...
; }
; __device__ __forceinline__ void qkt(f32x16& p0, f32x16& p1, const char* Ks, const bf16x8* qr, int r32, int hi) {
;   bf16x8 ka[4], kb[4];
; #pragma unroll
;   for (int d0 = 0; d0 < 4; ++d0) { const int cb = (d0 * 16 + hi * 8) * 2;
;     ka[d0] = *reinterpret_cast<const bf16x8*>(Ks + KSWZ64(r32, cb)); kb[d0] = *reinterpret_cast<const bf16x8*>(Ks + KSWZ64(32 + r32, cb)); }
;   asm volatile("s_waitcnt lgkmcnt(0)" ::: "memory"); SBAR();
;   p0 = f32x16{}; p1 = f32x16{};
; #pragma unroll
;   for (int d0 = 0; d0 < 4; ++d0) {
;     p0 = __builtin_amdgcn_mfma_f32_32x32x16_bf16(ka[d0], qr[d0], p0, 0, 0, 0);
;     p1 = __builtin_amdgcn_mfma_f32_32x32x16_bf16(kb[d0], qr[d0], p1, 0, 0, 0); }
.LBB0_301:
	s_mov_b32 s68, s64
	s_mov_b32 s64, s0
	v_add_f32_e32 v96, 0, v141
	v_add_f32_e32 v96, v143, v96
	v_add_f32_e32 v96, v139, v96
	v_add_f32_e32 v96, v142, v96
	v_add_f32_e32 v96, v137, v96
	v_add_f32_e32 v96, v140, v96
	v_add_f32_e32 v96, v136, v96
	v_add_f32_e32 v96, v138, v96
	v_add_f32_e32 v96, v133, v96
	v_add_f32_e32 v96, v135, v96
	v_add_f32_e32 v96, v131, v96
	v_add_f32_e32 v96, v134, v96
	v_exp_f32_e32 v80, v80
	v_add_f32_e32 v96, v129, v96
	v_exp_f32_e32 v81, v81
	v_add_f32_e32 v96, v132, v96
	v_exp_f32_e32 v82, v82
	v_add_f32_e32 v96, v128, v96
	v_exp_f32_e32 v83, v83
	v_add_f32_e32 v96, v130, v96
	v_exp_f32_e32 v84, v84
	v_add_f32_e32 v96, v80, v96
	v_exp_f32_e32 v85, v85
	v_add_f32_e32 v96, v81, v96
	v_exp_f32_e32 v86, v86
	v_add_f32_e32 v96, v82, v96
	v_exp_f32_e32 v87, v87
	v_add_f32_e32 v96, v83, v96
	v_exp_f32_e32 v88, v88
	v_add_f32_e32 v96, v84, v96
	v_exp_f32_e32 v89, v89
	v_add_f32_e32 v96, v85, v96
	v_exp_f32_e32 v90, v90
	v_add_f32_e32 v96, v86, v96
	v_exp_f32_e32 v91, v91
	v_add_f32_e32 v96, v87, v96
	v_exp_f32_e32 v92, v92
	v_add_f32_e32 v96, v88, v96
	v_exp_f32_e32 v93, v93
	v_add_f32_e32 v96, v89, v96
	v_exp_f32_e32 v94, v94
	v_add_f32_e32 v96, v90, v96
	v_exp_f32_e32 v95, v95
	v_add_f32_e32 v96, v91, v96
	v_add_f32_e32 v96, v92, v96
	v_add_f32_e32 v96, v93, v96
	v_add_f32_e32 v96, v94, v96
	v_add_f32_e32 v241, v95, v96
	v_mov_b32_e32 v242, v241
	v_cvt_pk_bf16_f32 v180, v141, v143
	v_cvt_pk_bf16_f32 v181, v139, v142
	v_cvt_pk_bf16_f32 v182, v137, v140
	v_cvt_pk_bf16_f32 v183, v136, v138
	v_cvt_pk_bf16_f32 v184, v133, v135
	v_cvt_pk_bf16_f32 v185, v131, v134
	v_cvt_pk_bf16_f32 v186, v129, v132
	v_cvt_pk_bf16_f32 v187, v128, v130
	v_cvt_pk_bf16_f32 v188, v80, v81
	v_cvt_pk_bf16_f32 v189, v82, v83
	v_cvt_pk_bf16_f32 v190, v84, v85
	v_cvt_pk_bf16_f32 v191, v86, v87
	v_cvt_pk_bf16_f32 v192, v88, v89
	v_cvt_pk_bf16_f32 v193, v90, v91
	v_cvt_pk_bf16_f32 v194, v92, v93
	v_cvt_pk_bf16_f32 v195, v94, v95
	s_nop 1
	v_permlane32_swap_b32_e32 v241, v242
	v_permlane32_swap_b32_e32 v180, v182
	v_permlane32_swap_b32_e32 v181, v183
	v_permlane32_swap_b32_e32 v184, v186
	v_permlane32_swap_b32_e32 v185, v187
	v_permlane32_swap_b32_e32 v188, v190
	v_permlane32_swap_b32_e32 v189, v191
	v_permlane32_swap_b32_e32 v192, v194
	v_permlane32_swap_b32_e32 v193, v195
	s_lshl_b32 s0, s68, 13
	s_add_i32 s4, s0, 0
	v_add_u32_e32 v84, s4, v224
	v_add_u32_e32 v92, s4, v227
	v_add_u32_e32 v96, s4, v229
	ds_read_b128 v[80:83], v84 offset:49152
	ds_read_b128 v[84:87], v84 offset:53248
	ds_read_b128 v[88:91], v92 offset:49152
	ds_read_b128 v[92:95], v92 offset:53248
	ds_read_b128 v[128:131], v96 offset:49152
	ds_read_b128 v[132:135], v96 offset:53248
	v_add_u32_e32 v96, s4, v230
	ds_read_b128 v[136:139], v96 offset:49152
	ds_read_b128 v[140:143], v96 offset:53248
	s_waitcnt lgkmcnt(7)
	v_mfma_f32_32x32x16_bf16 v[112:127], v[80:83], v[164:167], 0
	s_waitcnt lgkmcnt(6)
	v_mfma_f32_32x32x16_bf16 v[96:111], v[84:87], v[164:167], 0
	s_waitcnt lgkmcnt(5)
	v_mfma_f32_32x32x16_bf16 v[112:127], v[88:91], v[160:163], v[112:127]
	s_waitcnt lgkmcnt(4)
	v_mfma_f32_32x32x16_bf16 v[96:111], v[92:95], v[160:163], v[96:111]
	s_waitcnt lgkmcnt(3)
	v_mfma_f32_32x32x16_bf16 v[112:127], v[128:131], v[156:159], v[112:127]
	s_waitcnt lgkmcnt(2)
	v_mfma_f32_32x32x16_bf16 v[96:111], v[132:135], v[156:159], v[96:111]
	s_waitcnt lgkmcnt(1)
	v_mfma_f32_32x32x16_bf16 v[112:127], v[136:139], v[152:155], v[112:127]
	s_waitcnt lgkmcnt(0)
	v_mfma_f32_32x32x16_bf16 v[96:111], v[140:143], v[152:155], v[96:111]
	s_add_u32 s74, s70, s15
	s_addc_u32 s75, s71, 0
	global_load_dwordx4 v[168:171], v202, s[74:75] offset:2048
	s_add_u32 s74, s70, 0x18dc0000
	s_addc_u32 s75, s71, 0
	global_load_dwordx4 v[172:175], v202, s[74:75] offset:2048
	s_add_u32 s74, s72, 0x18d80000
	s_addc_u32 s75, s73, 0
	global_load_dwordx4 v[176:179], v204, s[74:75] offset:1024
	s_add_i32 s0, s65, 0xffffff47
	s_cmp_gt_u32 s0, 0xfffffeec
	s_mov_b64 s[0:1], -1
	s_cbranch_scc0 .LBB0_303
; __device__ __forceinline__ void partialSM(f32x16& p0, f32x16& p1, float& m_reg, float& mn, float& alpha, int kt0, int qpos, int qw, int hi, const float* tb2, float cL, float cR) {
;     ...
;   } else {
;     const float* tp = tb2 + (kt0 - qpos + 192 + 4 * hi);
; #pragma unroll
;     for (int r4 = 0; r4 < 4; ++r4) {
;       float ta[4], tb[4];
; #pragma unroll
;       for (int i = 0; i < 4; ++i) { ta[i] = tp[8 * r4 + i] - m_reg; tb[i] = tp[32 + 8 * r4 + i] - m_reg; }
; #pragma unroll
;       for (int i = 0; i < 4; ++i) { p0[4 * r4 + i] = fmaf(p0[4 * r4 + i], C1, ta[i]); p1[4 * r4 + i] = fmaf(p1[4 * r4 + i], C1, tb[i]); }
;       asm volatile("" ::: "memory");
	ds_read2_b32 v[80:81], v240 offset1:1
	ds_read2_b32 v[82:83], v240 offset0:32 offset1:33
	ds_read2_b32 v[84:85], v240 offset0:34 offset1:35
	ds_read2_b32 v[86:87], v240 offset0:2 offset1:3
	ds_read2_b32 v[88:89], v240 offset0:8 offset1:9
	ds_read2_b32 v[90:91], v240 offset0:40 offset1:41
	ds_read2_b32 v[92:93], v240 offset0:42 offset1:43
	ds_read2_b32 v[94:95], v240 offset0:10 offset1:11
	ds_read2_b32 v[128:129], v240 offset0:16 offset1:17
	ds_read2_b32 v[244:245], v240 offset0:48 offset1:49
	ds_read2_b32 v[246:247], v240 offset0:50 offset1:51
	ds_read2_b32 v[130:131], v240 offset0:18 offset1:19
	s_waitcnt lgkmcnt(11)
	v_sub_f32_e32 v81, v81, v1
	v_sub_f32_e32 v80, v80, v0
	ds_read2_b32 v[132:133], v240 offset0:24 offset1:25
	ds_read2_b32 v[134:135], v240 offset0:26 offset1:27
	ds_read2_b32 v[248:249], v240 offset0:56 offset1:57
	s_waitcnt lgkmcnt(6)
	v_sub_f32_e32 v137, v129, v75
	v_sub_f32_e32 v136, v128, v72
	v_pk_fma_f32 v[128:129], v[112:113], s[6:7], v[80:81] op_sel_hi:[1,0,1]
	ds_read2_b32 v[80:81], v240 offset0:58 offset1:59
	v_sub_f32_e32 v89, v89, v69
	v_sub_f32_e32 v88, v88, v68
	v_sub_f32_e32 v95, v95, v71
	v_sub_f32_e32 v94, v94, v70
	v_sub_f32_e32 v87, v87, v67
	v_sub_f32_e32 v86, v86, v66
	s_waitcnt lgkmcnt(3)
	v_sub_f32_e32 v141, v133, v79
	v_sub_f32_e32 v140, v132, v78
	s_waitcnt lgkmcnt(2)
	v_sub_f32_e32 v143, v135, v77
	v_sub_f32_e32 v142, v134, v76
	v_sub_f32_e32 v139, v131, v73
	v_sub_f32_e32 v138, v130, v74
	v_pk_fma_f32 v[130:131], v[114:115], s[6:7], v[86:87] op_sel_hi:[1,0,1]
	v_pk_fma_f32 v[134:135], v[118:119], s[6:7], v[94:95] op_sel_hi:[1,0,1]
	v_pk_fma_f32 v[132:133], v[116:117], s[6:7], v[88:89] op_sel_hi:[1,0,1]
	s_waitcnt lgkmcnt(1)
	v_sub_f32_e32 v249, v249, v79
	v_sub_f32_e32 v248, v248, v78
	s_waitcnt lgkmcnt(0)
	v_sub_f32_e32 v95, v81, v77
	v_sub_f32_e32 v94, v80, v76
	v_sub_f32_e32 v89, v245, v75
	v_sub_f32_e32 v88, v244, v72
	v_sub_f32_e32 v245, v247, v73
	v_sub_f32_e32 v244, v246, v74
	v_sub_f32_e32 v91, v91, v69
	v_sub_f32_e32 v90, v90, v68
	v_sub_f32_e32 v87, v93, v71
	v_sub_f32_e32 v86, v92, v70
	v_sub_f32_e32 v81, v83, v1
	v_sub_f32_e32 v80, v82, v0
	v_sub_f32_e32 v83, v85, v67
	v_sub_f32_e32 v82, v84, v66
	v_pk_fma_f32 v[138:139], v[122:123], s[6:7], v[138:139] op_sel_hi:[1,0,1]
	v_pk_fma_f32 v[136:137], v[120:121], s[6:7], v[136:137] op_sel_hi:[1,0,1]
	v_pk_fma_f32 v[142:143], v[126:127], s[6:7], v[142:143] op_sel_hi:[1,0,1]
	v_pk_fma_f32 v[140:141], v[124:125], s[6:7], v[140:141] op_sel_hi:[1,0,1]
	v_pk_fma_f32 v[82:83], v[98:99], s[6:7], v[82:83] op_sel_hi:[1,0,1]
	v_pk_fma_f32 v[80:81], v[96:97], s[6:7], v[80:81] op_sel_hi:[1,0,1]
	v_pk_fma_f32 v[86:87], v[102:103], s[6:7], v[86:87] op_sel_hi:[1,0,1]
	v_pk_fma_f32 v[84:85], v[100:101], s[6:7], v[90:91] op_sel_hi:[1,0,1]
	v_pk_fma_f32 v[90:91], v[106:107], s[6:7], v[244:245] op_sel_hi:[1,0,1]
	v_pk_fma_f32 v[88:89], v[104:105], s[6:7], v[88:89] op_sel_hi:[1,0,1]
	v_pk_fma_f32 v[94:95], v[110:111], s[6:7], v[94:95] op_sel_hi:[1,0,1]
	v_pk_fma_f32 v[92:93], v[108:109], s[6:7], v[248:249] op_sel_hi:[1,0,1]
	s_mov_b64 s[0:1], 0

; #define SBAR() __builtin_amdgcn_sched_barrier(0)
; __device__ __forceinline__ void partialSM(f32x16& p0, f32x16& p1, float& m_reg, float& mn, float& alpha, int kt0, int qpos, int qw, int hi, const float* tb2, float cL, float cR) {
;     ...
; #pragma unroll
;   for (int r = 0; r < 16; ++r) p0[r] = __builtin_amdgcn_exp2f(p0[r]);
; template <int D0> __device__ __forceinline__ void pv_one(f32x16& od, int vb, bf16x8 pa0, bf16x8 pa1, bf16x8 pa2, bf16x8 pa3) {
;   const s16x4 l0 = tr_read<v_rd_off(D0, 0, 0)>(vb), h0 = tr_read<v_rd_off(D0, 0, 1)>(vb), l1 = tr_read<v_rd_off(D0, 1, 0)>(vb), h1 = tr_read<v_rd_off(D0, 1, 1)>(vb);
;   const s16x4 l2 = tr_read<v_rd_off(D0, 2, 0)>(vb), h2 = tr_read<v_rd_off(D0, 2, 1)>(vb), l3 = tr_read<v_rd_off(D0, 3, 0)>(vb), h3 = tr_read<v_rd_off(D0, 3, 1)>(vb);
;   asm volatile("s_waitcnt lgkmcnt(0)" ::: "memory"); SBAR();
;     ...
;   od = __builtin_amdgcn_mfma_f32_32x32x16_bf16(pa0, PK(l0, h0), od, 0, 0, 0);
;   od = __builtin_amdgcn_mfma_f32_32x32x16_bf16(pa1, PK(l1, h1), od, 0, 0, 0);
;   od = __builtin_amdgcn_mfma_f32_32x32x16_bf16(pa2, PK(l2, h2), od, 0, 0, 0);
;   od = __builtin_amdgcn_mfma_f32_32x32x16_bf16(pa3, PK(l3, h3), od, 0, 0, 0);
;     ...
; }
; __device__ __forceinline__ void pv_d0(f32x16* o, int vb, bf16x8 pa0, bf16x8 pa1, bf16x8 pa2, bf16x8 pa3) {
;   pv_one<0>(o[0], vb, pa0, pa1, pa2, pa3); pv_one<1>(o[1], vb, pa0, pa1, pa2, pa3); pv_one<2>(o[2], vb, pa0, pa1, pa2, pa3); pv_one<3>(o[3], vb, pa0, pa1, pa2, pa3);
.LBB0_305:
	v_exp_f32_e32 v112, v128
	v_exp_f32_e32 v113, v129
	v_exp_f32_e32 v114, v130
	v_exp_f32_e32 v115, v131
	v_exp_f32_e32 v116, v132
	v_exp_f32_e32 v117, v133
	v_exp_f32_e32 v118, v134
	v_exp_f32_e32 v119, v135
	v_exp_f32_e32 v120, v136
	v_exp_f32_e32 v121, v137
	v_exp_f32_e32 v122, v138
	v_exp_f32_e32 v123, v139
	v_exp_f32_e32 v124, v140
	v_exp_f32_e32 v125, v141
	v_exp_f32_e32 v126, v142
	v_exp_f32_e32 v127, v143
	s_lshl_b32 s0, s64, 14
	v_add_u32_e32 v128, s0, v220
	ds_read_b64_tr_b16 v[96:97], v128 offset:0
	ds_read_b64_tr_b16 v[98:99], v128 offset:0x800
	ds_read_b64_tr_b16 v[100:101], v128 offset:0x1000
	ds_read_b64_tr_b16 v[102:103], v128 offset:0x1800
	ds_read_b64_tr_b16 v[104:105], v128 offset:0x2000
	ds_read_b64_tr_b16 v[106:107], v128 offset:0x2800
	ds_read_b64_tr_b16 v[108:109], v128 offset:0x3000
	ds_read_b64_tr_b16 v[110:111], v128 offset:0x3800
	s_waitcnt lgkmcnt(0)
	s_nop 0
	v_mfma_f32_32x32x16_bf16 v[2:17], v[180:183], v[96:99], v[2:17]
	ds_read_b64_tr_b16 v[96:97], v128 offset:0x200
	ds_read_b64_tr_b16 v[98:99], v128 offset:0xa00
	v_mfma_f32_32x32x16_bf16 v[2:17], v[184:187], v[100:103], v[2:17]
	ds_read_b64_tr_b16 v[100:101], v128 offset:0x1200
	ds_read_b64_tr_b16 v[102:103], v128 offset:0x1a00
	v_mfma_f32_32x32x16_bf16 v[2:17], v[188:191], v[104:107], v[2:17]
	ds_read_b64_tr_b16 v[104:105], v128 offset:0x2200
	ds_read_b64_tr_b16 v[106:107], v128 offset:0x2a00
	v_mfma_f32_32x32x16_bf16 v[2:17], v[192:195], v[108:111], v[2:17]
	ds_read_b64_tr_b16 v[108:109], v128 offset:0x3200
	ds_read_b64_tr_b16 v[110:111], v128 offset:0x3a00
	s_waitcnt lgkmcnt(0)
	v_mfma_f32_32x32x16_bf16 v[18:33], v[180:183], v[96:99], v[18:33]
	ds_read_b64_tr_b16 v[96:97], v128 offset:0x400
	ds_read_b64_tr_b16 v[98:99], v128 offset:0xc00
	v_mfma_f32_32x32x16_bf16 v[18:33], v[184:187], v[100:103], v[18:33]
	ds_read_b64_tr_b16 v[100:101], v128 offset:0x1400
	ds_read_b64_tr_b16 v[102:103], v128 offset:0x1c00
	v_mfma_f32_32x32x16_bf16 v[18:33], v[188:191], v[104:107], v[18:33]
	ds_read_b64_tr_b16 v[104:105], v128 offset:0x2400
	ds_read_b64_tr_b16 v[106:107], v128 offset:0x2c00
	v_mfma_f32_32x32x16_bf16 v[18:33], v[192:195], v[108:111], v[18:33]
	ds_read_b64_tr_b16 v[108:109], v128 offset:0x3400
	ds_read_b64_tr_b16 v[110:111], v128 offset:0x3c00
	s_waitcnt lgkmcnt(0)
	v_mfma_f32_32x32x16_bf16 v[34:49], v[180:183], v[96:99], v[34:49]
	ds_read_b64_tr_b16 v[96:97], v128 offset:0x600
	ds_read_b64_tr_b16 v[98:99], v128 offset:0xe00
	v_mfma_f32_32x32x16_bf16 v[34:49], v[184:187], v[100:103], v[34:49]
	ds_read_b64_tr_b16 v[100:101], v128 offset:0x1600
	ds_read_b64_tr_b16 v[102:103], v128 offset:0x1e00
	v_mfma_f32_32x32x16_bf16 v[34:49], v[188:191], v[104:107], v[34:49]
	ds_read_b64_tr_b16 v[104:105], v128 offset:0x2600
	ds_read_b64_tr_b16 v[106:107], v128 offset:0x2e00
	v_mfma_f32_32x32x16_bf16 v[34:49], v[192:195], v[108:111], v[34:49]
	ds_read_b64_tr_b16 v[108:109], v128 offset:0x3600
	ds_read_b64_tr_b16 v[110:111], v128 offset:0x3e00
	s_waitcnt lgkmcnt(0)
	v_mfma_f32_32x32x16_bf16 v[50:65], v[180:183], v[96:99], v[50:65]
	s_add_i32 s0, s0, 0
	v_add_u32_e32 v96, s0, v201
	s_barrier
; #define SBAR() __builtin_amdgcn_sched_barrier(0)
; #define SLOAD(i, k0) do { sr_[i].vs0 = *(const GAS bf16x8*)(&Vh[(long)((k0) + sr) * LDK + sc]); sr_[i].vs1 = *(const GAS bf16x8*)(&Vh[(long)((k0) + 32 + sr) * LDK + sc]); \
;     sr_[i].ks0 = *(const GAS bf16x8*)(&Kh[(long)((k0) + kr) * LDK + kc]); } while (0)
; __device__ __forceinline__ void finishSM(f32x16& p0, f32x16& p1, float alpha, float& l_reg, bf16x8& pa0, bf16x8& pa1, bf16x8& pa2, bf16x8& pa3) {
; #pragma unroll
;   for (int r = 0; r < 16; ++r) p1[r] = __builtin_amdgcn_exp2f(p1[r]);
;   float ps = 0;
; #pragma unroll
;   for (int r = 0; r < 16; ++r) ps += p0[r];
; #pragma unroll
;   for (int r = 0; r < 16; ++r) ps += p1[r];
;   { auto rr = __builtin_amdgcn_permlane32_swap(__float_as_uint(ps), __float_as_uint(ps), false, false);
;     ps = __uint_as_float(rr[0]) + __uint_as_float(rr[1]); }
;   l_reg = l_reg * alpha + ps;
;     ...
;   PK4(p0, 0, pa0); PK4(p0, 8, pa1); PK4(p1, 0, pa2); PK4(p1, 8, pa3);
;     ...
; }
; __device__ __forceinline__ void qkt(f32x16& p0, f32x16& p1, const char* Ks, const bf16x8* qr, int r32, int hi) {
;   bf16x8 ka[4], kb[4];
; #pragma unroll
;   for (int d0 = 0; d0 < 4; ++d0) { const int cb = (d0 * 16 + hi * 8) * 2;
;     ka[d0] = *reinterpret_cast<const bf16x8*>(Ks + KSWZ64(r32, cb)); kb[d0] = *reinterpret_cast<const bf16x8*>(Ks + KSWZ64(32 + r32, cb)); }
;   asm volatile("s_waitcnt lgkmcnt(0)" ::: "memory"); SBAR();
;   p0 = f32x16{}; p1 = f32x16{};
; #pragma unroll
;   for (int d0 = 0; d0 < 4; ++d0) {
;     p0 = __builtin_amdgcn_mfma_f32_32x32x16_bf16(ka[d0], qr[d0], p0, 0, 0, 0);
;     p1 = __builtin_amdgcn_mfma_f32_32x32x16_bf16(kb[d0], qr[d0], p1, 0, 0, 0); }
; template <bool GRPB> __device__ __forceinline__ void attn_pass(const float mbK, const float bmax2, const int pass, float* __restrict__ scr, bf16* __restrict__ mixrow, const float lam, const float* __restrict__ gsub, const float one_m_li, ...
;     ...
;     HSTEP(pB0, pB1, mnB, alB, pA0, pA1, alA, t * KVBLK, SLOAD(0, (t + 2) * KVBLK));
;     __syncthreads(); SWRITE(bm1, 0);
;     RESC(alB);
;     { const int tmp = bm1; bm1 = b0; b0 = bp1; bp1 = tmp; }
;     HSTEP(pA0, pA1, mnA, alA, pB0, pB1, alB, (t + 1) * KVBLK, if (t + 3 < NT) SLOAD(0, (t + 3) * KVBLK));
;     __syncthreads(); if (t + 3 < NT) SWRITE(bm1, 0);
	s_waitcnt vmcnt(2)
	ds_write_b128 v96, v[168:171]
	v_add_u32_e32 v96, s0, v217
	v_mfma_f32_32x32x16_bf16 v[50:65], v[184:187], v[100:103], v[50:65]
	s_waitcnt vmcnt(1)
	ds_write_b128 v96, v[172:175]
	v_lshl_add_u32 v96, s64, 13, v222
	s_waitcnt vmcnt(0)
	ds_write_b128 v96, v[176:179] offset:49152
	v_mfma_f32_32x32x16_bf16 v[50:65], v[188:191], v[104:107], v[50:65]
	v_mfma_f32_32x32x16_bf16 v[50:65], v[192:195], v[108:111], v[50:65]
	v_add_f32_e32 v96, 0, v112
	v_add_f32_e32 v96, v113, v96
	v_add_f32_e32 v96, v114, v96
	v_add_f32_e32 v96, v115, v96
	v_add_f32_e32 v96, v116, v96
	v_add_f32_e32 v96, v117, v96
	v_add_f32_e32 v96, v118, v96
	v_add_f32_e32 v96, v119, v96
	v_add_f32_e32 v96, v120, v96
	v_add_f32_e32 v96, v121, v96
	v_add_f32_e32 v96, v122, v96
	v_add_f32_e32 v96, v123, v96
	v_exp_f32_e32 v80, v80
	v_add_f32_e32 v96, v124, v96
	v_exp_f32_e32 v81, v81
	v_add_f32_e32 v96, v125, v96
	v_exp_f32_e32 v82, v82
	v_add_f32_e32 v96, v126, v96
	v_exp_f32_e32 v83, v83
	v_add_f32_e32 v96, v127, v96
	v_exp_f32_e32 v84, v84
	v_add_f32_e32 v96, v80, v96
	v_exp_f32_e32 v85, v85
	v_add_f32_e32 v96, v81, v96
	v_exp_f32_e32 v86, v86
	v_add_f32_e32 v96, v82, v96
	v_exp_f32_e32 v87, v87
	v_add_f32_e32 v96, v83, v96
	v_exp_f32_e32 v88, v88
	v_add_f32_e32 v96, v84, v96
	v_exp_f32_e32 v89, v89
	v_add_f32_e32 v96, v85, v96
	v_exp_f32_e32 v90, v90
	v_add_f32_e32 v96, v86, v96
	v_exp_f32_e32 v91, v91
	v_add_f32_e32 v96, v87, v96
	v_exp_f32_e32 v92, v92
	v_add_f32_e32 v96, v88, v96
	v_exp_f32_e32 v93, v93
	v_add_f32_e32 v96, v89, v96
	v_exp_f32_e32 v94, v94
	v_add_f32_e32 v96, v90, v96
	v_exp_f32_e32 v95, v95
	v_add_f32_e32 v96, v91, v96
	v_add_f32_e32 v96, v92, v96
	v_add_f32_e32 v96, v93, v96
	v_add_f32_e32 v96, v94, v96
	v_add_f32_e32 v243, v95, v96
	v_mov_b32_e32 v244, v243
	v_cvt_pk_bf16_f32 v180, v112, v113
	v_cvt_pk_bf16_f32 v181, v114, v115
	v_cvt_pk_bf16_f32 v182, v116, v117
	v_cvt_pk_bf16_f32 v183, v118, v119
	v_cvt_pk_bf16_f32 v188, v120, v121
	v_cvt_pk_bf16_f32 v189, v122, v123
	v_cvt_pk_bf16_f32 v190, v124, v125
	v_cvt_pk_bf16_f32 v191, v126, v127
	v_cvt_pk_bf16_f32 v192, v80, v81
	v_cvt_pk_bf16_f32 v193, v82, v83
	v_cvt_pk_bf16_f32 v194, v84, v85
	v_cvt_pk_bf16_f32 v195, v86, v87
	v_cvt_pk_bf16_f32 v184, v88, v89
	v_cvt_pk_bf16_f32 v185, v90, v91
	v_cvt_pk_bf16_f32 v186, v92, v93
	v_cvt_pk_bf16_f32 v187, v94, v95
	s_nop 1
	v_permlane32_swap_b32_e32 v243, v244
	v_permlane32_swap_b32_e32 v180, v182
	v_permlane32_swap_b32_e32 v181, v183
	v_permlane32_swap_b32_e32 v188, v190
	v_permlane32_swap_b32_e32 v189, v191
	v_permlane32_swap_b32_e32 v192, v194
	v_permlane32_swap_b32_e32 v193, v195
	v_permlane32_swap_b32_e32 v184, v186
	v_permlane32_swap_b32_e32 v185, v187
	s_lshl_b32 s0, s66, 13
	s_add_i32 s0, s0, 0
	v_add_u32_e32 v84, s0, v224
	v_add_u32_e32 v92, s0, v227
	v_add_u32_e32 v100, s0, v229
	v_add_u32_e32 v108, s0, v230
	ds_read_b128 v[80:83], v84 offset:49152
	ds_read_b128 v[84:87], v84 offset:53248
	ds_read_b128 v[88:91], v92 offset:49152
	ds_read_b128 v[92:95], v92 offset:53248
	ds_read_b128 v[96:99], v100 offset:49152
	ds_read_b128 v[100:103], v100 offset:53248
	ds_read_b128 v[104:107], v108 offset:49152
	ds_read_b128 v[108:111], v108 offset:53248
	s_waitcnt lgkmcnt(7)
	v_mfma_f32_32x32x16_bf16 v[128:143], v[80:83], v[164:167], 0
	s_waitcnt lgkmcnt(6)
	v_mfma_f32_32x32x16_bf16 v[112:127], v[84:87], v[164:167], 0
	s_waitcnt lgkmcnt(5)
	v_mfma_f32_32x32x16_bf16 v[128:143], v[88:91], v[160:163], v[128:143]
	s_waitcnt lgkmcnt(4)
	v_mfma_f32_32x32x16_bf16 v[112:127], v[92:95], v[160:163], v[112:127]
	s_waitcnt lgkmcnt(3)
	v_mfma_f32_32x32x16_bf16 v[128:143], v[96:99], v[156:159], v[128:143]
	s_waitcnt lgkmcnt(2)
	v_mfma_f32_32x32x16_bf16 v[112:127], v[100:103], v[156:159], v[112:127]
	s_waitcnt lgkmcnt(1)
	v_mfma_f32_32x32x16_bf16 v[128:143], v[104:107], v[152:155], v[128:143]
	s_waitcnt lgkmcnt(0)
	v_mfma_f32_32x32x16_bf16 v[112:127], v[108:111], v[152:155], v[112:127]
	s_cmp_lt_u32 s67, 61
	s_cselect_b64 s[0:1], -1, 0
	s_cmp_gt_u32 s67, 60
	s_cbranch_scc1 .LBB0_307
	s_add_u32 s74, s70, 0x18e00000
	s_addc_u32 s75, s71, 0
	global_load_dwordx4 v[168:171], v202, s[74:75] offset:2048
	s_add_u32 s74, s70, 0x18e40000
	s_addc_u32 s75, s71, 0
	global_load_dwordx4 v[172:175], v202, s[74:75] offset:2048
	s_add_u32 s74, s72, 0x18e00000
	s_addc_u32 s75, s73, 0
	global_load_dwordx4 v[176:179], v204, s[74:75] offset:1024

; #define GAS __attribute__((address_space(1)))
; __device__ __forceinline__ float bf2f(unsigned short b) { return __uint_as_float(((unsigned)b) << 16); }
; template <bool GRPB> __device__ __forceinline__ void attn_pass(const float mbK, const float bmax2, const int pass, float* __restrict__ scr, bf16* __restrict__ mixrow, const float lam, const float* __restrict__ gsub, const float one_m_li, ...
;     ...
;   const float cL = __uint_as_float(__builtin_amdgcn_readfirstlane(__float_as_uint(tb2[0]))), cR = __uint_as_float(__builtin_amdgcn_readfirstlane(__float_as_uint(tb2[384])));
;   const int qw = __builtin_amdgcn_readfirstlane(q0seq + wid * 32), qpos = qw + r32;
;   float m_reg, l_reg = 0; bf16x8 qr[4]; f32x16 o[4];
; #pragma unroll
;   for (int d = 0; d < 4; ++d) o[d] = f32x16{};
;   const bf16* Qw = Qb + (long)(wid * 32 + r32) * LDK + hi * 8;
; #pragma unroll
;   for (int d0 = 0; d0 < 4; ++d0) qr[d0] = *(const GAS bf16x8*)(Qw + d0 * 16);
;   { float qs = 0.f;
; #pragma unroll
;     for (int d0 = 0; d0 < 4; ++d0)
; #pragma unroll
;       for (int j = 0; j < 8; ++j) { const float v = bf2f((unsigned short)qr[d0][j]); qs = fmaf(v, v, qs); }
;     ...
;   if (hi == 0) li_e[r32] = l_reg; asm volatile("s_waitcnt lgkmcnt(0)" ::: "memory");
;   GAS f32x4* scr4 = (GAS f32x4*)(scr + (size_t)tid * 64);
;   if (pass == 0) {
; #pragma unroll
;     for (int r4 = 0; r4 < 4; ++r4) { const f32x4 lv = *(const f32x4*)(li_e + 8 * r4 + 4 * hi);
;       const f32x4 rl = (f32x4){__builtin_amdgcn_rcpf(lv[0]), __builtin_amdgcn_rcpf(lv[1]), __builtin_amdgcn_rcpf(lv[2]), __builtin_amdgcn_rcpf(lv[3])};
; #pragma unroll
;       for (int d0 = 0; d0 < 4; ++d0) scr4[d0 * 4 + r4] = (f32x4){o[d0][4 * r4 + 0] * rl[0], o[d0][4 * r4 + 1] * rl[1], o[d0][4 * r4 + 2] * rl[2], o[d0][4 * r4 + 3] * rl[3]}; }
.LBB0_321:
	s_or_b64 exec, exec, s[0:1]
	s_waitcnt lgkmcnt(0)
	v_add_u32_e32 v74, v66, v200
	ds_read_b128 v[66:69], v74
	ds_read_b128 v[70:73], v74 offset:32
	v_ashrrev_i32_e32 v147, 31, v146
	v_lshlrev_b64 v[0:1], 8, v[146:147]
	v_lshl_add_u64 v[0:1], s[40:41], 0, v[0:1]
	s_waitcnt lgkmcnt(1)
	v_rcp_f32_e32 v66, v66
	v_rcp_f32_e32 v67, v67
	v_rcp_f32_e32 v68, v68
	v_rcp_f32_e32 v69, v69
	v_readlane_b32 s0, v254, 39
	v_pk_mul_f32 v[2:3], v[2:3], v[66:67]
	v_mov_b32_e32 v146, v232
	v_pk_mul_f32 v[4:5], v[4:5], v[68:69]
	global_store_dwordx4 v[0:1], v[2:5], off
	v_mov_b32_e32 v201, v144
	s_nop 0
	v_pk_mul_f32 v[2:3], v[18:19], v[66:67]
	v_pk_mul_f32 v[4:5], v[20:21], v[68:69]
	s_waitcnt lgkmcnt(0)
	v_rcp_f32_e32 v18, v70
	v_rcp_f32_e32 v19, v71
	v_rcp_f32_e32 v20, v72
	v_rcp_f32_e32 v21, v73
	global_store_dwordx4 v[0:1], v[2:5], off offset:64
	s_nop 1
	v_pk_mul_f32 v[2:3], v[34:35], v[66:67]
	v_pk_mul_f32 v[4:5], v[36:37], v[68:69]
	global_store_dwordx4 v[0:1], v[2:5], off offset:128
	s_nop 1
	v_pk_mul_f32 v[2:3], v[50:51], v[66:67]
	v_pk_mul_f32 v[4:5], v[52:53], v[68:69]
	global_store_dwordx4 v[0:1], v[2:5], off offset:192
	s_nop 1
	v_pk_mul_f32 v[2:3], v[6:7], v[18:19]
	v_pk_mul_f32 v[4:5], v[8:9], v[20:21]
	global_store_dwordx4 v[0:1], v[2:5], off offset:16
	s_nop 1
	v_pk_mul_f32 v[2:3], v[22:23], v[18:19]
	v_pk_mul_f32 v[4:5], v[24:25], v[20:21]
	global_store_dwordx4 v[0:1], v[2:5], off offset:80
	s_nop 1
	v_pk_mul_f32 v[2:3], v[38:39], v[18:19]
	v_pk_mul_f32 v[4:5], v[40:41], v[20:21]
	global_store_dwordx4 v[0:1], v[2:5], off offset:144
	s_nop 1
	v_pk_mul_f32 v[2:3], v[54:55], v[18:19]
	v_pk_mul_f32 v[4:5], v[56:57], v[20:21]
	global_store_dwordx4 v[0:1], v[2:5], off offset:208
	ds_read_b128 v[2:5], v74 offset:64
	s_waitcnt lgkmcnt(0)
	v_rcp_f32_e32 v6, v2
	v_rcp_f32_e32 v7, v3
	v_rcp_f32_e32 v8, v4
	v_rcp_f32_e32 v9, v5
	v_pk_mul_f32 v[2:3], v[10:11], v[6:7]
	v_mov_b32_e32 v11, v144
	v_pk_mul_f32 v[4:5], v[12:13], v[8:9]
	global_store_dwordx4 v[0:1], v[2:5], off offset:32
	s_nop 1
	v_pk_mul_f32 v[2:3], v[26:27], v[6:7]
	v_pk_mul_f32 v[4:5], v[28:29], v[8:9]
	global_store_dwordx4 v[0:1], v[2:5], off offset:96
	s_nop 1
	v_pk_mul_f32 v[2:3], v[42:43], v[6:7]
	v_pk_mul_f32 v[4:5], v[44:45], v[8:9]
	global_store_dwordx4 v[0:1], v[2:5], off offset:160
	s_nop 1
	v_pk_mul_f32 v[2:3], v[58:59], v[6:7]
	v_pk_mul_f32 v[4:5], v[60:61], v[8:9]
	global_store_dwordx4 v[0:1], v[2:5], off offset:224
	ds_read_b128 v[2:5], v74 offset:96
	s_waitcnt lgkmcnt(0)
	v_rcp_f32_e32 v6, v2
	v_rcp_f32_e32 v7, v3
	v_rcp_f32_e32 v8, v4
	v_rcp_f32_e32 v9, v5
	v_pk_mul_f32 v[2:3], v[14:15], v[6:7]
	v_pk_mul_f32 v[4:5], v[16:17], v[8:9]
	global_store_dwordx4 v[0:1], v[2:5], off offset:48
	s_nop 1
	v_pk_mul_f32 v[2:3], v[30:31], v[6:7]
	v_pk_mul_f32 v[4:5], v[32:33], v[8:9]
	global_store_dwordx4 v[0:1], v[2:5], off offset:112
	s_nop 1
	v_pk_mul_f32 v[2:3], v[46:47], v[6:7]
	v_pk_mul_f32 v[4:5], v[48:49], v[8:9]
	global_store_dwordx4 v[0:1], v[2:5], off offset:176
	s_nop 1
	v_pk_mul_f32 v[2:3], v[62:63], v[6:7]
	v_pk_mul_f32 v[4:5], v[64:65], v[8:9]
	global_store_dwordx4 v[0:1], v[2:5], off offset:240
	v_mov_b32_e32 v0, s0
	ds_read_b32 v0, v0
	v_readlane_b32 s0, v254, 40
	v_bfe_u32 v217, v146, 5, 1
	v_lshlrev_b32_e32 v200, 4, v217
	v_lshlrev_b32_e32 v12, 3, v146
	s_waitcnt lgkmcnt(0)
	v_readfirstlane_b32 s62, v0
	v_mov_b32_e32 v0, s0
	ds_read_b32 v0, v0
	s_movk_i32 s0, 0xffe0
	v_bfe_u32 v5, v12, 5, 2
	v_lshlrev_b32_e32 v6, 4, v146
	v_and_b32_e32 v7, 48, v6
	s_waitcnt lgkmcnt(0)
	v_readfirstlane_b32 s63, v0
	v_ashrrev_i32_e32 v0, 1, v146
	v_and_b32_e32 v215, 0xffffffe0, v0
	v_add_u32_e32 v1, s39, v215
	v_bfi_b32 v0, s0, v0, v146
	v_readfirstlane_b32 s64, v1
	v_ashrrev_i32_e32 v1, 31, v0
	v_lshlrev_b64 v[0:1], 13, v[0:1]
	v_lshl_add_u64 v[0:1], s[52:53], 0, v[0:1]
	v_lshl_add_u64 v[0:1], v[0:1], 0, v[200:201]
	global_load_dwordx4 v[164:167], v[0:1], off offset:128
	global_load_dwordx4 v[160:163], v[0:1], off offset:160
	global_load_dwordx4 v[152:155], v[0:1], off offset:192
	global_load_dwordx4 v[156:159], v[0:1], off offset:224
	v_and_b32_e32 v10, 0x70, v6
	s_barrier
	v_and_b32_e32 v218, 31, v146
	v_add_u32_e32 v147, s64, v218
	s_waitcnt vmcnt(3)
	v_lshlrev_b32_e32 v0, 16, v164
	v_fma_f32 v0, v0, v0, 0
	v_and_b32_e32 v1, 0xffff0000, v164
	v_fmac_f32_e32 v0, v1, v1
	v_lshlrev_b32_e32 v1, 16, v165
	v_fmac_f32_e32 v0, v1, v1
	v_and_b32_e32 v1, 0xffff0000, v165
	v_fmac_f32_e32 v0, v1, v1
	v_lshlrev_b32_e32 v1, 16, v166
	v_fmac_f32_e32 v0, v1, v1
	v_and_b32_e32 v1, 0xffff0000, v166
	v_fmac_f32_e32 v0, v1, v1
	v_lshlrev_b32_e32 v1, 16, v167
	v_fmac_f32_e32 v0, v1, v1
	v_and_b32_e32 v1, 0xffff0000, v167
	v_fmac_f32_e32 v0, v1, v1
	s_waitcnt vmcnt(2)
	v_lshlrev_b32_e32 v1, 16, v160
	v_fmac_f32_e32 v0, v1, v1
	v_and_b32_e32 v1, 0xffff0000, v160
	v_fmac_f32_e32 v0, v1, v1
	v_lshlrev_b32_e32 v1, 16, v161
	v_fmac_f32_e32 v0, v1, v1
	v_and_b32_e32 v1, 0xffff0000, v161
	v_fmac_f32_e32 v0, v1, v1
	v_lshlrev_b32_e32 v1, 16, v162
	v_fmac_f32_e32 v0, v1, v1
	v_and_b32_e32 v1, 0xffff0000, v162
	v_fmac_f32_e32 v0, v1, v1
	v_lshlrev_b32_e32 v1, 16, v163
	v_fmac_f32_e32 v0, v1, v1
	v_and_b32_e32 v1, 0xffff0000, v163
	v_fmac_f32_e32 v0, v1, v1
	s_waitcnt vmcnt(1)
	v_lshlrev_b32_e32 v1, 16, v152
	v_fmac_f32_e32 v0, v1, v1
	v_and_b32_e32 v1, 0xffff0000, v152
	v_fmac_f32_e32 v0, v1, v1
	v_lshlrev_b32_e32 v1, 16, v153
	v_fmac_f32_e32 v0, v1, v1
	v_and_b32_e32 v1, 0xffff0000, v153
	v_fmac_f32_e32 v0, v1, v1
	v_lshlrev_b32_e32 v1, 16, v154
	v_fmac_f32_e32 v0, v1, v1
	v_and_b32_e32 v1, 0xffff0000, v154
	v_fmac_f32_e32 v0, v1, v1
	v_lshlrev_b32_e32 v1, 16, v155
	v_fmac_f32_e32 v0, v1, v1
	v_and_b32_e32 v1, 0xffff0000, v155
	v_fmac_f32_e32 v0, v1, v1
	s_waitcnt vmcnt(0)
; __device__ __forceinline__ float bf2f(unsigned short b) { return __uint_as_float(((unsigned)b) << 16); }
; __device__ __forceinline__ int v_st(int k, int c) { const int kk = (k & ~0xC) | ((k & 4) << 1) | ((k & 8) >> 1); return ((kk >> 3) * 4 + (c >> 5)) * 512 + ((kk & 7) * 32 + (c & 31)) * 2; }
; __device__ __forceinline__ int v_rd_base(int lane) { return ((lane & 3) << 3) | (((lane >> 2) & 3) << 6) | (((lane >> 4) & 1) << 5) | (((lane >> 5) & 1) << 8); }
; #define SLOAD(i, k0) do { sr_[i].vs0 = *(const GAS bf16x8*)(&Vh[(long)((k0) + sr) * LDK + sc]); sr_[i].vs1 = *(const GAS bf16x8*)(&Vh[(long)((k0) + 32 + sr) * LDK + sc]); \
;     sr_[i].ks0 = *(const GAS bf16x8*)(&Kh[(long)((k0) + kr) * LDK + kc]); } while (0)
; #define SWRITE(b, i) do { *(bf16x8*)(V_lds + (b) * SHM_V + vst0) = sr_[i].vs0; *(bf16x8*)(V_lds + (b) * SHM_V + vst1) = sr_[i].vs1; \
;     *(bf16x8*)(K_lds + (b) * SHM_K + kst) = sr_[i].ks0; } while (0)
; template <bool GRPB> __device__ __forceinline__ void attn_pass(const float mbK, const float bmax2, const int pass, float* __restrict__ scr, bf16* __restrict__ mixrow, const float lam, const float* __restrict__ gsub, const float one_m_li, ...
;     ...
;       for (int j = 0; j < 8; ++j) { const float v = bf2f((unsigned short)qr[d0][j]); qs = fmaf(v, v, qs); }
;     { auto rr = __builtin_amdgcn_permlane32_swap(__float_as_uint(qs), __float_as_uint(qs), false, false); qs = __uint_as_float(rr[0]) + __uint_as_float(rr[1]); }
;     m_reg = __builtin_sqrtf(qs) * mbK + bmax2 + 0.25f; }
;   const int sr = tid >> 4, sc = (tid & 15) * 8, vst0 = v_st(sr, sc), vst1 = v_st(32 + sr, sc);
;   const int kr = tid >> 3, kc = (tid & 7) * 8, kst = KSWZ64(kr, kc * 2);
;   const int vb0 = (int)(uintptr_t)V_lds + v_rd_base(lane);
;   struct { bf16x8 vs0, vs1, ks0; } sr_[2];
;     ...
;   f32x16 pA0, pA1, pB0, pB1; float mnA, mnB, alA, alB; bf16x8 pa0, pa1, pa2, pa3; constexpr int NT = SEQ / KVBLK;
;   __syncthreads();
;   SLOAD(0, 0); SLOAD(1, KVBLK); asm volatile("s_waitcnt vmcnt(0)" ::: "memory"); SWRITE(0, 0); SWRITE(1, 1);
;   SLOAD(0, 2 * KVBLK); asm volatile("s_waitcnt vmcnt(0)" ::: "memory"); SWRITE(2, 0); __syncthreads();
	v_lshlrev_b32_e32 v1, 16, v156
	v_fmac_f32_e32 v0, v1, v1
	v_and_b32_e32 v1, 0xffff0000, v156
	v_fmac_f32_e32 v0, v1, v1
	v_lshlrev_b32_e32 v1, 16, v157
	v_fmac_f32_e32 v0, v1, v1
	v_and_b32_e32 v1, 0xffff0000, v157
	v_fmac_f32_e32 v0, v1, v1
	v_lshlrev_b32_e32 v1, 16, v158
	v_fmac_f32_e32 v0, v1, v1
	v_and_b32_e32 v1, 0xffff0000, v158
	v_fmac_f32_e32 v0, v1, v1
	v_lshlrev_b32_e32 v1, 16, v159
	v_fmac_f32_e32 v0, v1, v1
	v_and_b32_e32 v1, 0xffff0000, v159
	v_fmac_f32_e32 v0, v1, v1
	v_mov_b32_e32 v1, v0
	s_nop 1
	v_permlane32_swap_b32_e32 v0, v1
	v_add_f32_e32 v0, v0, v1
	v_cmp_gt_f32_e32 vcc, s10, v0
	v_mul_f32_e32 v1, 0x4f800000, v0
	s_nop 0
	v_cndmask_b32_e32 v0, v0, v1, vcc
	v_sqrt_f32_e32 v1, v0
	s_nop 0
	v_add_u32_e32 v2, -1, v1
	v_fma_f32 v3, -v2, v1, v0
	v_cmp_ge_f32_e64 s[0:1], 0, v3
	v_add_u32_e32 v3, 1, v1
	s_nop 0
	v_cndmask_b32_e64 v2, v1, v2, s[0:1]
	v_fma_f32 v1, -v3, v1, v0
	v_cmp_lt_f32_e64 s[0:1], 0, v1
	s_nop 1
	v_cndmask_b32_e64 v1, v2, v3, s[0:1]
	v_mul_f32_e32 v2, 0x37800000, v1
	v_cndmask_b32_e32 v1, v1, v2, vcc
	v_cmp_class_f32_e32 vcc, v0, v198
	v_and_b32_e32 v2, 0x78, v12
	v_lshlrev_b32_e32 v6, 1, v2
	v_cndmask_b32_e32 v0, v1, v0, vcc
	v_fma_f32 v0, v214, v0, s45
	v_add_f32_e32 v64, 0x3e800000, v0
	v_ashrrev_i32_e32 v0, 4, v146
	v_and_b32_e32 v1, 0xfffff0, v0
	v_lshlrev_b32_e32 v3, 1, v0
	v_and_or_b32 v1, v3, 8, v1
	v_lshrrev_b32_e32 v3, 1, v0
	v_lshrrev_b32_e32 v1, 1, v1
	v_and_b32_e32 v4, 3, v0
	v_or_b32_e32 v1, v1, v5
	v_and_or_b32 v3, v3, 4, v4
	v_lshlrev_b32_e32 v1, 9, v1
	v_lshlrev_b32_e32 v3, 6, v3
	v_add_u32_e32 v4, 32, v0
	v_or3_b32 v221, v1, v3, v7
	v_and_b32_e32 v1, 0xfffff0, v4
	v_lshlrev_b32_e32 v8, 1, v4
	v_and_or_b32 v1, v8, 8, v1
	v_lshrrev_b32_e32 v1, 1, v1
	v_or_b32_e32 v1, v1, v5
	v_lshlrev_b32_e32 v1, 9, v1
	v_ashrrev_i32_e32 v8, 3, v146
	v_or3_b32 v222, v1, v3, v7
	v_lshlrev_b32_e32 v1, 7, v8
	v_and_b32_e32 v3, 0x70, v146
	v_bitop3_b32 v223, v10, v1, v3 bitop3:0xde
	v_ashrrev_i32_e32 v1, 31, v0
	v_lshlrev_b64 v[48:49], 13, v[0:1]
	v_lshl_add_u64 v[0:1], s[50:51], 0, v[48:49]
	v_mov_b32_e32 v7, v144
	v_ashrrev_i32_e32 v5, 31, v4
	v_lshl_add_u64 v[26:27], v[0:1], 0, v[6:7]
	v_lshlrev_b64 v[4:5], 13, v[4:5]
	global_load_dwordx4 v[0:3], v[26:27], off offset:2048
	v_lshl_add_u64 v[4:5], s[50:51], 0, v[4:5]
	v_ashrrev_i32_e32 v9, 31, v8
	s_mov_b32 s0, 0x80000
	v_lshl_add_u64 v[4:5], v[4:5], 0, v[6:7]
	v_lshlrev_b64 v[50:51], 13, v[8:9]
	v_add_co_u32_e32 v14, vcc, s0, v26
	global_load_dwordx4 v[4:7], v[4:5], off offset:2048
	v_lshl_add_u64 v[8:9], s[50:51], 0, v[50:51]
	v_addc_co_u32_e32 v15, vcc, 0, v27, vcc
	s_mov_b32 s1, 0xc0000
	v_lshl_add_u64 v[28:29], v[8:9], 0, v[10:11]
	v_add_co_u32_e32 v18, vcc, s1, v26
	global_load_dwordx4 v[8:11], v[28:29], off offset:1152
	s_nop 0
	v_addc_co_u32_e32 v19, vcc, 0, v27, vcc
	global_load_dwordx4 v[14:17], v[14:15], off offset:2048
	v_add_co_u32_e32 v22, vcc, s0, v28
	global_load_dwordx4 v[18:21], v[18:19], off offset:2048
	s_nop 0
	v_addc_co_u32_e32 v23, vcc, 0, v29, vcc
	global_load_dwordx4 v[22:25], v[22:23], off offset:1152
	v_add_u32_e32 v13, 0, v221
	s_mov_b32 s0, 0x100000
	s_waitcnt vmcnt(3)
	v_add_u32_e32 v30, 0, v222
	s_mov_b32 s1, 0x140000
	v_add_u32_e32 v224, 0, v223
	s_waitcnt vmcnt(5)
	ds_write_b128 v13, v[0:3]
	v_add_co_u32_e32 v0, vcc, s0, v26
	s_waitcnt vmcnt(4)
	ds_write_b128 v30, v[4:7]
	v_addc_co_u32_e32 v1, vcc, 0, v27, vcc
	v_add_co_u32_e32 v4, vcc, s1, v26
	s_waitcnt vmcnt(3)
	ds_write_b128 v224, v[8:11] offset:49152
	v_addc_co_u32_e32 v5, vcc, 0, v27, vcc
	v_add_co_u32_e32 v8, vcc, s0, v28
	global_load_dwordx4 v[0:3], v[0:1], off offset:2048
	s_nop 0
	v_addc_co_u32_e32 v9, vcc, 0, v29, vcc
	global_load_dwordx4 v[4:7], v[4:5], off offset:2048
	s_nop 0
	global_load_dwordx4 v[8:11], v[8:9], off offset:1152
	s_waitcnt vmcnt(5)
	ds_write_b128 v13, v[14:17] offset:16384
	s_waitcnt vmcnt(4)
	ds_write_b128 v30, v[18:21] offset:16384
	s_waitcnt vmcnt(3)
	ds_write_b128 v224, v[22:25] offset:57344
	s_waitcnt vmcnt(0)
	s_waitcnt vmcnt(2)
	ds_write_b128 v13, v[0:3] offset:32768
	s_waitcnt vmcnt(1)
	ds_write_b128 v30, v[4:7] offset:32768
	v_add_u32_e32 v0, 0x10000, v224
	s_waitcnt vmcnt(0)
	ds_write_b128 v0, v[8:11]
	v_lshlrev_b32_e32 v8, 7, v218
	v_and_b32_e32 v9, 0x70, v12
	v_or_b32_e32 v10, 32, v200
	v_bitop3_b32 v229, v10, v8, v9 bitop3:0xde
	v_or_b32_e32 v10, 64, v200
	v_bitop3_b32 v231, v10, v8, v9 bitop3:0xde
	v_or_b32_e32 v10, 0x60, v200
	v_bitop3_b32 v226, v200, v8, v9 bitop3:0xde
	v_bitop3_b32 v240, v10, v8, v9 bitop3:0xde
	v_add_u32_e32 v225, 0, v226
	v_add_u32_e32 v227, 0, v229
	v_add_u32_e32 v228, 0, v231
	v_add_u32_e32 v230, 0, v240
	s_waitcnt lgkmcnt(0)
	s_barrier
; #define SBAR() __builtin_amdgcn_sched_barrier(0)
; __device__ __forceinline__ void partialSM(f32x16& p0, f32x16& p1, float& m_reg, float& mn, float& alpha, int kt0, int qpos, int qw, int hi, const float* tb2, float cL, float cR) {
;   mn = m_reg; alpha = 1.f;
;   const int rel_hi = kt0 + 63 - qw, rel_lo = kt0 - (qw + 31);
;   if (rel_hi <= -91 || rel_lo >= 91) {
;     const float cm = ((rel_hi <= -91) ? cL : cR) - m_reg;
; #pragma unroll
;     for (int r = 0; r < 16; ++r) { p0[r] = fmaf(p0[r], C1, cm); p1[r] = fmaf(p1[r], C1, cm); }
;   } else {
;     const float* tp = tb2 + (kt0 - qpos + 192 + 4 * hi);
; #pragma unroll
;     for (int r4 = 0; r4 < 4; ++r4) {
;       float ta[4], tb[4];
; #pragma unroll
;       for (int i = 0; i < 4; ++i) { ta[i] = tp[8 * r4 + i] - m_reg; tb[i] = tp[32 + 8 * r4 + i] - m_reg; }
; #pragma unroll
;       for (int i = 0; i < 4; ++i) { p0[4 * r4 + i] = fmaf(p0[4 * r4 + i], C1, ta[i]); p1[4 * r4 + i] = fmaf(p1[4 * r4 + i], C1, tb[i]); }
; __device__ __forceinline__ void qkt(f32x16& p0, f32x16& p1, const char* Ks, const bf16x8* qr, int r32, int hi) {
;   bf16x8 ka[4], kb[4];
; #pragma unroll
;   for (int d0 = 0; d0 < 4; ++d0) { const int cb = (d0 * 16 + hi * 8) * 2;
;     ka[d0] = *reinterpret_cast<const bf16x8*>(Ks + KSWZ64(r32, cb)); kb[d0] = *reinterpret_cast<const bf16x8*>(Ks + KSWZ64(32 + r32, cb)); }
;   asm volatile("s_waitcnt lgkmcnt(0)" ::: "memory"); SBAR();
;   p0 = f32x16{}; p1 = f32x16{};
; #pragma unroll
;   for (int d0 = 0; d0 < 4; ++d0) {
;     p0 = __builtin_amdgcn_mfma_f32_32x32x16_bf16(ka[d0], qr[d0], p0, 0, 0, 0);
;     p1 = __builtin_amdgcn_mfma_f32_32x32x16_bf16(kb[d0], qr[d0], p1, 0, 0, 0); }
	ds_read_b128 v[0:3], v225 offset:49152
	ds_read_b128 v[4:7], v225 offset:53248
	ds_read_b128 v[32:35], v227 offset:49152
	ds_read_b128 v[36:39], v227 offset:53248
	ds_read_b128 v[40:43], v228 offset:49152
	ds_read_b128 v[44:47], v228 offset:53248
	ds_read_b128 v[52:55], v230 offset:49152
	ds_read_b128 v[56:59], v230 offset:53248
	s_waitcnt lgkmcnt(7)
	v_mfma_f32_32x32x16_bf16 v[16:31], v[0:3], v[164:167], 0
	s_add_i32 s4, s64, 0xffffff66
	s_mov_b64 s[0:1], -1
	s_cmp_gt_u32 s4, 0xfffffeec
	s_waitcnt lgkmcnt(6)
	v_mfma_f32_32x32x16_bf16 v[0:15], v[4:7], v[164:167], 0
	s_waitcnt lgkmcnt(5)
	v_mfma_f32_32x32x16_bf16 v[16:31], v[32:35], v[160:163], v[16:31]
	s_waitcnt lgkmcnt(4)
	v_mfma_f32_32x32x16_bf16 v[0:15], v[36:39], v[160:163], v[0:15]
	s_waitcnt lgkmcnt(3)
	v_mfma_f32_32x32x16_bf16 v[16:31], v[40:43], v[152:155], v[16:31]
	s_waitcnt lgkmcnt(2)
	v_mfma_f32_32x32x16_bf16 v[0:15], v[44:47], v[152:155], v[0:15]
	s_waitcnt lgkmcnt(1)
	v_mfma_f32_32x32x16_bf16 v[16:31], v[52:55], v[156:159], v[16:31]
	v_lshlrev_b32_e32 v52, 2, v147
	s_waitcnt lgkmcnt(0)
	v_mfma_f32_32x32x16_bf16 v[0:15], v[56:59], v[156:159], v[0:15]
	s_cbranch_scc0 .LBB0_323
	v_sub_u32_e32 v32, 0, v52
	s_mov_b32 s0, 0x12b00
	v_add3_u32 v53, v32, v200, s0
	ds_read2_b32 v[32:33], v53 offset1:1
	ds_read2_b32 v[54:55], v53 offset0:32 offset1:33
	ds_read2_b32 v[56:57], v53 offset0:34 offset1:35
	ds_read2_b32 v[34:35], v53 offset0:2 offset1:3
	ds_read2_b32 v[36:37], v53 offset0:8 offset1:9
	ds_read2_b32 v[58:59], v53 offset0:40 offset1:41
	ds_read2_b32 v[60:61], v53 offset0:42 offset1:43
	ds_read2_b32 v[38:39], v53 offset0:10 offset1:11
	ds_read2_b32 v[40:41], v53 offset0:16 offset1:17
	ds_read2_b32 v[62:63], v53 offset0:48 offset1:49
	ds_read2_b32 v[66:67], v53 offset0:50 offset1:51
	ds_read2_b32 v[42:43], v53 offset0:18 offset1:19
	ds_read2_b32 v[44:45], v53 offset0:24 offset1:25
	ds_read2_b32 v[46:47], v53 offset0:26 offset1:27
	ds_read2_b32 v[68:69], v53 offset0:58 offset1:59
	ds_read2_b32 v[70:71], v53 offset0:56 offset1:57
	s_waitcnt lgkmcnt(3)
	v_sub_f32_e32 v45, v45, v64
	v_sub_f32_e32 v44, v44, v64
	s_waitcnt lgkmcnt(2)
	v_sub_f32_e32 v47, v47, v64
	v_sub_f32_e32 v46, v46, v64
	v_sub_f32_e32 v41, v41, v64
	v_sub_f32_e32 v40, v40, v64
	v_sub_f32_e32 v43, v43, v64
	v_sub_f32_e32 v42, v42, v64
	v_sub_f32_e32 v37, v37, v64
	v_sub_f32_e32 v36, v36, v64
	v_sub_f32_e32 v39, v39, v64
	v_sub_f32_e32 v38, v38, v64
	v_sub_f32_e32 v33, v33, v64
	v_sub_f32_e32 v32, v32, v64
	v_sub_f32_e32 v35, v35, v64
	v_sub_f32_e32 v34, v34, v64
	s_waitcnt lgkmcnt(0)
	v_sub_f32_e32 v71, v71, v64
	v_sub_f32_e32 v70, v70, v64
	v_sub_f32_e32 v69, v69, v64
	v_sub_f32_e32 v68, v68, v64
	v_sub_f32_e32 v63, v63, v64
	v_sub_f32_e32 v62, v62, v64
	v_sub_f32_e32 v67, v67, v64
	v_sub_f32_e32 v66, v66, v64
	v_sub_f32_e32 v59, v59, v64
	v_sub_f32_e32 v58, v58, v64
	v_sub_f32_e32 v61, v61, v64
	v_sub_f32_e32 v60, v60, v64
	v_sub_f32_e32 v55, v55, v64
	v_sub_f32_e32 v54, v54, v64
	v_sub_f32_e32 v57, v57, v64
	v_sub_f32_e32 v56, v56, v64
	v_pk_fma_f32 v[34:35], v[18:19], s[6:7], v[34:35] op_sel_hi:[1,0,1]
	v_pk_fma_f32 v[32:33], v[16:17], s[6:7], v[32:33] op_sel_hi:[1,0,1]
	v_pk_fma_f32 v[38:39], v[22:23], s[6:7], v[38:39] op_sel_hi:[1,0,1]
	v_pk_fma_f32 v[36:37], v[20:21], s[6:7], v[36:37] op_sel_hi:[1,0,1]
	v_pk_fma_f32 v[42:43], v[26:27], s[6:7], v[42:43] op_sel_hi:[1,0,1]
	v_pk_fma_f32 v[40:41], v[24:25], s[6:7], v[40:41] op_sel_hi:[1,0,1]
	v_pk_fma_f32 v[46:47], v[30:31], s[6:7], v[46:47] op_sel_hi:[1,0,1]
	v_pk_fma_f32 v[44:45], v[28:29], s[6:7], v[44:45] op_sel_hi:[1,0,1]
	v_pk_fma_f32 v[82:83], v[2:3], s[6:7], v[56:57] op_sel_hi:[1,0,1]
	v_pk_fma_f32 v[80:81], v[0:1], s[6:7], v[54:55] op_sel_hi:[1,0,1]
	v_pk_fma_f32 v[86:87], v[6:7], s[6:7], v[60:61] op_sel_hi:[1,0,1]
	v_pk_fma_f32 v[84:85], v[4:5], s[6:7], v[58:59] op_sel_hi:[1,0,1]
	v_pk_fma_f32 v[90:91], v[10:11], s[6:7], v[66:67] op_sel_hi:[1,0,1]
	v_pk_fma_f32 v[88:89], v[8:9], s[6:7], v[62:63] op_sel_hi:[1,0,1]
	v_pk_fma_f32 v[94:95], v[14:15], s[6:7], v[68:69] op_sel_hi:[1,0,1]
	v_pk_fma_f32 v[92:93], v[12:13], s[6:7], v[70:71] op_sel_hi:[1,0,1]
	s_mov_b64 s[0:1], 0

; #define SBAR() __builtin_amdgcn_sched_barrier(0)
; __device__ __forceinline__ void finishSM(f32x16& p0, f32x16& p1, float alpha, float& l_reg, bf16x8& pa0, bf16x8& pa1, bf16x8& pa2, bf16x8& pa3) {
; #pragma unroll
;   for (int r = 0; r < 16; ++r) p1[r] = __builtin_amdgcn_exp2f(p1[r]);
;   float ps = 0;
; #pragma unroll
;   for (int r = 0; r < 16; ++r) ps += p0[r];
; #pragma unroll
;   for (int r = 0; r < 16; ++r) ps += p1[r];
;   { auto rr = __builtin_amdgcn_permlane32_swap(__float_as_uint(ps), __float_as_uint(ps), false, false);
;     ps = __uint_as_float(rr[0]) + __uint_as_float(rr[1]); }
;   l_reg = l_reg * alpha + ps;
;     ...
;   PK4(p0, 0, pa0); PK4(p0, 8, pa1); PK4(p1, 0, pa2); PK4(p1, 8, pa3);
;     ...
; }
; __device__ __forceinline__ void qkt(f32x16& p0, f32x16& p1, const char* Ks, const bf16x8* qr, int r32, int hi) {
;   bf16x8 ka[4], kb[4];
; #pragma unroll
;   for (int d0 = 0; d0 < 4; ++d0) { const int cb = (d0 * 16 + hi * 8) * 2;
;     ka[d0] = *reinterpret_cast<const bf16x8*>(Ks + KSWZ64(r32, cb)); kb[d0] = *reinterpret_cast<const bf16x8*>(Ks + KSWZ64(32 + r32, cb)); }
;   asm volatile("s_waitcnt lgkmcnt(0)" ::: "memory"); SBAR();
;   p0 = f32x16{}; p1 = f32x16{};
; #pragma unroll
;   for (int d0 = 0; d0 < 4; ++d0) {
;     p0 = __builtin_amdgcn_mfma_f32_32x32x16_bf16(ka[d0], qr[d0], p0, 0, 0, 0);
;     p1 = __builtin_amdgcn_mfma_f32_32x32x16_bf16(kb[d0], qr[d0], p1, 0, 0, 0); }
.LBB0_326:
	s_mov_b32 s68, s65
	s_mov_b32 s65, s0
	v_add_f32_e32 v96, 0, v141
	v_add_f32_e32 v96, v143, v96
	v_add_f32_e32 v96, v139, v96
	v_add_f32_e32 v96, v142, v96
	v_add_f32_e32 v96, v137, v96
	v_add_f32_e32 v96, v140, v96
	v_add_f32_e32 v96, v136, v96
	v_add_f32_e32 v96, v138, v96
	v_add_f32_e32 v96, v133, v96
	v_add_f32_e32 v96, v135, v96
	v_add_f32_e32 v96, v131, v96
	v_add_f32_e32 v96, v134, v96
	v_exp_f32_e32 v80, v80
	v_add_f32_e32 v96, v129, v96
	v_exp_f32_e32 v81, v81
	v_add_f32_e32 v96, v132, v96
	v_exp_f32_e32 v82, v82
	v_add_f32_e32 v96, v128, v96
	v_exp_f32_e32 v83, v83
	v_add_f32_e32 v96, v130, v96
	v_exp_f32_e32 v84, v84
	v_add_f32_e32 v96, v80, v96
	v_exp_f32_e32 v85, v85
	v_add_f32_e32 v96, v81, v96
	v_exp_f32_e32 v86, v86
	v_add_f32_e32 v96, v82, v96
	v_exp_f32_e32 v87, v87
	v_add_f32_e32 v96, v83, v96
	v_exp_f32_e32 v88, v88
	v_add_f32_e32 v96, v84, v96
	v_exp_f32_e32 v89, v89
	v_add_f32_e32 v96, v85, v96
	v_exp_f32_e32 v90, v90
	v_add_f32_e32 v96, v86, v96
	v_exp_f32_e32 v91, v91
	v_add_f32_e32 v96, v87, v96
	v_exp_f32_e32 v92, v92
	v_add_f32_e32 v96, v88, v96
	v_exp_f32_e32 v93, v93
	v_add_f32_e32 v96, v89, v96
	v_exp_f32_e32 v94, v94
	v_add_f32_e32 v96, v90, v96
	v_exp_f32_e32 v95, v95
	v_add_f32_e32 v96, v91, v96
	v_add_f32_e32 v96, v92, v96
	v_add_f32_e32 v96, v93, v96
	v_add_f32_e32 v96, v94, v96
	v_add_f32_e32 v243, v95, v96
	v_mov_b32_e32 v244, v243
	v_cvt_pk_bf16_f32 v180, v141, v143
	v_cvt_pk_bf16_f32 v181, v139, v142
	v_cvt_pk_bf16_f32 v182, v137, v140
	v_cvt_pk_bf16_f32 v183, v136, v138
	v_cvt_pk_bf16_f32 v184, v133, v135
	v_cvt_pk_bf16_f32 v185, v131, v134
	v_cvt_pk_bf16_f32 v186, v129, v132
	v_cvt_pk_bf16_f32 v187, v128, v130
	v_cvt_pk_bf16_f32 v188, v80, v81
	v_cvt_pk_bf16_f32 v189, v82, v83
	v_cvt_pk_bf16_f32 v190, v84, v85
	v_cvt_pk_bf16_f32 v191, v86, v87
	v_cvt_pk_bf16_f32 v192, v88, v89
	v_cvt_pk_bf16_f32 v193, v90, v91
	v_cvt_pk_bf16_f32 v194, v92, v93
	v_cvt_pk_bf16_f32 v195, v94, v95
	s_nop 1
	v_permlane32_swap_b32_e32 v243, v244
	v_permlane32_swap_b32_e32 v180, v182
	v_permlane32_swap_b32_e32 v181, v183
	v_permlane32_swap_b32_e32 v184, v186
	v_permlane32_swap_b32_e32 v185, v187
	v_permlane32_swap_b32_e32 v188, v190
	v_permlane32_swap_b32_e32 v189, v191
	v_permlane32_swap_b32_e32 v192, v194
	v_permlane32_swap_b32_e32 v193, v195
	s_lshl_b32 s0, s68, 13
	s_add_i32 s4, s0, 0
	v_add_u32_e32 v84, s4, v226
	v_add_u32_e32 v92, s4, v229
	v_add_u32_e32 v96, s4, v231
	ds_read_b128 v[80:83], v84 offset:49152
	ds_read_b128 v[84:87], v84 offset:53248
	ds_read_b128 v[88:91], v92 offset:49152
	ds_read_b128 v[92:95], v92 offset:53248
	ds_read_b128 v[128:131], v96 offset:49152
	ds_read_b128 v[132:135], v96 offset:53248
	v_add_u32_e32 v96, s4, v240
	ds_read_b128 v[136:139], v96 offset:49152
	ds_read_b128 v[140:143], v96 offset:53248
	s_waitcnt lgkmcnt(7)
	v_mfma_f32_32x32x16_bf16 v[112:127], v[80:83], v[164:167], 0
	s_waitcnt lgkmcnt(6)
	v_mfma_f32_32x32x16_bf16 v[96:111], v[84:87], v[164:167], 0
	s_waitcnt lgkmcnt(5)
	v_mfma_f32_32x32x16_bf16 v[112:127], v[88:91], v[160:163], v[112:127]
	s_waitcnt lgkmcnt(4)
	v_mfma_f32_32x32x16_bf16 v[96:111], v[92:95], v[160:163], v[96:111]
	s_waitcnt lgkmcnt(3)
	v_mfma_f32_32x32x16_bf16 v[112:127], v[128:131], v[152:155], v[112:127]
	s_waitcnt lgkmcnt(2)
	v_mfma_f32_32x32x16_bf16 v[96:111], v[132:135], v[152:155], v[96:111]
	s_waitcnt lgkmcnt(1)
	v_mfma_f32_32x32x16_bf16 v[112:127], v[136:139], v[156:159], v[112:127]
	s_waitcnt lgkmcnt(0)
	v_mfma_f32_32x32x16_bf16 v[96:111], v[140:143], v[156:159], v[96:111]
	s_add_u32 s74, s70, s15
	s_addc_u32 s75, s71, 0
	global_load_dwordx4 v[168:171], v202, s[74:75] offset:2048
	s_add_u32 s74, s70, 0x18dc0000
	s_addc_u32 s75, s71, 0
	global_load_dwordx4 v[172:175], v202, s[74:75] offset:2048
	s_add_u32 s74, s72, 0x18d80000
	s_addc_u32 s75, s73, 0
	global_load_dwordx4 v[176:179], v204, s[74:75] offset:1152
	s_add_i32 s0, s66, 0xffffff47
	s_cmp_gt_u32 s0, 0xfffffeec
	s_mov_b64 s[0:1], -1
	s_cbranch_scc0 .LBB0_328
; __device__ __forceinline__ void partialSM(f32x16& p0, f32x16& p1, float& m_reg, float& mn, float& alpha, int kt0, int qpos, int qw, int hi, const float* tb2, float cL, float cR) {
;     ...
;   } else {
;     const float* tp = tb2 + (kt0 - qpos + 192 + 4 * hi);
; #pragma unroll
;     for (int r4 = 0; r4 < 4; ++r4) {
;       float ta[4], tb[4];
; #pragma unroll
;       for (int i = 0; i < 4; ++i) { ta[i] = tp[8 * r4 + i] - m_reg; tb[i] = tp[32 + 8 * r4 + i] - m_reg; }
; #pragma unroll
;       for (int i = 0; i < 4; ++i) { p0[4 * r4 + i] = fmaf(p0[4 * r4 + i], C1, ta[i]); p1[4 * r4 + i] = fmaf(p1[4 * r4 + i], C1, tb[i]); }
;       asm volatile("" ::: "memory");
	ds_read2_b32 v[80:81], v242 offset1:1
	ds_read2_b32 v[82:83], v242 offset0:32 offset1:33
	ds_read2_b32 v[84:85], v242 offset0:34 offset1:35
	ds_read2_b32 v[86:87], v242 offset0:2 offset1:3
	ds_read2_b32 v[88:89], v242 offset0:8 offset1:9
	ds_read2_b32 v[90:91], v242 offset0:40 offset1:41
	ds_read2_b32 v[92:93], v242 offset0:42 offset1:43
	ds_read2_b32 v[94:95], v242 offset0:10 offset1:11
	ds_read2_b32 v[128:129], v242 offset0:16 offset1:17
	ds_read2_b32 v[246:247], v242 offset0:48 offset1:49
	ds_read2_b32 v[248:249], v242 offset0:50 offset1:51
	ds_read2_b32 v[130:131], v242 offset0:18 offset1:19
	s_waitcnt lgkmcnt(11)
	v_sub_f32_e32 v81, v81, v65
	v_sub_f32_e32 v80, v80, v64
	ds_read2_b32 v[132:133], v242 offset0:24 offset1:25
	ds_read2_b32 v[134:135], v242 offset0:26 offset1:27
	ds_read2_b32 v[250:251], v242 offset0:56 offset1:57
	s_waitcnt lgkmcnt(6)
	v_sub_f32_e32 v137, v129, v75
	v_sub_f32_e32 v136, v128, v72
	v_pk_fma_f32 v[128:129], v[112:113], s[6:7], v[80:81] op_sel_hi:[1,0,1]
	ds_read2_b32 v[80:81], v242 offset0:58 offset1:59
	v_sub_f32_e32 v89, v89, v69
	v_sub_f32_e32 v88, v88, v68
	v_sub_f32_e32 v95, v95, v71
	v_sub_f32_e32 v94, v94, v70
	v_sub_f32_e32 v87, v87, v67
	v_sub_f32_e32 v86, v86, v66
	s_waitcnt lgkmcnt(3)
	v_sub_f32_e32 v141, v133, v79
	v_sub_f32_e32 v140, v132, v78
	s_waitcnt lgkmcnt(2)
	v_sub_f32_e32 v143, v135, v77
	v_sub_f32_e32 v142, v134, v76
	v_sub_f32_e32 v139, v131, v73
	v_sub_f32_e32 v138, v130, v74
	v_pk_fma_f32 v[130:131], v[114:115], s[6:7], v[86:87] op_sel_hi:[1,0,1]
	v_pk_fma_f32 v[134:135], v[118:119], s[6:7], v[94:95] op_sel_hi:[1,0,1]
	v_pk_fma_f32 v[132:133], v[116:117], s[6:7], v[88:89] op_sel_hi:[1,0,1]
	s_waitcnt lgkmcnt(1)
	v_sub_f32_e32 v251, v251, v79
	v_sub_f32_e32 v250, v250, v78
	s_waitcnt lgkmcnt(0)
	v_sub_f32_e32 v95, v81, v77
	v_sub_f32_e32 v94, v80, v76
	v_sub_f32_e32 v89, v247, v75
	v_sub_f32_e32 v88, v246, v72
	v_sub_f32_e32 v247, v249, v73
	v_sub_f32_e32 v246, v248, v74
	v_sub_f32_e32 v91, v91, v69
	v_sub_f32_e32 v90, v90, v68
	v_sub_f32_e32 v87, v93, v71
	v_sub_f32_e32 v86, v92, v70
	v_sub_f32_e32 v81, v83, v65
	v_sub_f32_e32 v80, v82, v64
	v_sub_f32_e32 v83, v85, v67
	v_sub_f32_e32 v82, v84, v66
	v_pk_fma_f32 v[138:139], v[122:123], s[6:7], v[138:139] op_sel_hi:[1,0,1]
	v_pk_fma_f32 v[136:137], v[120:121], s[6:7], v[136:137] op_sel_hi:[1,0,1]
	v_pk_fma_f32 v[142:143], v[126:127], s[6:7], v[142:143] op_sel_hi:[1,0,1]
	v_pk_fma_f32 v[140:141], v[124:125], s[6:7], v[140:141] op_sel_hi:[1,0,1]
	v_pk_fma_f32 v[82:83], v[98:99], s[6:7], v[82:83] op_sel_hi:[1,0,1]
	v_pk_fma_f32 v[80:81], v[96:97], s[6:7], v[80:81] op_sel_hi:[1,0,1]
	v_pk_fma_f32 v[86:87], v[102:103], s[6:7], v[86:87] op_sel_hi:[1,0,1]
	v_pk_fma_f32 v[84:85], v[100:101], s[6:7], v[90:91] op_sel_hi:[1,0,1]
	v_pk_fma_f32 v[90:91], v[106:107], s[6:7], v[246:247] op_sel_hi:[1,0,1]
	v_pk_fma_f32 v[88:89], v[104:105], s[6:7], v[88:89] op_sel_hi:[1,0,1]
	v_pk_fma_f32 v[94:95], v[110:111], s[6:7], v[94:95] op_sel_hi:[1,0,1]
	v_pk_fma_f32 v[92:93], v[108:109], s[6:7], v[250:251] op_sel_hi:[1,0,1]
	s_mov_b64 s[0:1], 0

; #define SBAR() __builtin_amdgcn_sched_barrier(0)
; __device__ __forceinline__ void partialSM(f32x16& p0, f32x16& p1, float& m_reg, float& mn, float& alpha, int kt0, int qpos, int qw, int hi, const float* tb2, float cL, float cR) {
;     ...
; #pragma unroll
;   for (int r = 0; r < 16; ++r) p0[r] = __builtin_amdgcn_exp2f(p0[r]);
; template <int D0> __device__ __forceinline__ void pv_one(f32x16& od, int vb, bf16x8 pa0, bf16x8 pa1, bf16x8 pa2, bf16x8 pa3) {
;   const s16x4 l0 = tr_read<v_rd_off(D0, 0, 0)>(vb), h0 = tr_read<v_rd_off(D0, 0, 1)>(vb), l1 = tr_read<v_rd_off(D0, 1, 0)>(vb), h1 = tr_read<v_rd_off(D0, 1, 1)>(vb);
;   const s16x4 l2 = tr_read<v_rd_off(D0, 2, 0)>(vb), h2 = tr_read<v_rd_off(D0, 2, 1)>(vb), l3 = tr_read<v_rd_off(D0, 3, 0)>(vb), h3 = tr_read<v_rd_off(D0, 3, 1)>(vb);
;   asm volatile("s_waitcnt lgkmcnt(0)" ::: "memory"); SBAR();
;     ...
;   od = __builtin_amdgcn_mfma_f32_32x32x16_bf16(pa0, PK(l0, h0), od, 0, 0, 0);
;   od = __builtin_amdgcn_mfma_f32_32x32x16_bf16(pa1, PK(l1, h1), od, 0, 0, 0);
;   od = __builtin_amdgcn_mfma_f32_32x32x16_bf16(pa2, PK(l2, h2), od, 0, 0, 0);
;   od = __builtin_amdgcn_mfma_f32_32x32x16_bf16(pa3, PK(l3, h3), od, 0, 0, 0);
;     ...
; }
; __device__ __forceinline__ void pv_d0(f32x16* o, int vb, bf16x8 pa0, bf16x8 pa1, bf16x8 pa2, bf16x8 pa3) {
;   pv_one<0>(o[0], vb, pa0, pa1, pa2, pa3); pv_one<1>(o[1], vb, pa0, pa1, pa2, pa3); pv_one<2>(o[2], vb, pa0, pa1, pa2, pa3); pv_one<3>(o[3], vb, pa0, pa1, pa2, pa3);
.LBB0_330:
	v_exp_f32_e32 v112, v128
	v_exp_f32_e32 v113, v129
	v_exp_f32_e32 v114, v130
	v_exp_f32_e32 v115, v131
	v_exp_f32_e32 v116, v132
	v_exp_f32_e32 v117, v133
	v_exp_f32_e32 v118, v134
	v_exp_f32_e32 v119, v135
	v_exp_f32_e32 v120, v136
	v_exp_f32_e32 v121, v137
	v_exp_f32_e32 v122, v138
	v_exp_f32_e32 v123, v139
	v_exp_f32_e32 v124, v140
	v_exp_f32_e32 v125, v141
	v_exp_f32_e32 v126, v142
	v_exp_f32_e32 v127, v143
	s_lshl_b32 s0, s65, 14
	v_add_u32_e32 v128, s0, v219
	ds_read_b64_tr_b16 v[96:97], v128 offset:0
	ds_read_b64_tr_b16 v[98:99], v128 offset:0x800
	ds_read_b64_tr_b16 v[100:101], v128 offset:0x1000
	ds_read_b64_tr_b16 v[102:103], v128 offset:0x1800
	ds_read_b64_tr_b16 v[104:105], v128 offset:0x2000
	ds_read_b64_tr_b16 v[106:107], v128 offset:0x2800
	ds_read_b64_tr_b16 v[108:109], v128 offset:0x3000
	ds_read_b64_tr_b16 v[110:111], v128 offset:0x3800
	s_waitcnt lgkmcnt(0)
	s_nop 0
	v_mfma_f32_32x32x16_bf16 v[0:15], v[180:183], v[96:99], v[0:15]
	ds_read_b64_tr_b16 v[96:97], v128 offset:0x200
	ds_read_b64_tr_b16 v[98:99], v128 offset:0xa00
	v_mfma_f32_32x32x16_bf16 v[0:15], v[184:187], v[100:103], v[0:15]
	ds_read_b64_tr_b16 v[100:101], v128 offset:0x1200
	ds_read_b64_tr_b16 v[102:103], v128 offset:0x1a00
	v_mfma_f32_32x32x16_bf16 v[0:15], v[188:191], v[104:107], v[0:15]
	ds_read_b64_tr_b16 v[104:105], v128 offset:0x2200
	ds_read_b64_tr_b16 v[106:107], v128 offset:0x2a00
	v_mfma_f32_32x32x16_bf16 v[0:15], v[192:195], v[108:111], v[0:15]
	ds_read_b64_tr_b16 v[108:109], v128 offset:0x3200
	ds_read_b64_tr_b16 v[110:111], v128 offset:0x3a00
	s_waitcnt lgkmcnt(0)
	v_mfma_f32_32x32x16_bf16 v[16:31], v[180:183], v[96:99], v[16:31]
	ds_read_b64_tr_b16 v[96:97], v128 offset:0x400
	ds_read_b64_tr_b16 v[98:99], v128 offset:0xc00
	v_mfma_f32_32x32x16_bf16 v[16:31], v[184:187], v[100:103], v[16:31]
	ds_read_b64_tr_b16 v[100:101], v128 offset:0x1400
	ds_read_b64_tr_b16 v[102:103], v128 offset:0x1c00
	v_mfma_f32_32x32x16_bf16 v[16:31], v[188:191], v[104:107], v[16:31]
	ds_read_b64_tr_b16 v[104:105], v128 offset:0x2400
	ds_read_b64_tr_b16 v[106:107], v128 offset:0x2c00
	v_mfma_f32_32x32x16_bf16 v[16:31], v[192:195], v[108:111], v[16:31]
	ds_read_b64_tr_b16 v[108:109], v128 offset:0x3400
	ds_read_b64_tr_b16 v[110:111], v128 offset:0x3c00
	s_waitcnt lgkmcnt(0)
	v_mfma_f32_32x32x16_bf16 v[32:47], v[180:183], v[96:99], v[32:47]
	ds_read_b64_tr_b16 v[96:97], v128 offset:0x600
	ds_read_b64_tr_b16 v[98:99], v128 offset:0xe00
	v_mfma_f32_32x32x16_bf16 v[32:47], v[184:187], v[100:103], v[32:47]
	ds_read_b64_tr_b16 v[100:101], v128 offset:0x1600
	ds_read_b64_tr_b16 v[102:103], v128 offset:0x1e00
	v_mfma_f32_32x32x16_bf16 v[32:47], v[188:191], v[104:107], v[32:47]
	ds_read_b64_tr_b16 v[104:105], v128 offset:0x2600
	ds_read_b64_tr_b16 v[106:107], v128 offset:0x2e00
	v_mfma_f32_32x32x16_bf16 v[32:47], v[192:195], v[108:111], v[32:47]
	ds_read_b64_tr_b16 v[108:109], v128 offset:0x3600
	ds_read_b64_tr_b16 v[110:111], v128 offset:0x3e00
	s_waitcnt lgkmcnt(0)
	v_mfma_f32_32x32x16_bf16 v[48:63], v[180:183], v[96:99], v[48:63]
	s_add_i32 s0, s0, 0
	v_add_u32_e32 v96, s0, v221
	s_barrier
; #define SBAR() __builtin_amdgcn_sched_barrier(0)
; #define SLOAD(i, k0) do { sr_[i].vs0 = *(const GAS bf16x8*)(&Vh[(long)((k0) + sr) * LDK + sc]); sr_[i].vs1 = *(const GAS bf16x8*)(&Vh[(long)((k0) + 32 + sr) * LDK + sc]); \
;     sr_[i].ks0 = *(const GAS bf16x8*)(&Kh[(long)((k0) + kr) * LDK + kc]); } while (0)
; __device__ __forceinline__ void finishSM(f32x16& p0, f32x16& p1, float alpha, float& l_reg, bf16x8& pa0, bf16x8& pa1, bf16x8& pa2, bf16x8& pa3) {
; #pragma unroll
;   for (int r = 0; r < 16; ++r) p1[r] = __builtin_amdgcn_exp2f(p1[r]);
;   float ps = 0;
; #pragma unroll
;   for (int r = 0; r < 16; ++r) ps += p0[r];
; #pragma unroll
;   for (int r = 0; r < 16; ++r) ps += p1[r];
;   { auto rr = __builtin_amdgcn_permlane32_swap(__float_as_uint(ps), __float_as_uint(ps), false, false);
;     ps = __uint_as_float(rr[0]) + __uint_as_float(rr[1]); }
;   l_reg = l_reg * alpha + ps;
;     ...
;   PK4(p0, 0, pa0); PK4(p0, 8, pa1); PK4(p1, 0, pa2); PK4(p1, 8, pa3);
;     ...
; }
; __device__ __forceinline__ void qkt(f32x16& p0, f32x16& p1, const char* Ks, const bf16x8* qr, int r32, int hi) {
;   bf16x8 ka[4], kb[4];
; #pragma unroll
;   for (int d0 = 0; d0 < 4; ++d0) { const int cb = (d0 * 16 + hi * 8) * 2;
;     ka[d0] = *reinterpret_cast<const bf16x8*>(Ks + KSWZ64(r32, cb)); kb[d0] = *reinterpret_cast<const bf16x8*>(Ks + KSWZ64(32 + r32, cb)); }
;   asm volatile("s_waitcnt lgkmcnt(0)" ::: "memory"); SBAR();
;   p0 = f32x16{}; p1 = f32x16{};
; #pragma unroll
;   for (int d0 = 0; d0 < 4; ++d0) {
;     p0 = __builtin_amdgcn_mfma_f32_32x32x16_bf16(ka[d0], qr[d0], p0, 0, 0, 0);
;     p1 = __builtin_amdgcn_mfma_f32_32x32x16_bf16(kb[d0], qr[d0], p1, 0, 0, 0); }
; template <bool GRPB> __device__ __forceinline__ void attn_pass(const float mbK, const float bmax2, const int pass, float* __restrict__ scr, bf16* __restrict__ mixrow, const float lam, const float* __restrict__ gsub, const float one_m_li, ...
;     ...
;     HSTEP(pB0, pB1, mnB, alB, pA0, pA1, alA, t * KVBLK, SLOAD(0, (t + 2) * KVBLK));
;     __syncthreads(); SWRITE(bm1, 0);
;     RESC(alB);
;     { const int tmp = bm1; bm1 = b0; b0 = bp1; bp1 = tmp; }
;     HSTEP(pA0, pA1, mnA, alA, pB0, pB1, alB, (t + 1) * KVBLK, if (t + 3 < NT) SLOAD(0, (t + 3) * KVBLK));
;     __syncthreads(); if (t + 3 < NT) SWRITE(bm1, 0);
	s_waitcnt vmcnt(2)
	ds_write_b128 v96, v[168:171]
	v_add_u32_e32 v96, s0, v222
	v_mfma_f32_32x32x16_bf16 v[48:63], v[184:187], v[100:103], v[48:63]
	s_waitcnt vmcnt(1)
	ds_write_b128 v96, v[172:175]
	v_lshl_add_u32 v96, s65, 13, v224
	s_waitcnt vmcnt(0)
	ds_write_b128 v96, v[176:179] offset:49152
	v_mfma_f32_32x32x16_bf16 v[48:63], v[188:191], v[104:107], v[48:63]
	v_mfma_f32_32x32x16_bf16 v[48:63], v[192:195], v[108:111], v[48:63]
	v_add_f32_e32 v96, 0, v112
	v_add_f32_e32 v96, v113, v96
	v_add_f32_e32 v96, v114, v96
	v_add_f32_e32 v96, v115, v96
	v_add_f32_e32 v96, v116, v96
	v_add_f32_e32 v96, v117, v96
	v_add_f32_e32 v96, v118, v96
	v_add_f32_e32 v96, v119, v96
	v_add_f32_e32 v96, v120, v96
	v_add_f32_e32 v96, v121, v96
	v_add_f32_e32 v96, v122, v96
	v_add_f32_e32 v96, v123, v96
	v_exp_f32_e32 v80, v80
	v_add_f32_e32 v96, v124, v96
	v_exp_f32_e32 v81, v81
	v_add_f32_e32 v96, v125, v96
	v_exp_f32_e32 v82, v82
	v_add_f32_e32 v96, v126, v96
	v_exp_f32_e32 v83, v83
	v_add_f32_e32 v96, v127, v96
	v_exp_f32_e32 v84, v84
	v_add_f32_e32 v96, v80, v96
	v_exp_f32_e32 v85, v85
	v_add_f32_e32 v96, v81, v96
	v_exp_f32_e32 v86, v86
	v_add_f32_e32 v96, v82, v96
	v_exp_f32_e32 v87, v87
	v_add_f32_e32 v96, v83, v96
	v_exp_f32_e32 v88, v88
	v_add_f32_e32 v96, v84, v96
	v_exp_f32_e32 v89, v89
	v_add_f32_e32 v96, v85, v96
	v_exp_f32_e32 v90, v90
	v_add_f32_e32 v96, v86, v96
	v_exp_f32_e32 v91, v91
	v_add_f32_e32 v96, v87, v96
	v_exp_f32_e32 v92, v92
	v_add_f32_e32 v96, v88, v96
	v_exp_f32_e32 v93, v93
	v_add_f32_e32 v96, v89, v96
	v_exp_f32_e32 v94, v94
	v_add_f32_e32 v96, v90, v96
	v_exp_f32_e32 v95, v95
	v_add_f32_e32 v96, v91, v96
	v_add_f32_e32 v96, v92, v96
	v_add_f32_e32 v96, v93, v96
	v_add_f32_e32 v96, v94, v96
	v_add_f32_e32 v245, v95, v96
	v_mov_b32_e32 v246, v245
	v_cvt_pk_bf16_f32 v180, v112, v113
	v_cvt_pk_bf16_f32 v181, v114, v115
	v_cvt_pk_bf16_f32 v182, v116, v117
	v_cvt_pk_bf16_f32 v183, v118, v119
	v_cvt_pk_bf16_f32 v188, v120, v121
	v_cvt_pk_bf16_f32 v189, v122, v123
	v_cvt_pk_bf16_f32 v190, v124, v125
	v_cvt_pk_bf16_f32 v191, v126, v127
	v_cvt_pk_bf16_f32 v192, v80, v81
	v_cvt_pk_bf16_f32 v193, v82, v83
	v_cvt_pk_bf16_f32 v194, v84, v85
	v_cvt_pk_bf16_f32 v195, v86, v87
	v_cvt_pk_bf16_f32 v184, v88, v89
	v_cvt_pk_bf16_f32 v185, v90, v91
	v_cvt_pk_bf16_f32 v186, v92, v93
	v_cvt_pk_bf16_f32 v187, v94, v95
	s_nop 1
	v_permlane32_swap_b32_e32 v245, v246
	v_permlane32_swap_b32_e32 v180, v182
	v_permlane32_swap_b32_e32 v181, v183
	v_permlane32_swap_b32_e32 v188, v190
	v_permlane32_swap_b32_e32 v189, v191
	v_permlane32_swap_b32_e32 v192, v194
	v_permlane32_swap_b32_e32 v193, v195
	v_permlane32_swap_b32_e32 v184, v186
	v_permlane32_swap_b32_e32 v185, v187
	s_lshl_b32 s0, s67, 13
	s_add_i32 s0, s0, 0
	v_add_u32_e32 v84, s0, v226
	v_add_u32_e32 v92, s0, v229
	v_add_u32_e32 v100, s0, v231
	v_add_u32_e32 v108, s0, v240
	ds_read_b128 v[80:83], v84 offset:49152
	ds_read_b128 v[84:87], v84 offset:53248
	ds_read_b128 v[88:91], v92 offset:49152
	ds_read_b128 v[92:95], v92 offset:53248
	ds_read_b128 v[96:99], v100 offset:49152
	ds_read_b128 v[100:103], v100 offset:53248
	ds_read_b128 v[104:107], v108 offset:49152
	ds_read_b128 v[108:111], v108 offset:53248
	s_waitcnt lgkmcnt(7)
	v_mfma_f32_32x32x16_bf16 v[128:143], v[80:83], v[164:167], 0
	s_waitcnt lgkmcnt(6)
	v_mfma_f32_32x32x16_bf16 v[112:127], v[84:87], v[164:167], 0
	s_waitcnt lgkmcnt(5)
	v_mfma_f32_32x32x16_bf16 v[128:143], v[88:91], v[160:163], v[128:143]
	s_waitcnt lgkmcnt(4)
	v_mfma_f32_32x32x16_bf16 v[112:127], v[92:95], v[160:163], v[112:127]
	s_waitcnt lgkmcnt(3)
	v_mfma_f32_32x32x16_bf16 v[128:143], v[96:99], v[152:155], v[128:143]
	s_waitcnt lgkmcnt(2)
	v_mfma_f32_32x32x16_bf16 v[112:127], v[100:103], v[152:155], v[112:127]
	s_waitcnt lgkmcnt(1)
	v_mfma_f32_32x32x16_bf16 v[128:143], v[104:107], v[156:159], v[128:143]
	s_waitcnt lgkmcnt(0)
	v_mfma_f32_32x32x16_bf16 v[112:127], v[108:111], v[156:159], v[112:127]
	s_cmp_lt_u32 s60, 61
	s_cselect_b64 s[0:1], -1, 0
	s_cmp_gt_u32 s60, 60
	s_cbranch_scc1 .LBB0_332
	s_add_u32 s74, s70, 0x18e00000
	s_addc_u32 s75, s71, 0
	global_load_dwordx4 v[168:171], v202, s[74:75] offset:2048
	s_add_u32 s74, s70, 0x18e40000
	s_addc_u32 s75, s71, 0
	global_load_dwordx4 v[172:175], v202, s[74:75] offset:2048
	s_add_u32 s74, s72, 0x18e00000
	s_addc_u32 s75, s73, 0
	global_load_dwordx4 v[176:179], v204, s[74:75] offset:1152

; #define GAS __attribute__((address_space(1)))
; __device__ __forceinline__ float bf2f(unsigned short b) { return __uint_as_float(((unsigned)b) << 16); }
; __device__ __forceinline__ int v_st(int k, int c) { const int kk = (k & ~0xC) | ((k & 4) << 1) | ((k & 8) >> 1); return ((kk >> 3) * 4 + (c >> 5)) * 512 + ((kk & 7) * 32 + (c & 31)) * 2; }
; __device__ __forceinline__ int v_rd_base(int lane) { return ((lane & 3) << 3) | (((lane >> 2) & 3) << 6) | (((lane >> 4) & 1) << 5) | (((lane >> 5) & 1) << 8); }
; template <bool GRPB> __device__ __forceinline__ void attn_pass(const float mbK, const float bmax2, const int pass, float* __restrict__ scr, bf16* __restrict__ mixrow, const float lam, const float* __restrict__ gsub, const float one_m_li, ...
;     ...
;   const float cL = __uint_as_float(__builtin_amdgcn_readfirstlane(__float_as_uint(tb2[0]))), cR = __uint_as_float(__builtin_amdgcn_readfirstlane(__float_as_uint(tb2[384])));
;   const int qw = __builtin_amdgcn_readfirstlane(q0seq + wid * 32), qpos = qw + r32;
;   float m_reg, l_reg = 0; bf16x8 qr[4]; f32x16 o[4];
; #pragma unroll
;   for (int d = 0; d < 4; ++d) o[d] = f32x16{};
;   const bf16* Qw = Qb + (long)(wid * 32 + r32) * LDK + hi * 8;
; #pragma unroll
;   for (int d0 = 0; d0 < 4; ++d0) qr[d0] = *(const GAS bf16x8*)(Qw + d0 * 16);
;   { float qs = 0.f;
; #pragma unroll
;     for (int d0 = 0; d0 < 4; ++d0)
; #pragma unroll
;       for (int j = 0; j < 8; ++j) { const float v = bf2f((unsigned short)qr[d0][j]); qs = fmaf(v, v, qs); }
;     { auto rr = __builtin_amdgcn_permlane32_swap(__float_as_uint(qs), __float_as_uint(qs), false, false); qs = __uint_as_float(rr[0]) + __uint_as_float(rr[1]); }
;     m_reg = __builtin_sqrtf(qs) * mbK + bmax2 + 0.25f; }
;   const int sr = tid >> 4, sc = (tid & 15) * 8, vst0 = v_st(sr, sc), vst1 = v_st(32 + sr, sc);
;   const int kr = tid >> 3, kc = (tid & 7) * 8, kst = KSWZ64(kr, kc * 2);
;   const int vb0 = (int)(uintptr_t)V_lds + v_rd_base(lane);
;   struct { bf16x8 vs0, vs1, ks0; } sr_[2];
;     ...
;   f32x16 pA0, pA1, pB0, pB1; float mnA, mnB, alA, alB; bf16x8 pa0, pa1, pa2, pa3; constexpr int NT = SEQ / KVBLK;
;   __syncthreads();
;   SLOAD(0, 0); SLOAD(1, KVBLK); asm volatile("s_waitcnt vmcnt(0)" ::: "memory"); SWRITE(0, 0); SWRITE(1, 1);
;   SLOAD(0, 2 * KVBLK); asm volatile("s_waitcnt vmcnt(0)" ::: "memory"); SWRITE(2, 0); __syncthreads();
.LBB0_347:
	s_and_b64 vcc, exec, s[0:1]
	s_cbranch_vccz .LBB0_249
	v_readlane_b32 s0, v254, 39
	v_mov_b32_e32 v146, v232
	v_mov_b32_e32 v181, v144
	v_mov_b32_e32 v0, s0
	ds_read_b32 v0, v0
	v_readlane_b32 s0, v254, 40
	v_lshrrev_b32_e32 v2, 1, v146
	v_and_b32_e32 v180, 16, v2
	v_lshlrev_b32_e32 v8, 4, v146
	s_waitcnt lgkmcnt(0)
	v_readfirstlane_b32 s54, v0
	v_mov_b32_e32 v0, s0
	ds_read_b32 v0, v0
	s_movk_i32 s0, 0xffe0
	v_and_b32_e32 v9, 48, v8
	v_ashrrev_i32_e32 v12, 3, v146
	v_ashrrev_i32_e32 v13, 31, v12
	s_waitcnt lgkmcnt(0)
	v_readfirstlane_b32 s55, v0
	v_ashrrev_i32_e32 v0, 1, v146
	v_and_b32_e32 v1, 0xffffffe0, v0
	v_add_u32_e32 v1, s39, v1
	v_bfi_b32 v0, s0, v0, v146
	v_readfirstlane_b32 s60, v1
	v_ashrrev_i32_e32 v1, 31, v0
	v_lshlrev_b64 v[0:1], 13, v[0:1]
	v_lshl_add_u64 v[0:1], s[52:53], 0, v[0:1]
	v_lshl_add_u64 v[0:1], v[0:1], 0, v[180:181]
	global_load_dwordx4 v[164:167], v[0:1], off
	global_load_dwordx4 v[160:163], v[0:1], off offset:32
	global_load_dwordx4 v[156:159], v[0:1], off offset:64
	global_load_dwordx4 v[152:155], v[0:1], off offset:96
	s_barrier
	v_lshlrev_b64 v[52:53], 13, v[12:13]
	v_mov_b32_e32 v11, v144
	v_and_b32_e32 v147, 31, v146
	v_add_u32_e32 v190, s60, v147
	s_waitcnt vmcnt(3)
	v_lshlrev_b32_e32 v0, 16, v164
	v_fma_f32 v0, v0, v0, 0
	v_and_b32_e32 v1, 0xffff0000, v164
	v_fmac_f32_e32 v0, v1, v1
	v_lshlrev_b32_e32 v1, 16, v165
	v_fmac_f32_e32 v0, v1, v1
	v_and_b32_e32 v1, 0xffff0000, v165
	v_fmac_f32_e32 v0, v1, v1
	v_lshlrev_b32_e32 v1, 16, v166
	v_fmac_f32_e32 v0, v1, v1
	v_and_b32_e32 v1, 0xffff0000, v166
	v_fmac_f32_e32 v0, v1, v1
	v_lshlrev_b32_e32 v1, 16, v167
	v_fmac_f32_e32 v0, v1, v1
	v_and_b32_e32 v1, 0xffff0000, v167
	v_fmac_f32_e32 v0, v1, v1
	s_waitcnt vmcnt(2)
	v_lshlrev_b32_e32 v1, 16, v160
	v_fmac_f32_e32 v0, v1, v1
	v_and_b32_e32 v1, 0xffff0000, v160
	v_fmac_f32_e32 v0, v1, v1
	v_lshlrev_b32_e32 v1, 16, v161
	v_fmac_f32_e32 v0, v1, v1
	v_and_b32_e32 v1, 0xffff0000, v161
	v_fmac_f32_e32 v0, v1, v1
	v_lshlrev_b32_e32 v1, 16, v162
	v_fmac_f32_e32 v0, v1, v1
	v_and_b32_e32 v1, 0xffff0000, v162
	v_fmac_f32_e32 v0, v1, v1
	v_lshlrev_b32_e32 v1, 16, v163
	v_fmac_f32_e32 v0, v1, v1
	v_and_b32_e32 v1, 0xffff0000, v163
	v_fmac_f32_e32 v0, v1, v1
	s_waitcnt vmcnt(1)
	v_lshlrev_b32_e32 v1, 16, v156
	v_fmac_f32_e32 v0, v1, v1
	v_and_b32_e32 v1, 0xffff0000, v156
	v_fmac_f32_e32 v0, v1, v1
	v_lshlrev_b32_e32 v1, 16, v157
	v_fmac_f32_e32 v0, v1, v1
	v_and_b32_e32 v1, 0xffff0000, v157
	v_fmac_f32_e32 v0, v1, v1
	v_lshlrev_b32_e32 v1, 16, v158
	v_fmac_f32_e32 v0, v1, v1
	v_and_b32_e32 v1, 0xffff0000, v158
	v_fmac_f32_e32 v0, v1, v1
	v_lshlrev_b32_e32 v1, 16, v159
	v_fmac_f32_e32 v0, v1, v1
	v_and_b32_e32 v1, 0xffff0000, v159
	v_fmac_f32_e32 v0, v1, v1
	s_waitcnt vmcnt(0)
	v_lshlrev_b32_e32 v1, 16, v152
	v_fmac_f32_e32 v0, v1, v1
	v_and_b32_e32 v1, 0xffff0000, v152
	v_fmac_f32_e32 v0, v1, v1
	v_lshlrev_b32_e32 v1, 16, v153
	v_fmac_f32_e32 v0, v1, v1
	v_and_b32_e32 v1, 0xffff0000, v153
	v_fmac_f32_e32 v0, v1, v1
	v_lshlrev_b32_e32 v1, 16, v154
	v_fmac_f32_e32 v0, v1, v1
	v_and_b32_e32 v1, 0xffff0000, v154
	v_fmac_f32_e32 v0, v1, v1
	v_lshlrev_b32_e32 v1, 16, v155
	v_fmac_f32_e32 v0, v1, v1
	v_and_b32_e32 v1, 0xffff0000, v155
	v_fmac_f32_e32 v0, v1, v1
	v_mov_b32_e32 v1, v0
	s_nop 1
	v_permlane32_swap_b32_e32 v0, v1
	v_add_f32_e32 v0, v0, v1
	v_cmp_gt_f32_e32 vcc, s10, v0
	v_mul_f32_e32 v1, 0x4f800000, v0
	s_nop 0
	v_cndmask_b32_e32 v0, v0, v1, vcc
	v_sqrt_f32_e32 v1, v0
	s_nop 0
	v_add_u32_e32 v2, -1, v1
	v_fma_f32 v3, -v2, v1, v0
	v_cmp_ge_f32_e64 s[0:1], 0, v3
	v_add_u32_e32 v3, 1, v1
	s_nop 0
	v_cndmask_b32_e64 v2, v1, v2, s[0:1]
	v_fma_f32 v1, -v3, v1, v0
	v_cmp_lt_f32_e64 s[0:1], 0, v1
	s_nop 1
	v_cndmask_b32_e64 v1, v2, v3, s[0:1]
	v_mul_f32_e32 v2, 0x37800000, v1
	v_cndmask_b32_e32 v1, v1, v2, vcc
	v_ashrrev_i32_e32 v2, 4, v146
	v_cmp_class_f32_e32 vcc, v0, v198
	v_and_b32_e32 v3, 0xfffff0, v2
	v_lshlrev_b32_e32 v5, 1, v2
	v_cndmask_b32_e32 v0, v1, v0, vcc
	v_lshlrev_b32_e32 v1, 3, v146
	v_and_or_b32 v3, v5, 8, v3
	v_lshrrev_b32_e32 v5, 1, v2
	v_lshrrev_b32_e32 v3, 1, v3
	v_bfe_u32 v7, v1, 5, 2
	v_and_b32_e32 v6, 3, v2
	v_or_b32_e32 v3, v3, v7
	v_and_or_b32 v5, v5, 4, v6
	v_lshlrev_b32_e32 v3, 9, v3
	v_lshlrev_b32_e32 v5, 6, v5
	v_add_u32_e32 v6, 32, v2
	v_or3_b32 v181, v3, v5, v9
	v_and_b32_e32 v3, 0xfffff0, v6
	v_lshlrev_b32_e32 v10, 1, v6
	v_and_or_b32 v3, v10, 8, v3
	v_lshrrev_b32_e32 v3, 1, v3
	v_or_b32_e32 v3, v3, v7
	v_lshlrev_b32_e32 v3, 9, v3
	v_or3_b32 v191, v3, v5, v9
	v_lshlrev_b32_e32 v3, 7, v12
	v_and_b32_e32 v10, 0x70, v8
	v_and_b32_e32 v5, 0x70, v146
	v_bitop3_b32 v192, v10, v3, v5 bitop3:0xde
	v_ashrrev_i32_e32 v3, 31, v2
	v_and_b32_e32 v4, 0x78, v1
	v_lshlrev_b64 v[50:51], 13, v[2:3]
	v_lshl_add_u64 v[2:3], s[50:51], 0, v[50:51]
	v_lshlrev_b32_e32 v8, 1, v4
	v_mov_b32_e32 v9, v144
	v_ashrrev_i32_e32 v7, 31, v6
	v_lshl_add_u64 v[18:19], v[2:3], 0, v[8:9]
	v_lshlrev_b64 v[6:7], 13, v[6:7]
	global_load_dwordx4 v[2:5], v[18:19], off offset:2048
	v_lshl_add_u64 v[6:7], s[50:51], 0, v[6:7]
	s_mov_b32 s0, 0x80000
	v_lshl_add_u64 v[6:7], v[6:7], 0, v[8:9]
	v_add_co_u32_e32 v14, vcc, s0, v18
	global_load_dwordx4 v[6:9], v[6:7], off offset:2048
	v_lshl_add_u64 v[12:13], s[50:51], 0, v[52:53]
	v_addc_co_u32_e32 v15, vcc, 0, v19, vcc
	s_mov_b32 s1, 0xc0000
	v_lshl_add_u64 v[20:21], v[12:13], 0, v[10:11]
	v_add_co_u32_e32 v22, vcc, s1, v18
	global_load_dwordx4 v[10:13], v[20:21], off offset:1024
	s_nop 0
	v_addc_co_u32_e32 v23, vcc, 0, v19, vcc
	global_load_dwordx4 v[14:17], v[14:15], off offset:2048
	v_add_co_u32_e32 v26, vcc, s0, v20
	global_load_dwordx4 v[22:25], v[22:23], off offset:2048
	s_nop 0
	v_addc_co_u32_e32 v27, vcc, 0, v21, vcc
	global_load_dwordx4 v[26:29], v[26:27], off offset:1024
	v_add_u32_e32 v30, 0, v181
	s_mov_b32 s0, 0x100000
	s_waitcnt vmcnt(3)
; #define SBAR() __builtin_amdgcn_sched_barrier(0)
; __device__ __forceinline__ void partialSM(f32x16& p0, f32x16& p1, float& m_reg, float& mn, float& alpha, int kt0, int qpos, int qw, int hi, const float* tb2, float cL, float cR) {
;   mn = m_reg; alpha = 1.f;
;   const int rel_hi = kt0 + 63 - qw, rel_lo = kt0 - (qw + 31);
;   if (rel_hi <= -91 || rel_lo >= 91) {
;     const float cm = ((rel_hi <= -91) ? cL : cR) - m_reg;
; #pragma unroll
;     for (int r = 0; r < 16; ++r) { p0[r] = fmaf(p0[r], C1, cm); p1[r] = fmaf(p1[r], C1, cm); }
;   } else {
;     const float* tp = tb2 + (kt0 - qpos + 192 + 4 * hi);
; #pragma unroll
;     for (int r4 = 0; r4 < 4; ++r4) {
;       float ta[4], tb[4];
; #pragma unroll
;       for (int i = 0; i < 4; ++i) { ta[i] = tp[8 * r4 + i] - m_reg; tb[i] = tp[32 + 8 * r4 + i] - m_reg; }
; #pragma unroll
;       for (int i = 0; i < 4; ++i) { p0[4 * r4 + i] = fmaf(p0[4 * r4 + i], C1, ta[i]); p1[4 * r4 + i] = fmaf(p1[4 * r4 + i], C1, tb[i]); }
; __device__ __forceinline__ void qkt(f32x16& p0, f32x16& p1, const char* Ks, const bf16x8* qr, int r32, int hi) {
;   bf16x8 ka[4], kb[4];
; #pragma unroll
;   for (int d0 = 0; d0 < 4; ++d0) { const int cb = (d0 * 16 + hi * 8) * 2;
;     ka[d0] = *reinterpret_cast<const bf16x8*>(Ks + KSWZ64(r32, cb)); kb[d0] = *reinterpret_cast<const bf16x8*>(Ks + KSWZ64(32 + r32, cb)); }
;   asm volatile("s_waitcnt lgkmcnt(0)" ::: "memory"); SBAR();
;   p0 = f32x16{}; p1 = f32x16{};
; #pragma unroll
;   for (int d0 = 0; d0 < 4; ++d0) {
;     p0 = __builtin_amdgcn_mfma_f32_32x32x16_bf16(ka[d0], qr[d0], p0, 0, 0, 0);
;     p1 = __builtin_amdgcn_mfma_f32_32x32x16_bf16(kb[d0], qr[d0], p1, 0, 0, 0); }
	v_add_u32_e32 v31, 0, v191
	s_mov_b32 s1, 0x140000
	v_add_u32_e32 v200, 0, v192
	v_and_b32_e32 v1, 0x70, v1
	v_fma_f32 v0, v216, v0, s45
	v_add_f32_e32 v0, 0x3e800000, v0
	s_waitcnt vmcnt(5)
	ds_write_b128 v30, v[2:5]
	v_add_co_u32_e32 v2, vcc, s0, v18
	s_waitcnt vmcnt(4)
	ds_write_b128 v31, v[6:9]
	v_addc_co_u32_e32 v3, vcc, 0, v19, vcc
	v_add_co_u32_e32 v6, vcc, s1, v18
	s_waitcnt vmcnt(3)
	ds_write_b128 v200, v[10:13] offset:49152
	v_addc_co_u32_e32 v7, vcc, 0, v19, vcc
	v_add_co_u32_e32 v10, vcc, s0, v20
	global_load_dwordx4 v[2:5], v[2:3], off offset:2048
	s_nop 0
	v_addc_co_u32_e32 v11, vcc, 0, v21, vcc
	global_load_dwordx4 v[6:9], v[6:7], off offset:2048
	s_nop 0
	global_load_dwordx4 v[10:13], v[10:11], off offset:1024
	s_waitcnt vmcnt(5)
	ds_write_b128 v30, v[14:17] offset:16384
	s_waitcnt vmcnt(4)
	ds_write_b128 v31, v[22:25] offset:16384
	s_waitcnt vmcnt(3)
	ds_write_b128 v200, v[26:29] offset:57344
	s_waitcnt vmcnt(0)
	s_waitcnt vmcnt(2)
	ds_write_b128 v30, v[2:5] offset:32768
	s_waitcnt vmcnt(1)
	ds_write_b128 v31, v[6:9] offset:32768
	v_add_u32_e32 v2, 0x10000, v200
	s_waitcnt vmcnt(0)
	ds_write_b128 v2, v[10:13]
	v_lshlrev_b32_e32 v10, 7, v147
	v_or_b32_e32 v11, 32, v180
	v_bitop3_b32 v205, v11, v10, v1 bitop3:0xde
	v_or_b32_e32 v11, 64, v180
	v_bitop3_b32 v207, v11, v10, v1 bitop3:0xde
	v_or_b32_e32 v11, 0x60, v180
	v_bitop3_b32 v202, v180, v10, v1 bitop3:0xde
	v_bitop3_b32 v208, v11, v10, v1 bitop3:0xde
	v_add_u32_e32 v201, 0, v202
	v_add_u32_e32 v203, 0, v205
	v_add_u32_e32 v204, 0, v207
	v_add_u32_e32 v206, 0, v208
	s_waitcnt lgkmcnt(0)
	s_barrier
	ds_read_b128 v[2:5], v201 offset:49152
	ds_read_b128 v[6:9], v201 offset:53248
	ds_read_b128 v[34:37], v203 offset:49152
	ds_read_b128 v[38:41], v203 offset:53248
	ds_read_b128 v[42:45], v204 offset:49152
	ds_read_b128 v[46:49], v204 offset:53248
	ds_read_b128 v[54:57], v206 offset:49152
	ds_read_b128 v[58:61], v206 offset:53248
	s_waitcnt lgkmcnt(7)
	v_mfma_f32_32x32x16_bf16 v[18:33], v[2:5], v[164:167], 0
	s_add_i32 s2, s60, 0xffffff66
	s_mov_b64 s[0:1], -1
	s_cmp_gt_u32 s2, 0xfffffeec
	s_waitcnt lgkmcnt(6)
	v_mfma_f32_32x32x16_bf16 v[2:17], v[6:9], v[164:167], 0
	s_waitcnt lgkmcnt(5)
	v_mfma_f32_32x32x16_bf16 v[18:33], v[34:37], v[160:163], v[18:33]
	s_waitcnt lgkmcnt(4)
	v_mfma_f32_32x32x16_bf16 v[2:17], v[38:41], v[160:163], v[2:17]
	s_waitcnt lgkmcnt(3)
	v_mfma_f32_32x32x16_bf16 v[18:33], v[42:45], v[156:159], v[18:33]
	s_waitcnt lgkmcnt(2)
	v_mfma_f32_32x32x16_bf16 v[2:17], v[46:49], v[156:159], v[2:17]
	s_waitcnt lgkmcnt(1)
	v_mfma_f32_32x32x16_bf16 v[18:33], v[54:57], v[152:155], v[18:33]
	v_lshlrev_b32_e32 v54, 2, v190
	s_waitcnt lgkmcnt(0)
	v_mfma_f32_32x32x16_bf16 v[2:17], v[58:61], v[152:155], v[2:17]
	s_cbranch_scc0 .LBB0_350
	v_sub_u32_e32 v1, 0, v54
	s_mov_b32 s0, 0x12b00
	v_add3_u32 v1, v1, v180, s0
	ds_read2_b32 v[34:35], v1 offset1:1
	ds_read2_b32 v[56:57], v1 offset0:32 offset1:33
	ds_read2_b32 v[58:59], v1 offset0:34 offset1:35
	ds_read2_b32 v[36:37], v1 offset0:2 offset1:3
	ds_read2_b32 v[38:39], v1 offset0:8 offset1:9
	ds_read2_b32 v[60:61], v1 offset0:40 offset1:41
	ds_read2_b32 v[62:63], v1 offset0:42 offset1:43
	ds_read2_b32 v[40:41], v1 offset0:10 offset1:11
	ds_read2_b32 v[42:43], v1 offset0:16 offset1:17
	ds_read2_b32 v[64:65], v1 offset0:48 offset1:49
	ds_read2_b32 v[66:67], v1 offset0:50 offset1:51
	ds_read2_b32 v[44:45], v1 offset0:18 offset1:19
	ds_read2_b32 v[46:47], v1 offset0:24 offset1:25
	ds_read2_b32 v[48:49], v1 offset0:26 offset1:27
	ds_read2_b32 v[68:69], v1 offset0:58 offset1:59
	ds_read2_b32 v[70:71], v1 offset0:56 offset1:57
	s_waitcnt lgkmcnt(3)
	v_sub_f32_e32 v47, v47, v0
	v_sub_f32_e32 v46, v46, v0
	s_waitcnt lgkmcnt(2)
	v_sub_f32_e32 v49, v49, v0
	v_sub_f32_e32 v48, v48, v0
	v_sub_f32_e32 v43, v43, v0
	v_sub_f32_e32 v42, v42, v0
	v_sub_f32_e32 v45, v45, v0
	v_sub_f32_e32 v44, v44, v0
	v_sub_f32_e32 v39, v39, v0
	v_sub_f32_e32 v38, v38, v0
	v_sub_f32_e32 v41, v41, v0
	v_sub_f32_e32 v40, v40, v0
	v_sub_f32_e32 v35, v35, v0
	v_sub_f32_e32 v34, v34, v0
	v_sub_f32_e32 v37, v37, v0
	v_sub_f32_e32 v36, v36, v0
	s_waitcnt lgkmcnt(0)
	v_sub_f32_e32 v71, v71, v0
	v_sub_f32_e32 v70, v70, v0
	v_sub_f32_e32 v69, v69, v0
	v_sub_f32_e32 v68, v68, v0
	v_sub_f32_e32 v65, v65, v0
	v_sub_f32_e32 v64, v64, v0
	v_sub_f32_e32 v67, v67, v0
	v_sub_f32_e32 v66, v66, v0
	v_sub_f32_e32 v61, v61, v0
	v_sub_f32_e32 v60, v60, v0
	v_sub_f32_e32 v63, v63, v0
	v_sub_f32_e32 v62, v62, v0
	v_sub_f32_e32 v57, v57, v0
	v_sub_f32_e32 v56, v56, v0
	v_sub_f32_e32 v59, v59, v0
	v_sub_f32_e32 v58, v58, v0
	v_pk_fma_f32 v[36:37], v[20:21], s[6:7], v[36:37] op_sel_hi:[1,0,1]
	v_pk_fma_f32 v[34:35], v[18:19], s[6:7], v[34:35] op_sel_hi:[1,0,1]
	v_pk_fma_f32 v[40:41], v[24:25], s[6:7], v[40:41] op_sel_hi:[1,0,1]
	v_pk_fma_f32 v[38:39], v[22:23], s[6:7], v[38:39] op_sel_hi:[1,0,1]
	v_pk_fma_f32 v[44:45], v[28:29], s[6:7], v[44:45] op_sel_hi:[1,0,1]
	v_pk_fma_f32 v[42:43], v[26:27], s[6:7], v[42:43] op_sel_hi:[1,0,1]
	v_pk_fma_f32 v[48:49], v[32:33], s[6:7], v[48:49] op_sel_hi:[1,0,1]
	v_pk_fma_f32 v[46:47], v[30:31], s[6:7], v[46:47] op_sel_hi:[1,0,1]
	v_pk_fma_f32 v[82:83], v[4:5], s[6:7], v[58:59] op_sel_hi:[1,0,1]
	v_pk_fma_f32 v[80:81], v[2:3], s[6:7], v[56:57] op_sel_hi:[1,0,1]
	v_pk_fma_f32 v[86:87], v[8:9], s[6:7], v[62:63] op_sel_hi:[1,0,1]
	v_pk_fma_f32 v[84:85], v[6:7], s[6:7], v[60:61] op_sel_hi:[1,0,1]
	v_pk_fma_f32 v[90:91], v[12:13], s[6:7], v[66:67] op_sel_hi:[1,0,1]
	v_pk_fma_f32 v[88:89], v[10:11], s[6:7], v[64:65] op_sel_hi:[1,0,1]
	v_pk_fma_f32 v[94:95], v[16:17], s[6:7], v[68:69] op_sel_hi:[1,0,1]
	v_pk_fma_f32 v[92:93], v[14:15], s[6:7], v[70:71] op_sel_hi:[1,0,1]
	s_mov_b64 s[0:1], 0

; #define SBAR() __builtin_amdgcn_sched_barrier(0)
; __device__ __forceinline__ void partialSM(f32x16& p0, f32x16& p1, float& m_reg, float& mn, float& alpha, int kt0, int qpos, int qw, int hi, const float* tb2, float cL, float cR) {
;     ...
; #pragma unroll
;   for (int r = 0; r < 16; ++r) p0[r] = __builtin_amdgcn_exp2f(p0[r]);
; }
; __device__ __forceinline__ void finishSM(f32x16& p0, f32x16& p1, float alpha, float& l_reg, bf16x8& pa0, bf16x8& pa1, bf16x8& pa2, bf16x8& pa3) {
; #pragma unroll
;   for (int r = 0; r < 16; ++r) p1[r] = __builtin_amdgcn_exp2f(p1[r]);
;   float ps = 0;
; #pragma unroll
;   for (int r = 0; r < 16; ++r) ps += p0[r];
; #pragma unroll
;   for (int r = 0; r < 16; ++r) ps += p1[r];
;   { auto rr = __builtin_amdgcn_permlane32_swap(__float_as_uint(ps), __float_as_uint(ps), false, false);
;     ps = __uint_as_float(rr[0]) + __uint_as_float(rr[1]); }
;   l_reg = l_reg * alpha + ps;
;     ...
;   PK4(p0, 0, pa0); PK4(p0, 8, pa1); PK4(p1, 0, pa2); PK4(p1, 8, pa3);
;     ...
; }
; __device__ __forceinline__ void qkt(f32x16& p0, f32x16& p1, const char* Ks, const bf16x8* qr, int r32, int hi) {
;   bf16x8 ka[4], kb[4];
; #pragma unroll
;   for (int d0 = 0; d0 < 4; ++d0) { const int cb = (d0 * 16 + hi * 8) * 2;
;     ka[d0] = *reinterpret_cast<const bf16x8*>(Ks + KSWZ64(r32, cb)); kb[d0] = *reinterpret_cast<const bf16x8*>(Ks + KSWZ64(32 + r32, cb)); }
;   asm volatile("s_waitcnt lgkmcnt(0)" ::: "memory"); SBAR();
;   p0 = f32x16{}; p1 = f32x16{};
; #pragma unroll
;   for (int d0 = 0; d0 < 4; ++d0) {
;     p0 = __builtin_amdgcn_mfma_f32_32x32x16_bf16(ka[d0], qr[d0], p0, 0, 0, 0);
;     p1 = __builtin_amdgcn_mfma_f32_32x32x16_bf16(kb[d0], qr[d0], p1, 0, 0, 0); }
.LBB0_357:
	s_add_i32 s0, s4, 0
	v_exp_f32_e32 v230, v80
	v_add_u32_e32 v80, s0, v181
	s_barrier
	s_waitcnt vmcnt(2)
	ds_write_b128 v80, v[168:171]
	v_add_u32_e32 v80, s0, v191
	s_waitcnt vmcnt(1)
	ds_write_b128 v80, v[172:175]
	v_lshl_add_u32 v80, s61, 13, v200
	v_exp_f32_e32 v231, v81
	v_exp_f32_e32 v244, v82
	v_exp_f32_e32 v245, v83
	v_exp_f32_e32 v246, v84
	v_exp_f32_e32 v247, v85
	v_exp_f32_e32 v248, v86
	v_exp_f32_e32 v249, v87
	v_exp_f32_e32 v250, v88
	v_exp_f32_e32 v251, v89
	v_exp_f32_e32 v235, v90
	v_exp_f32_e32 v237, v91
	v_exp_f32_e32 v238, v92
	v_exp_f32_e32 v234, v93
	v_exp_f32_e32 v196, v94
	v_exp_f32_e32 v197, v95
	s_waitcnt vmcnt(0)
	ds_write_b128 v80, v[176:179] offset:49152
	s_lshl_b32 s0, s63, 13
	s_add_i32 s0, s0, 0
	v_add_u32_e32 v84, s0, v202
	v_add_u32_e32 v92, s0, v205
	v_add_u32_e32 v96, s0, v207
	ds_read_b128 v[80:83], v84 offset:49152
	ds_read_b128 v[84:87], v84 offset:53248
	ds_read_b128 v[88:91], v92 offset:49152
	ds_read_b128 v[92:95], v92 offset:53248
	ds_read_b128 v[218:221], v96 offset:49152
	ds_read_b128 v[222:225], v96 offset:53248
	v_add_u32_e32 v96, s0, v208
	ds_read_b128 v[226:229], v96 offset:49152
	ds_read_b128 v[240:243], v96 offset:53248
	s_waitcnt lgkmcnt(7)
	v_mfma_f32_32x32x16_bf16 v[112:127], v[80:83], v[164:167], 0
	v_add_f32_e32 v80, 0, v230
	v_add_f32_e32 v80, v231, v80
	v_add_f32_e32 v80, v244, v80
	v_add_f32_e32 v80, v245, v80
	v_add_f32_e32 v80, v246, v80
	v_add_f32_e32 v80, v247, v80
	v_add_f32_e32 v80, v248, v80
	s_waitcnt lgkmcnt(6)
	v_mfma_f32_32x32x16_bf16 v[96:111], v[84:87], v[164:167], 0
	v_add_f32_e32 v80, v249, v80
	v_add_f32_e32 v80, v250, v80
	v_add_f32_e32 v80, v251, v80
	v_add_f32_e32 v80, v235, v80
	v_add_f32_e32 v80, v237, v80
	v_exp_f32_e32 v128, v128
	v_add_f32_e32 v80, v238, v80
	s_waitcnt lgkmcnt(5)
	v_mfma_f32_32x32x16_bf16 v[112:127], v[88:91], v[160:163], v[112:127]
	v_exp_f32_e32 v129, v129
	v_add_f32_e32 v80, v234, v80
	v_exp_f32_e32 v130, v130
	v_add_f32_e32 v80, v196, v80
	v_exp_f32_e32 v131, v131
	v_add_f32_e32 v80, v197, v80
	v_exp_f32_e32 v132, v132
	s_waitcnt lgkmcnt(4)
	v_mfma_f32_32x32x16_bf16 v[96:111], v[92:95], v[160:163], v[96:111]
	v_add_f32_e32 v80, v128, v80
	v_exp_f32_e32 v133, v133
	v_add_f32_e32 v80, v129, v80
	v_exp_f32_e32 v134, v134
	v_add_f32_e32 v80, v130, v80
	v_exp_f32_e32 v135, v135
	v_add_f32_e32 v80, v131, v80
	s_waitcnt lgkmcnt(3)
	v_mfma_f32_32x32x16_bf16 v[112:127], v[218:221], v[156:159], v[112:127]
	v_exp_f32_e32 v136, v136
	v_add_f32_e32 v80, v132, v80
	v_exp_f32_e32 v137, v137
	v_add_f32_e32 v80, v133, v80
	v_exp_f32_e32 v138, v138
	v_add_f32_e32 v80, v134, v80
	v_exp_f32_e32 v139, v139
	s_waitcnt lgkmcnt(2)
	v_mfma_f32_32x32x16_bf16 v[96:111], v[222:225], v[156:159], v[96:111]
	v_add_f32_e32 v80, v135, v80
	v_exp_f32_e32 v140, v140
	v_add_f32_e32 v80, v136, v80
	v_exp_f32_e32 v141, v141
	v_add_f32_e32 v80, v137, v80
	v_exp_f32_e32 v142, v142
	v_add_f32_e32 v80, v138, v80
	s_waitcnt lgkmcnt(1)
	v_mfma_f32_32x32x16_bf16 v[112:127], v[226:229], v[152:155], v[112:127]
	v_exp_f32_e32 v143, v143
	v_add_f32_e32 v80, v139, v80
	v_add_f32_e32 v80, v140, v80
	v_add_f32_e32 v80, v141, v80
	v_add_f32_e32 v80, v142, v80
	v_add_f32_e32 v218, v143, v80
	v_mov_b32_e32 v219, v218
	s_waitcnt lgkmcnt(0)
	v_mfma_f32_32x32x16_bf16 v[96:111], v[240:243], v[152:155], v[96:111]
	v_cvt_pk_bf16_f32 v80, v230, v231
	v_cvt_pk_bf16_f32 v81, v244, v245
	v_cvt_pk_bf16_f32 v82, v246, v247
	v_cvt_pk_bf16_f32 v83, v248, v249
	v_cvt_pk_bf16_f32 v84, v250, v251
	v_cvt_pk_bf16_f32 v85, v235, v237
	v_cvt_pk_bf16_f32 v86, v238, v234
	v_cvt_pk_bf16_f32 v87, v196, v197
	v_cvt_pk_bf16_f32 v88, v128, v129
	v_cvt_pk_bf16_f32 v89, v130, v131
	v_cvt_pk_bf16_f32 v90, v132, v133
	v_cvt_pk_bf16_f32 v91, v134, v135
	v_cvt_pk_bf16_f32 v92, v136, v137
	v_cvt_pk_bf16_f32 v93, v138, v139
	v_cvt_pk_bf16_f32 v94, v140, v141
	v_cvt_pk_bf16_f32 v95, v142, v143
	v_permlane32_swap_b32_e32 v218, v219
	v_permlane32_swap_b32_e32 v80, v82
	v_permlane32_swap_b32_e32 v81, v83
	v_permlane32_swap_b32_e32 v84, v86
	v_permlane32_swap_b32_e32 v85, v87
	v_permlane32_swap_b32_e32 v88, v90
	v_permlane32_swap_b32_e32 v89, v91
	v_permlane32_swap_b32_e32 v92, v94
	v_permlane32_swap_b32_e32 v93, v95
	s_cmp_lt_u32 s64, 61
	s_cselect_b64 s[0:1], -1, 0
	s_cmp_gt_u32 s64, 60
	s_cbranch_scc1 .LBB0_359
	s_add_u32 s74, s70, 0x18e00000
	s_addc_u32 s75, s71, 0
	global_load_dwordx4 v[168:171], v182, s[74:75] offset:2048
	s_add_u32 s74, s70, 0x18e40000
	s_addc_u32 s75, s71, 0
	global_load_dwordx4 v[172:175], v182, s[74:75] offset:2048
	s_add_u32 s74, s72, 0x18e00000
	s_addc_u32 s75, s73, 0
	global_load_dwordx4 v[176:179], v184, s[74:75] offset:1024

; #define GAS __attribute__((address_space(1)))
; template <bool GRPB> __device__ __forceinline__ void attn_pass(const float mbK, const float bmax2, const int pass, float* __restrict__ scr, bf16* __restrict__ mixrow, const float lam, const float* __restrict__ gsub, const float one_m_li, ...
;     ...
;   const float cL = __uint_as_float(__builtin_amdgcn_readfirstlane(__float_as_uint(tb2[0]))), cR = __uint_as_float(__builtin_amdgcn_readfirstlane(__float_as_uint(tb2[384])));
;   const int qw = __builtin_amdgcn_readfirstlane(q0seq + wid * 32), qpos = qw + r32;
;   float m_reg, l_reg = 0; bf16x8 qr[4]; f32x16 o[4];
; #pragma unroll
;   for (int d = 0; d < 4; ++d) o[d] = f32x16{};
;   const bf16* Qw = Qb + (long)(wid * 32 + r32) * LDK + hi * 8;
; #pragma unroll
;   for (int d0 = 0; d0 < 4; ++d0) qr[d0] = *(const GAS bf16x8*)(Qw + d0 * 16);
;     ...
;   if (hi == 0) li_e[r32] = l_reg; asm volatile("s_waitcnt lgkmcnt(0)" ::: "memory");
;   GAS f32x4* scr4 = (GAS f32x4*)(scr + (size_t)tid * 64);
;   if (pass == 0) {
; #pragma unroll
;     for (int r4 = 0; r4 < 4; ++r4) { const f32x4 lv = *(const f32x4*)(li_e + 8 * r4 + 4 * hi);
;       const f32x4 rl = (f32x4){__builtin_amdgcn_rcpf(lv[0]), __builtin_amdgcn_rcpf(lv[1]), __builtin_amdgcn_rcpf(lv[2]), __builtin_amdgcn_rcpf(lv[3])};
; #pragma unroll
;       for (int d0 = 0; d0 < 4; ++d0) scr4[d0 * 4 + r4] = (f32x4){o[d0][4 * r4 + 0] * rl[0], o[d0][4 * r4 + 1] * rl[1], o[d0][4 * r4 + 2] * rl[2], o[d0][4 * r4 + 3] * rl[3]}; }
.LBB0_373:
	s_or_b64 exec, exec, s[0:1]
	s_waitcnt lgkmcnt(0)
	v_add_u32_e32 v76, v66, v180
	ds_read_b128 v[66:69], v76
	ds_read_b128 v[70:73], v76 offset:32
	v_ashrrev_i32_e32 v147, 31, v146
	v_lshlrev_b64 v[0:1], 8, v[146:147]
	v_lshl_add_u64 v[74:75], s[40:41], 0, v[0:1]
	s_waitcnt lgkmcnt(1)
	v_rcp_f32_e32 v66, v66
	v_rcp_f32_e32 v67, v67
	v_rcp_f32_e32 v68, v68
	v_rcp_f32_e32 v69, v69
	v_mov_b32_e32 v146, v232
	v_pk_mul_f32 v[0:1], v[2:3], v[66:67]
	s_movk_i32 s0, 0xffe0
	v_pk_mul_f32 v[2:3], v[4:5], v[68:69]
	global_store_dwordx4 v[74:75], v[0:3], off
	v_mov_b32_e32 v181, v144
	s_mov_b32 s1, 0xc0000
	v_pk_mul_f32 v[0:1], v[18:19], v[66:67]
	s_waitcnt lgkmcnt(0)
	v_rcp_f32_e32 v18, v70
	v_rcp_f32_e32 v19, v71
	v_pk_mul_f32 v[2:3], v[20:21], v[68:69]
	global_store_dwordx4 v[74:75], v[0:3], off offset:64
	s_nop 1
	v_pk_mul_f32 v[0:1], v[34:35], v[66:67]
	v_pk_mul_f32 v[2:3], v[36:37], v[68:69]
	v_rcp_f32_e32 v34, v72
	v_rcp_f32_e32 v35, v73
	global_store_dwordx4 v[74:75], v[0:3], off offset:128
	s_nop 1
	v_pk_mul_f32 v[0:1], v[50:51], v[66:67]
	v_pk_mul_f32 v[2:3], v[52:53], v[68:69]
	global_store_dwordx4 v[74:75], v[0:3], off offset:192
	s_nop 1
	v_pk_mul_f32 v[0:1], v[6:7], v[18:19]
	ds_read_b128 v[4:7], v76 offset:64
	v_pk_mul_f32 v[2:3], v[8:9], v[34:35]
	global_store_dwordx4 v[74:75], v[0:3], off offset:16
	s_nop 1
	v_pk_mul_f32 v[0:1], v[22:23], v[18:19]
	v_pk_mul_f32 v[2:3], v[24:25], v[34:35]
	global_store_dwordx4 v[74:75], v[0:3], off offset:80
	s_nop 1
	v_pk_mul_f32 v[0:1], v[38:39], v[18:19]
	v_pk_mul_f32 v[2:3], v[40:41], v[34:35]
	global_store_dwordx4 v[74:75], v[0:3], off offset:144
	s_nop 1
	v_pk_mul_f32 v[0:1], v[54:55], v[18:19]
	ds_read_b128 v[18:21], v76 offset:96
	s_waitcnt lgkmcnt(1)
	v_rcp_f32_e32 v4, v4
	v_rcp_f32_e32 v5, v5
	v_rcp_f32_e32 v6, v6
	v_rcp_f32_e32 v7, v7
	v_pk_mul_f32 v[2:3], v[56:57], v[34:35]
	global_store_dwordx4 v[74:75], v[0:3], off offset:208
	s_waitcnt lgkmcnt(0)
	v_rcp_f32_e32 v8, v20
	v_rcp_f32_e32 v9, v21
	v_pk_mul_f32 v[0:1], v[10:11], v[4:5]
	v_pk_mul_f32 v[2:3], v[12:13], v[6:7]
	global_store_dwordx4 v[74:75], v[0:3], off offset:32
	s_nop 1
	v_pk_mul_f32 v[0:1], v[26:27], v[4:5]
	v_pk_mul_f32 v[2:3], v[28:29], v[6:7]
	global_store_dwordx4 v[74:75], v[0:3], off offset:96
	s_nop 1
	v_pk_mul_f32 v[0:1], v[42:43], v[4:5]
	v_pk_mul_f32 v[2:3], v[44:45], v[6:7]
	global_store_dwordx4 v[74:75], v[0:3], off offset:160
	v_mov_b32_e32 v43, v144
	s_nop 0
	v_pk_mul_f32 v[0:1], v[58:59], v[4:5]
	v_rcp_f32_e32 v4, v18
	v_rcp_f32_e32 v5, v19
	v_pk_mul_f32 v[2:3], v[60:61], v[6:7]
	global_store_dwordx4 v[74:75], v[0:3], off offset:224
	s_nop 1
	v_pk_mul_f32 v[0:1], v[14:15], v[4:5]
	v_pk_mul_f32 v[2:3], v[16:17], v[8:9]
	global_store_dwordx4 v[74:75], v[0:3], off offset:48
	s_nop 1
	v_pk_mul_f32 v[0:1], v[30:31], v[4:5]
	v_pk_mul_f32 v[2:3], v[32:33], v[8:9]
	global_store_dwordx4 v[74:75], v[0:3], off offset:112
	s_nop 1
	v_pk_mul_f32 v[0:1], v[46:47], v[4:5]
	v_pk_mul_f32 v[2:3], v[48:49], v[8:9]
	global_store_dwordx4 v[74:75], v[0:3], off offset:176
	s_nop 1
	v_pk_mul_f32 v[0:1], v[62:63], v[4:5]
	v_pk_mul_f32 v[2:3], v[64:65], v[8:9]
	global_store_dwordx4 v[74:75], v[0:3], off offset:240
	s_nop 0
	v_bfe_u32 v190, v146, 5, 1
	v_ashrrev_i32_e32 v2, 1, v146
	v_bfi_b32 v0, s0, v2, v146
	v_ashrrev_i32_e32 v1, 31, v0
	v_lshlrev_b64 v[0:1], 13, v[0:1]
	v_lshl_add_u64 v[0:1], s[52:53], 0, v[0:1]
	v_lshlrev_b32_e32 v180, 4, v190
	v_lshl_add_u64 v[0:1], v[0:1], 0, v[180:181]
	global_load_dwordx4 v[164:167], v[0:1], off offset:128
	global_load_dwordx4 v[160:163], v[0:1], off offset:160
	global_load_dwordx4 v[156:159], v[0:1], off offset:192
	v_readlane_b32 s0, v254, 39
	v_and_b32_e32 v215, 0xffffffe0, v2
	v_ashrrev_i32_e32 v36, 4, v146
	v_mov_b32_e32 v3, s0
	v_readlane_b32 s0, v254, 40
	v_lshlrev_b32_e32 v45, 3, v146
	v_ashrrev_i32_e32 v37, 31, v36
	v_mov_b32_e32 v4, s0
	ds_read_b32 v3, v3
	ds_read_b32 v4, v4
	global_load_dwordx4 v[152:155], v[0:1], off offset:224
	v_lshlrev_b64 v[48:49], 13, v[36:37]
	v_ashrrev_i32_e32 v40, 3, v146
	s_waitcnt lgkmcnt(1)
	v_readfirstlane_b32 s52, v3
	v_mov_b32_e32 v3, v144
	s_mov_b32 s0, 0x80000
	v_ashrrev_i32_e32 v41, 31, v40
	v_lshlrev_b32_e32 v46, 4, v146
	v_lshlrev_b64 v[50:51], 13, v[40:41]
	v_add_u32_e32 v38, 32, v36
	v_and_b32_e32 v42, 0x70, v46
	v_lshl_add_u64 v[8:9], s[50:51], 0, v[50:51]
	v_ashrrev_i32_e32 v39, 31, v38
	v_lshl_add_u64 v[32:33], v[8:9], 0, v[42:43]
	s_waitcnt lgkmcnt(0)
	v_readfirstlane_b32 s53, v4
	s_barrier
; __device__ __forceinline__ float bf2f(unsigned short b) { return __uint_as_float(((unsigned)b) << 16); }
; __device__ __forceinline__ int v_st(int k, int c) { const int kk = (k & ~0xC) | ((k & 4) << 1) | ((k & 8) >> 1); return ((kk >> 3) * 4 + (c >> 5)) * 512 + ((kk & 7) * 32 + (c & 31)) * 2; }
; __device__ __forceinline__ int v_rd_base(int lane) { return ((lane & 3) << 3) | (((lane >> 2) & 3) << 6) | (((lane >> 4) & 1) << 5) | (((lane >> 5) & 1) << 8); }
; #define SLOAD(i, k0) do { sr_[i].vs0 = *(const GAS bf16x8*)(&Vh[(long)((k0) + sr) * LDK + sc]); sr_[i].vs1 = *(const GAS bf16x8*)(&Vh[(long)((k0) + 32 + sr) * LDK + sc]); \
;     sr_[i].ks0 = *(const GAS bf16x8*)(&Kh[(long)((k0) + kr) * LDK + kc]); } while (0)
; #define SWRITE(b, i) do { *(bf16x8*)(V_lds + (b) * SHM_V + vst0) = sr_[i].vs0; *(bf16x8*)(V_lds + (b) * SHM_V + vst1) = sr_[i].vs1; \
;     *(bf16x8*)(K_lds + (b) * SHM_K + kst) = sr_[i].ks0; } while (0)
; template <bool GRPB> __device__ __forceinline__ void attn_pass(const float mbK, const float bmax2, const int pass, float* __restrict__ scr, bf16* __restrict__ mixrow, const float lam, const float* __restrict__ gsub, const float one_m_li, ...
;     ...
;   { float qs = 0.f;
; #pragma unroll
;     for (int d0 = 0; d0 < 4; ++d0)
; #pragma unroll
;       for (int j = 0; j < 8; ++j) { const float v = bf2f((unsigned short)qr[d0][j]); qs = fmaf(v, v, qs); }
;     { auto rr = __builtin_amdgcn_permlane32_swap(__float_as_uint(qs), __float_as_uint(qs), false, false); qs = __uint_as_float(rr[0]) + __uint_as_float(rr[1]); }
;     m_reg = __builtin_sqrtf(qs) * mbK + bmax2 + 0.25f; }
;   const int sr = tid >> 4, sc = (tid & 15) * 8, vst0 = v_st(sr, sc), vst1 = v_st(32 + sr, sc);
;   const int kr = tid >> 3, kc = (tid & 7) * 8, kst = KSWZ64(kr, kc * 2);
;   const int vb0 = (int)(uintptr_t)V_lds + v_rd_base(lane);
;   struct { bf16x8 vs0, vs1, ks0; } sr_[2];
;     ...
;   f32x16 pA0, pA1, pB0, pB1; float mnA, mnB, alA, alB; bf16x8 pa0, pa1, pa2, pa3; constexpr int NT = SEQ / KVBLK;
;   __syncthreads();
;   SLOAD(0, 0); SLOAD(1, KVBLK); asm volatile("s_waitcnt vmcnt(0)" ::: "memory"); SWRITE(0, 0); SWRITE(1, 1);
;   SLOAD(0, 2 * KVBLK); asm volatile("s_waitcnt vmcnt(0)" ::: "memory"); SWRITE(2, 0); __syncthreads();
	v_add_u32_e32 v41, s39, v215
	v_and_b32_e32 v181, 31, v146
	v_readfirstlane_b32 s39, v41
	s_waitcnt vmcnt(3)
	v_lshlrev_b32_e32 v0, 16, v164
	v_and_b32_e32 v1, 0xffff0000, v164
	v_fma_f32 v44, v0, v0, 0
	v_lshlrev_b32_e32 v2, 16, v165
	v_fmac_f32_e32 v44, v1, v1
	v_fmac_f32_e32 v44, v2, v2
	v_and_b32_e32 v0, 0xffff0000, v165
	v_fmac_f32_e32 v44, v0, v0
	v_lshlrev_b32_e32 v0, 16, v166
	v_fmac_f32_e32 v44, v0, v0
	v_and_b32_e32 v0, 0xffff0000, v166
	v_fmac_f32_e32 v44, v0, v0
	v_lshlrev_b32_e32 v0, 16, v167
	v_fmac_f32_e32 v44, v0, v0
	v_and_b32_e32 v0, 0xffff0000, v167
	v_fmac_f32_e32 v44, v0, v0
	s_waitcnt vmcnt(2)
	v_lshlrev_b32_e32 v0, 16, v160
	v_fmac_f32_e32 v44, v0, v0
	v_and_b32_e32 v0, 0xffff0000, v160
	v_fmac_f32_e32 v44, v0, v0
	v_lshlrev_b32_e32 v0, 16, v161
	v_fmac_f32_e32 v44, v0, v0
	v_and_b32_e32 v0, 0xffff0000, v161
	v_fmac_f32_e32 v44, v0, v0
	v_lshlrev_b32_e32 v0, 16, v162
	v_fmac_f32_e32 v44, v0, v0
	v_and_b32_e32 v0, 0xffff0000, v162
	v_fmac_f32_e32 v44, v0, v0
	v_lshlrev_b32_e32 v0, 16, v163
	v_fmac_f32_e32 v44, v0, v0
	v_and_b32_e32 v0, 0xffff0000, v163
	v_fmac_f32_e32 v44, v0, v0
	s_waitcnt vmcnt(1)
	v_lshlrev_b32_e32 v0, 16, v156
	v_fmac_f32_e32 v44, v0, v0
	v_and_b32_e32 v0, 0xffff0000, v156
	v_fmac_f32_e32 v44, v0, v0
	v_lshlrev_b32_e32 v0, 16, v157
	v_fmac_f32_e32 v44, v0, v0
	v_and_b32_e32 v0, 0xffff0000, v157
	v_fmac_f32_e32 v44, v0, v0
	v_lshlrev_b32_e32 v0, 16, v158
	v_fmac_f32_e32 v44, v0, v0
	v_and_b32_e32 v0, 0xffff0000, v158
	v_fmac_f32_e32 v44, v0, v0
	v_lshlrev_b32_e32 v0, 16, v159
	v_and_b32_e32 v2, 0x78, v45
	v_fmac_f32_e32 v44, v0, v0
	v_lshl_add_u64 v[0:1], s[50:51], 0, v[48:49]
	v_lshlrev_b32_e32 v2, 1, v2
	v_lshl_add_u64 v[24:25], v[0:1], 0, v[2:3]
	v_add_co_u32_e32 v12, vcc, s0, v24
	v_lshlrev_b64 v[0:1], 13, v[38:39]
	s_nop 0
	v_addc_co_u32_e32 v13, vcc, 0, v25, vcc
	v_add_co_u32_e32 v16, vcc, s1, v24
	v_lshl_add_u64 v[0:1], s[50:51], 0, v[0:1]
	s_nop 0
	v_addc_co_u32_e32 v17, vcc, 0, v25, vcc
	v_add_co_u32_e32 v20, vcc, s0, v32
	s_mov_b32 s0, 0x100000
	s_nop 0
	v_addc_co_u32_e32 v21, vcc, 0, v33, vcc
	v_lshl_add_u64 v[4:5], v[0:1], 0, v[2:3]
	v_add_co_u32_e32 v26, vcc, s0, v24
	global_load_dwordx4 v[0:3], v[24:25], off offset:2048
	s_nop 0
	global_load_dwordx4 v[4:7], v[4:5], off offset:2048
	s_nop 0
	global_load_dwordx4 v[8:11], v[32:33], off offset:1152
	s_nop 0
	global_load_dwordx4 v[12:15], v[12:13], off offset:2048
	s_nop 0
	global_load_dwordx4 v[16:19], v[16:17], off offset:2048
	s_nop 0
	global_load_dwordx4 v[20:23], v[20:21], off offset:1152
	v_addc_co_u32_e32 v27, vcc, 0, v25, vcc
	s_mov_b32 s1, 0x140000
	v_add_co_u32_e32 v28, vcc, s1, v24
	s_waitcnt vmcnt(0)
	v_and_b32_e32 v37, 0xffff0000, v159
	s_nop 0
	v_addc_co_u32_e32 v29, vcc, 0, v25, vcc
	v_add_co_u32_e32 v32, vcc, s0, v32
	global_load_dwordx4 v[24:27], v[26:27], off offset:2048
	s_nop 0
	global_load_dwordx4 v[28:31], v[28:29], off offset:2048
	v_addc_co_u32_e32 v33, vcc, 0, v33, vcc
	global_load_dwordx4 v[32:35], v[32:33], off offset:1152
	v_fmac_f32_e32 v44, v37, v37
	s_waitcnt vmcnt(9)
	v_lshlrev_b32_e32 v37, 16, v152
	v_fmac_f32_e32 v44, v37, v37
	v_and_b32_e32 v37, 0xffff0000, v152
	v_fmac_f32_e32 v44, v37, v37
	v_lshlrev_b32_e32 v37, 16, v153
	v_fmac_f32_e32 v44, v37, v37
	v_and_b32_e32 v37, 0xffff0000, v153
	v_fmac_f32_e32 v44, v37, v37
	v_lshlrev_b32_e32 v37, 16, v154
	v_fmac_f32_e32 v44, v37, v37
	v_and_b32_e32 v37, 0xffff0000, v154
	v_fmac_f32_e32 v44, v37, v37
	v_lshlrev_b32_e32 v37, 16, v155
	v_fmac_f32_e32 v44, v37, v37
	v_and_b32_e32 v37, 0xffff0000, v155
	v_fmac_f32_e32 v44, v37, v37
	v_mov_b32_e32 v37, v44
	s_nop 1
	v_permlane32_swap_b32_e32 v44, v37
	v_add_f32_e32 v37, v44, v37
	v_mul_f32_e32 v39, 0x4f800000, v37
	v_cmp_gt_f32_e32 vcc, s10, v37
	v_add_u32_e32 v192, s39, v181
	s_nop 0
	v_cndmask_b32_e32 v37, v37, v39, vcc
	v_sqrt_f32_e32 v39, v37
	s_nop 0
	v_add_u32_e32 v41, -1, v39
	v_fma_f32 v43, -v41, v39, v37
	v_cmp_ge_f32_e64 s[0:1], 0, v43
	v_add_u32_e32 v43, 1, v39
	s_nop 0
	v_cndmask_b32_e64 v41, v39, v41, s[0:1]
	v_fma_f32 v39, -v43, v39, v37
	v_cmp_lt_f32_e64 s[0:1], 0, v39
	s_nop 1
	v_cndmask_b32_e64 v39, v41, v43, s[0:1]
	v_mul_f32_e32 v41, 0x37800000, v39
	v_cndmask_b32_e32 v39, v39, v41, vcc
	v_cmp_class_f32_e32 vcc, v37, v198
	v_bfe_u32 v41, v45, 5, 2
	s_nop 0
	v_cndmask_b32_e32 v37, v39, v37, vcc
	v_fma_f32 v37, v214, v37, s45
	v_add_f32_e32 v64, 0x3e800000, v37
	v_and_b32_e32 v37, 0xfffff0, v36
	v_lshlrev_b32_e32 v39, 1, v36
	v_and_or_b32 v37, v39, 8, v37
	v_lshrrev_b32_e32 v39, 1, v36
	v_lshrrev_b32_e32 v37, 1, v37
	v_and_b32_e32 v36, 3, v36
	v_or_b32_e32 v37, v37, v41
	v_and_or_b32 v36, v39, 4, v36
	v_lshlrev_b32_e32 v37, 9, v37
	v_lshlrev_b32_e32 v36, 6, v36
	v_and_b32_e32 v39, 48, v46
	v_or3_b32 v193, v37, v36, v39
	v_and_b32_e32 v37, 0xfffff0, v38
	v_lshlrev_b32_e32 v38, 1, v38
	v_and_or_b32 v37, v38, 8, v37
	v_lshrrev_b32_e32 v37, 1, v37
	v_or_b32_e32 v37, v37, v41
	v_lshlrev_b32_e32 v37, 9, v37
	v_or3_b32 v194, v37, v36, v39
	v_lshlrev_b32_e32 v36, 7, v40
	v_and_b32_e32 v37, 0x70, v146
	v_bitop3_b32 v195, v42, v36, v37 bitop3:0xde
	v_add_u32_e32 v36, 0, v193
	s_waitcnt vmcnt(8)
	ds_write_b128 v36, v[0:3]
	v_add_u32_e32 v0, 0, v194
	v_add_u32_e32 v200, 0, v195
	s_waitcnt vmcnt(7)
	ds_write_b128 v0, v[4:7]
	s_waitcnt vmcnt(6)
	ds_write_b128 v200, v[8:11] offset:49152
	s_waitcnt vmcnt(5)
	ds_write_b128 v36, v[12:15] offset:16384
	s_waitcnt vmcnt(4)
	ds_write_b128 v0, v[16:19] offset:16384
	s_waitcnt vmcnt(3)
	ds_write_b128 v200, v[20:23] offset:57344
	v_lshlrev_b32_e32 v8, 7, v181
	v_and_b32_e32 v9, 0x70, v45
	v_or_b32_e32 v10, 32, v180
	v_bitop3_b32 v206, v10, v8, v9 bitop3:0xde
	v_or_b32_e32 v10, 64, v180
	v_bitop3_b32 v208, v10, v8, v9 bitop3:0xde
	v_or_b32_e32 v10, 0x60, v180
	v_bitop3_b32 v203, v180, v8, v9 bitop3:0xde
	v_bitop3_b32 v209, v10, v8, v9 bitop3:0xde
	s_waitcnt vmcnt(0)
	s_waitcnt vmcnt(2)
	ds_write_b128 v36, v[24:27] offset:32768
	s_waitcnt vmcnt(1)
	ds_write_b128 v0, v[28:31] offset:32768
	v_add_u32_e32 v0, 0x10000, v200
	v_add_u32_e32 v202, 0, v203
	v_add_u32_e32 v204, 0, v206
	v_add_u32_e32 v205, 0, v208
	v_add_u32_e32 v207, 0, v209
	s_waitcnt vmcnt(0)
	ds_write_b128 v0, v[32:35]
	s_waitcnt lgkmcnt(0)
	s_barrier
; #define SBAR() __builtin_amdgcn_sched_barrier(0)
; __device__ __forceinline__ void partialSM(f32x16& p0, f32x16& p1, float& m_reg, float& mn, float& alpha, int kt0, int qpos, int qw, int hi, const float* tb2, float cL, float cR) {
;   mn = m_reg; alpha = 1.f;
;   const int rel_hi = kt0 + 63 - qw, rel_lo = kt0 - (qw + 31);
;   if (rel_hi <= -91 || rel_lo >= 91) {
;     const float cm = ((rel_hi <= -91) ? cL : cR) - m_reg;
; #pragma unroll
;     for (int r = 0; r < 16; ++r) { p0[r] = fmaf(p0[r], C1, cm); p1[r] = fmaf(p1[r], C1, cm); }
;   } else {
;     const float* tp = tb2 + (kt0 - qpos + 192 + 4 * hi);
; #pragma unroll
;     for (int r4 = 0; r4 < 4; ++r4) {
;       float ta[4], tb[4];
; #pragma unroll
;       for (int i = 0; i < 4; ++i) { ta[i] = tp[8 * r4 + i] - m_reg; tb[i] = tp[32 + 8 * r4 + i] - m_reg; }
; #pragma unroll
;       for (int i = 0; i < 4; ++i) { p0[4 * r4 + i] = fmaf(p0[4 * r4 + i], C1, ta[i]); p1[4 * r4 + i] = fmaf(p1[4 * r4 + i], C1, tb[i]); }
; __device__ __forceinline__ void qkt(f32x16& p0, f32x16& p1, const char* Ks, const bf16x8* qr, int r32, int hi) {
;   bf16x8 ka[4], kb[4];
; #pragma unroll
;   for (int d0 = 0; d0 < 4; ++d0) { const int cb = (d0 * 16 + hi * 8) * 2;
;     ka[d0] = *reinterpret_cast<const bf16x8*>(Ks + KSWZ64(r32, cb)); kb[d0] = *reinterpret_cast<const bf16x8*>(Ks + KSWZ64(32 + r32, cb)); }
;   asm volatile("s_waitcnt lgkmcnt(0)" ::: "memory"); SBAR();
;   p0 = f32x16{}; p1 = f32x16{};
; #pragma unroll
;   for (int d0 = 0; d0 < 4; ++d0) {
;     p0 = __builtin_amdgcn_mfma_f32_32x32x16_bf16(ka[d0], qr[d0], p0, 0, 0, 0);
;     p1 = __builtin_amdgcn_mfma_f32_32x32x16_bf16(kb[d0], qr[d0], p1, 0, 0, 0); }
	ds_read_b128 v[0:3], v202 offset:49152
	ds_read_b128 v[4:7], v202 offset:53248
	ds_read_b128 v[32:35], v204 offset:49152
	ds_read_b128 v[36:39], v204 offset:53248
	ds_read_b128 v[40:43], v205 offset:49152
	ds_read_b128 v[44:47], v205 offset:53248
	ds_read_b128 v[52:55], v207 offset:49152
	ds_read_b128 v[56:59], v207 offset:53248
	s_waitcnt lgkmcnt(7)
	v_mfma_f32_32x32x16_bf16 v[16:31], v[0:3], v[164:167], 0
	s_add_i32 s4, s39, 0xffffff66
	s_mov_b64 s[0:1], -1
	s_cmp_gt_u32 s4, 0xfffffeec
	s_waitcnt lgkmcnt(6)
	v_mfma_f32_32x32x16_bf16 v[0:15], v[4:7], v[164:167], 0
	s_waitcnt lgkmcnt(5)
	v_mfma_f32_32x32x16_bf16 v[16:31], v[32:35], v[160:163], v[16:31]
	s_waitcnt lgkmcnt(4)
	v_mfma_f32_32x32x16_bf16 v[0:15], v[36:39], v[160:163], v[0:15]
	s_waitcnt lgkmcnt(3)
	v_mfma_f32_32x32x16_bf16 v[16:31], v[40:43], v[156:159], v[16:31]
	s_waitcnt lgkmcnt(2)
	v_mfma_f32_32x32x16_bf16 v[0:15], v[44:47], v[156:159], v[0:15]
	s_waitcnt lgkmcnt(1)
	v_mfma_f32_32x32x16_bf16 v[16:31], v[52:55], v[152:155], v[16:31]
	v_lshlrev_b32_e32 v52, 2, v192
	s_waitcnt lgkmcnt(0)
	v_mfma_f32_32x32x16_bf16 v[0:15], v[56:59], v[152:155], v[0:15]
	s_cbranch_scc0 .LBB0_375
	v_sub_u32_e32 v32, 0, v52
	s_mov_b32 s0, 0x12b00
	v_add3_u32 v53, v32, v180, s0
	ds_read2_b32 v[32:33], v53 offset1:1
	ds_read2_b32 v[54:55], v53 offset0:32 offset1:33
	ds_read2_b32 v[56:57], v53 offset0:34 offset1:35
	ds_read2_b32 v[34:35], v53 offset0:2 offset1:3
	ds_read2_b32 v[36:37], v53 offset0:8 offset1:9
	ds_read2_b32 v[58:59], v53 offset0:40 offset1:41
	ds_read2_b32 v[60:61], v53 offset0:42 offset1:43
	ds_read2_b32 v[38:39], v53 offset0:10 offset1:11
	ds_read2_b32 v[40:41], v53 offset0:16 offset1:17
	ds_read2_b32 v[62:63], v53 offset0:48 offset1:49
	ds_read2_b32 v[66:67], v53 offset0:50 offset1:51
	ds_read2_b32 v[42:43], v53 offset0:18 offset1:19
	ds_read2_b32 v[44:45], v53 offset0:24 offset1:25
	ds_read2_b32 v[46:47], v53 offset0:26 offset1:27
	ds_read2_b32 v[68:69], v53 offset0:58 offset1:59
	ds_read2_b32 v[70:71], v53 offset0:56 offset1:57
	s_waitcnt lgkmcnt(3)
	v_sub_f32_e32 v45, v45, v64
	v_sub_f32_e32 v44, v44, v64
	s_waitcnt lgkmcnt(2)
	v_sub_f32_e32 v47, v47, v64
	v_sub_f32_e32 v46, v46, v64
	v_sub_f32_e32 v41, v41, v64
	v_sub_f32_e32 v40, v40, v64
	v_sub_f32_e32 v43, v43, v64
	v_sub_f32_e32 v42, v42, v64
	v_sub_f32_e32 v37, v37, v64
	v_sub_f32_e32 v36, v36, v64
	v_sub_f32_e32 v39, v39, v64
	v_sub_f32_e32 v38, v38, v64
	v_sub_f32_e32 v33, v33, v64
	v_sub_f32_e32 v32, v32, v64
	v_sub_f32_e32 v35, v35, v64
	v_sub_f32_e32 v34, v34, v64
	s_waitcnt lgkmcnt(0)
	v_sub_f32_e32 v71, v71, v64
	v_sub_f32_e32 v70, v70, v64
	v_sub_f32_e32 v69, v69, v64
	v_sub_f32_e32 v68, v68, v64
	v_sub_f32_e32 v63, v63, v64
	v_sub_f32_e32 v62, v62, v64
	v_sub_f32_e32 v67, v67, v64
	v_sub_f32_e32 v66, v66, v64
	v_sub_f32_e32 v59, v59, v64
	v_sub_f32_e32 v58, v58, v64
	v_sub_f32_e32 v61, v61, v64
	v_sub_f32_e32 v60, v60, v64
	v_sub_f32_e32 v55, v55, v64
	v_sub_f32_e32 v54, v54, v64
	v_sub_f32_e32 v57, v57, v64
	v_sub_f32_e32 v56, v56, v64
	v_pk_fma_f32 v[34:35], v[18:19], s[6:7], v[34:35] op_sel_hi:[1,0,1]
	v_pk_fma_f32 v[32:33], v[16:17], s[6:7], v[32:33] op_sel_hi:[1,0,1]
	v_pk_fma_f32 v[38:39], v[22:23], s[6:7], v[38:39] op_sel_hi:[1,0,1]
	v_pk_fma_f32 v[36:37], v[20:21], s[6:7], v[36:37] op_sel_hi:[1,0,1]
	v_pk_fma_f32 v[42:43], v[26:27], s[6:7], v[42:43] op_sel_hi:[1,0,1]
	v_pk_fma_f32 v[40:41], v[24:25], s[6:7], v[40:41] op_sel_hi:[1,0,1]
	v_pk_fma_f32 v[46:47], v[30:31], s[6:7], v[46:47] op_sel_hi:[1,0,1]
	v_pk_fma_f32 v[44:45], v[28:29], s[6:7], v[44:45] op_sel_hi:[1,0,1]
	v_pk_fma_f32 v[82:83], v[2:3], s[6:7], v[56:57] op_sel_hi:[1,0,1]
	v_pk_fma_f32 v[80:81], v[0:1], s[6:7], v[54:55] op_sel_hi:[1,0,1]
	v_pk_fma_f32 v[86:87], v[6:7], s[6:7], v[60:61] op_sel_hi:[1,0,1]
	v_pk_fma_f32 v[84:85], v[4:5], s[6:7], v[58:59] op_sel_hi:[1,0,1]
	v_pk_fma_f32 v[90:91], v[10:11], s[6:7], v[66:67] op_sel_hi:[1,0,1]
	v_pk_fma_f32 v[88:89], v[8:9], s[6:7], v[62:63] op_sel_hi:[1,0,1]
	v_pk_fma_f32 v[94:95], v[14:15], s[6:7], v[68:69] op_sel_hi:[1,0,1]
	v_pk_fma_f32 v[92:93], v[12:13], s[6:7], v[70:71] op_sel_hi:[1,0,1]
	s_mov_b64 s[0:1], 0

; #define SBAR() __builtin_amdgcn_sched_barrier(0)
; __device__ __forceinline__ void partialSM(f32x16& p0, f32x16& p1, float& m_reg, float& mn, float& alpha, int kt0, int qpos, int qw, int hi, const float* tb2, float cL, float cR) {
;     ...
; #pragma unroll
;   for (int r = 0; r < 16; ++r) p0[r] = __builtin_amdgcn_exp2f(p0[r]);
; }
; __device__ __forceinline__ void finishSM(f32x16& p0, f32x16& p1, float alpha, float& l_reg, bf16x8& pa0, bf16x8& pa1, bf16x8& pa2, bf16x8& pa3) {
; #pragma unroll
;   for (int r = 0; r < 16; ++r) p1[r] = __builtin_amdgcn_exp2f(p1[r]);
;   float ps = 0;
; #pragma unroll
;   for (int r = 0; r < 16; ++r) ps += p0[r];
; #pragma unroll
;   for (int r = 0; r < 16; ++r) ps += p1[r];
;   { auto rr = __builtin_amdgcn_permlane32_swap(__float_as_uint(ps), __float_as_uint(ps), false, false);
;     ps = __uint_as_float(rr[0]) + __uint_as_float(rr[1]); }
;   l_reg = l_reg * alpha + ps;
;     ...
;   PK4(p0, 0, pa0); PK4(p0, 8, pa1); PK4(p1, 0, pa2); PK4(p1, 8, pa3);
;     ...
; }
; __device__ __forceinline__ void qkt(f32x16& p0, f32x16& p1, const char* Ks, const bf16x8* qr, int r32, int hi) {
;   bf16x8 ka[4], kb[4];
; #pragma unroll
;   for (int d0 = 0; d0 < 4; ++d0) { const int cb = (d0 * 16 + hi * 8) * 2;
;     ka[d0] = *reinterpret_cast<const bf16x8*>(Ks + KSWZ64(r32, cb)); kb[d0] = *reinterpret_cast<const bf16x8*>(Ks + KSWZ64(32 + r32, cb)); }
;   asm volatile("s_waitcnt lgkmcnt(0)" ::: "memory"); SBAR();
;   p0 = f32x16{}; p1 = f32x16{};
; #pragma unroll
;   for (int d0 = 0; d0 < 4; ++d0) {
;     p0 = __builtin_amdgcn_mfma_f32_32x32x16_bf16(ka[d0], qr[d0], p0, 0, 0, 0);
;     p1 = __builtin_amdgcn_mfma_f32_32x32x16_bf16(kb[d0], qr[d0], p1, 0, 0, 0); }
.LBB0_382:
	s_add_i32 s0, s4, 0
	v_exp_f32_e32 v196, v80
	v_add_u32_e32 v80, s0, v193
	s_barrier
	s_waitcnt vmcnt(2)
	ds_write_b128 v80, v[168:171]
	v_add_u32_e32 v80, s0, v194
	s_waitcnt vmcnt(1)
	ds_write_b128 v80, v[172:175]
	v_lshl_add_u32 v80, s45, 13, v200
	v_exp_f32_e32 v197, v81
	v_exp_f32_e32 v234, v82
	v_exp_f32_e32 v235, v83
	v_exp_f32_e32 v237, v84
	v_exp_f32_e32 v238, v85
	v_exp_f32_e32 v244, v86
	v_exp_f32_e32 v245, v87
	v_exp_f32_e32 v246, v88
	v_exp_f32_e32 v247, v89
	v_exp_f32_e32 v248, v90
	v_exp_f32_e32 v249, v91
	v_exp_f32_e32 v250, v92
	v_exp_f32_e32 v251, v93
	v_exp_f32_e32 v198, v94
	v_exp_f32_e32 v199, v95
	s_waitcnt vmcnt(0)
	ds_write_b128 v80, v[176:179] offset:49152
	s_lshl_b32 s0, s49, 13
	s_add_i32 s0, s0, 0
	v_add_u32_e32 v84, s0, v203
	v_add_u32_e32 v92, s0, v206
	v_add_u32_e32 v96, s0, v208
	ds_read_b128 v[80:83], v84 offset:49152
	ds_read_b128 v[84:87], v84 offset:53248
	ds_read_b128 v[88:91], v92 offset:49152
	ds_read_b128 v[92:95], v92 offset:53248
	ds_read_b128 v[220:223], v96 offset:49152
	ds_read_b128 v[224:227], v96 offset:53248
	v_add_u32_e32 v96, s0, v209
	ds_read_b128 v[228:231], v96 offset:49152
	ds_read_b128 v[240:243], v96 offset:53248
	s_waitcnt lgkmcnt(7)
	v_mfma_f32_32x32x16_bf16 v[112:127], v[80:83], v[164:167], 0
	v_add_f32_e32 v80, 0, v196
	v_add_f32_e32 v80, v197, v80
	v_add_f32_e32 v80, v234, v80
	v_add_f32_e32 v80, v235, v80
	v_add_f32_e32 v80, v237, v80
	v_add_f32_e32 v80, v238, v80
	v_add_f32_e32 v80, v244, v80
	s_waitcnt lgkmcnt(6)
	v_mfma_f32_32x32x16_bf16 v[96:111], v[84:87], v[164:167], 0
	v_add_f32_e32 v80, v245, v80
	v_add_f32_e32 v80, v246, v80
	v_add_f32_e32 v80, v247, v80
	v_add_f32_e32 v80, v248, v80
	v_add_f32_e32 v80, v249, v80
	v_exp_f32_e32 v128, v128
	v_add_f32_e32 v80, v250, v80
	s_waitcnt lgkmcnt(5)
	v_mfma_f32_32x32x16_bf16 v[112:127], v[88:91], v[160:163], v[112:127]
	v_exp_f32_e32 v129, v129
	v_add_f32_e32 v80, v251, v80
	v_exp_f32_e32 v130, v130
	v_add_f32_e32 v80, v198, v80
	v_exp_f32_e32 v131, v131
	v_add_f32_e32 v80, v199, v80
	v_exp_f32_e32 v132, v132
	s_waitcnt lgkmcnt(4)
	v_mfma_f32_32x32x16_bf16 v[96:111], v[92:95], v[160:163], v[96:111]
	v_add_f32_e32 v80, v128, v80
	v_exp_f32_e32 v133, v133
	v_add_f32_e32 v80, v129, v80
	v_exp_f32_e32 v134, v134
	v_add_f32_e32 v80, v130, v80
	v_exp_f32_e32 v135, v135
	v_add_f32_e32 v80, v131, v80
	s_waitcnt lgkmcnt(3)
	v_mfma_f32_32x32x16_bf16 v[112:127], v[220:223], v[156:159], v[112:127]
	v_exp_f32_e32 v136, v136
	v_add_f32_e32 v80, v132, v80
	v_exp_f32_e32 v137, v137
	v_add_f32_e32 v80, v133, v80
	v_exp_f32_e32 v138, v138
	v_add_f32_e32 v80, v134, v80
	v_exp_f32_e32 v139, v139
	s_waitcnt lgkmcnt(2)
	v_mfma_f32_32x32x16_bf16 v[96:111], v[224:227], v[156:159], v[96:111]
	v_add_f32_e32 v80, v135, v80
	v_exp_f32_e32 v140, v140
	v_add_f32_e32 v80, v136, v80
	v_exp_f32_e32 v141, v141
	v_add_f32_e32 v80, v137, v80
	v_exp_f32_e32 v142, v142
	v_add_f32_e32 v80, v138, v80
	s_waitcnt lgkmcnt(1)
	v_mfma_f32_32x32x16_bf16 v[112:127], v[228:231], v[152:155], v[112:127]
	v_exp_f32_e32 v143, v143
	v_add_f32_e32 v80, v139, v80
	v_add_f32_e32 v80, v140, v80
	v_add_f32_e32 v80, v141, v80
	v_add_f32_e32 v80, v142, v80
	v_add_f32_e32 v219, v143, v80
	v_mov_b32_e32 v220, v219
	s_waitcnt lgkmcnt(0)
	v_mfma_f32_32x32x16_bf16 v[96:111], v[240:243], v[152:155], v[96:111]
	v_cvt_pk_bf16_f32 v80, v196, v197
	v_cvt_pk_bf16_f32 v81, v234, v235
	v_cvt_pk_bf16_f32 v82, v237, v238
	v_cvt_pk_bf16_f32 v83, v244, v245
	v_cvt_pk_bf16_f32 v84, v246, v247
	v_cvt_pk_bf16_f32 v85, v248, v249
	v_cvt_pk_bf16_f32 v86, v250, v251
	v_cvt_pk_bf16_f32 v87, v198, v199
	v_cvt_pk_bf16_f32 v88, v128, v129
	v_cvt_pk_bf16_f32 v89, v130, v131
	v_cvt_pk_bf16_f32 v90, v132, v133
	v_cvt_pk_bf16_f32 v91, v134, v135
	v_cvt_pk_bf16_f32 v92, v136, v137
	v_cvt_pk_bf16_f32 v93, v138, v139
	v_cvt_pk_bf16_f32 v94, v140, v141
	v_cvt_pk_bf16_f32 v95, v142, v143
	v_permlane32_swap_b32_e32 v219, v220
	v_permlane32_swap_b32_e32 v80, v82
	v_permlane32_swap_b32_e32 v81, v83
	v_permlane32_swap_b32_e32 v84, v86
	v_permlane32_swap_b32_e32 v85, v87
	v_permlane32_swap_b32_e32 v88, v90
	v_permlane32_swap_b32_e32 v89, v91
	v_permlane32_swap_b32_e32 v92, v94
	v_permlane32_swap_b32_e32 v93, v95
	s_cmp_lt_u32 s50, 61
	s_cselect_b64 s[0:1], -1, 0
	s_cmp_gt_u32 s50, 60
	s_cbranch_scc1 .LBB0_384
	s_add_u32 s74, s70, 0x18e00000
	s_addc_u32 s75, s71, 0
	global_load_dwordx4 v[168:171], v182, s[74:75] offset:2048
	s_add_u32 s74, s70, 0x18e40000
	s_addc_u32 s75, s71, 0
	global_load_dwordx4 v[172:175], v182, s[74:75] offset:2048
	s_add_u32 s74, s72, 0x18e00000
	s_addc_u32 s75, s73, 0
	global_load_dwordx4 v[176:179], v184, s[74:75] offset:1152
